# combo12: combo11 + GEMM K-loop LDS-DMA loads use scalar base + 32-bit lane offset instead of per-load 64-bit VALU adds
# baseline (speedup 1.0000x reference)
; #define PG8_STAGE(bufoff, gbase, voff) do { _Pragma("unroll") for (int _i = 0; _i < 2; ++_i) \
;         __builtin_amdgcn_global_load_lds((const unsigned*)((const char*)(gbase) + (voff)[_i]), (PG8_LAS unsigned*)(lds + (bufoff) + ldsw + _i * 8192), 16, 0, 0); } while (0)
; #define PG8_LDA(dst, b, h) do { _Pragma("unroll") for (int m = 0; m < 4; ++m) _Pragma("unroll") for (int k = 0; k < 2; ++k) dst[m][k] = *(const PG8_LAS bf16x8*)(lds + PG8_SA(b, h) + aoff + m * 2048 + k * 1024); } while (0)
; #define PG8_LDB(dst, b, h) do { _Pragma("unroll") for (int n = 0; n < 2; ++n) _Pragma("unroll") for (int k = 0; k < 2; ++k) dst[n][k] = *(const PG8_LAS bf16x8*)(lds + PG8_SB(b, h) + boff + n * 2048 + k * 1024); } while (0)
; #define PG8_WAIT_V(n) asm volatile("s_waitcnt vmcnt(" #n ")" ::: "memory")
; #define PG8_WAIT_L(n) asm volatile("s_waitcnt lgkmcnt(" #n ")" ::: "memory")
; #define PG8_BAR __builtin_amdgcn_s_barrier()
; #define PG8_SCHED __builtin_amdgcn_sched_barrier(0)
; template <class Epi, class Sched, bool ALIGN_EPI = false, bool SP2 = false>
; __device__ __forceinline__ void gemm_phase(PG8_LAS unsigned char* lds, const Gemm g, const Sched& S, const Epi& E, const int tid_arg) {
;     ...
;         const bool has_next = S.next(ui + 1, nxt);
;         const char* nA = has_next ? (const char*)g.A + (size_t)nxt.pm * tstep : cA; const char* nB = has_next ? (const char*)g.Bt + (size_t)nxt.pn * tstep : cB;
;         for (int t = 0; t < nt; t += 2) {
;             const bool last = (t == nt - 2);
;             const char* a1 = cA + (size_t)(t + 1) * kstep;
;             const char* a2 = last ? nA : cA + (size_t)(t + 2) * kstep; const char* b2 = last ? nB : cB + (size_t)(t + 2) * kstep;
;             const char* a3 = a2 + kstep; const char* b3 = b2 + kstep;
;             if (last && has_next) S.a_ready(nxt);
;             if constexpr (SP2) {
;             PG8_LDB(B0, 0, 0); PG8_LDB(B1, 0, 1); PG8_SCHED; PG8_LDA(At, 0, 0); PG8_STAGE(PG8_SA(1, 1), a1 + hstep, voffA);
;             PG8_WAIT_V(8); PG8_WAIT_L(0); PG8_BAR; PG8_MMA(0, 0, At, B0); PG8_MMA(0, 1, At, B1); PG8_BAR; PG8_SCHED;
;             PG8_LDA(At, 0, 1); PG8_STAGE(PG8_SB(0, 0), b2, voffB); PG8_STAGE(PG8_SB(0, 1), b2 + hstep, voffB); PG8_STAGE(PG8_SA(0, 0), a2, voffA);
;             PG8_WAIT_V(8); PG8_WAIT_L(0); PG8_BAR; PG8_MMA(1, 0, At, B0); PG8_MMA(1, 1, At, B1); PG8_BAR; PG8_SCHED;
.LBB0_253:
	ds_read_b128 v[144:147], v166
	ds_read_b128 v[148:151], v167
	ds_read_b128 v[152:155], v168
	ds_read_b128 v[156:159], v169
	ds_read_b128 v[184:187], v170
	ds_read_b128 v[188:191], v171
	ds_read_b128 v[192:195], v172
	ds_read_b128 v[196:199], v173
	s_add_u32 s0, s8, 0xfffc0080
	s_addc_u32 s1, s9, -1
	s_cmp_eq_u32 s70, 12
	s_cselect_b32 s35, s23, s1
	s_cselect_b32 s34, s36, s0
	s_cselect_b32 s1, s21, s69
	s_cselect_b32 s0, s37, s68
	s_mov_b32 m0, s57
	ds_read_b128 v[200:203], v165
	ds_read_b128 v[204:207], v165 offset:1024
	ds_read_b128 v[208:211], v165 offset:2048
	ds_read_b128 v[212:215], v165 offset:3072
	ds_read_b128 v[216:219], v165 offset:4096
	ds_read_b128 v[220:223], v165 offset:5120
	ds_read_b128 v[224:227], v165 offset:6144
	ds_read_b128 v[228:231], v165 offset:7168
	global_load_lds_dwordx4 v138, s[8:9]
	s_mov_b32 m0, s58
	s_nop 0
	global_load_lds_dwordx4 v136, s[8:9]
	s_waitcnt vmcnt(8)
	s_waitcnt lgkmcnt(0)
	s_setprio 1
	s_barrier
	v_mfma_f32_16x16x32_bf16 v[124:127], v[144:147], v[200:203], v[124:127]
	v_mfma_f32_16x16x32_bf16 v[120:123], v[152:155], v[200:203], v[120:123]
	v_mfma_f32_16x16x32_bf16 v[108:111], v[144:147], v[208:211], v[108:111]
	v_mfma_f32_16x16x32_bf16 v[104:107], v[152:155], v[208:211], v[104:107]
	v_mfma_f32_16x16x32_bf16 v[92:95], v[144:147], v[216:219], v[92:95]
	v_mfma_f32_16x16x32_bf16 v[88:91], v[152:155], v[216:219], v[88:91]
	v_mfma_f32_16x16x32_bf16 v[76:79], v[144:147], v[224:227], v[76:79]
	v_mfma_f32_16x16x32_bf16 v[72:75], v[152:155], v[224:227], v[72:75]
	v_mfma_f32_16x16x32_bf16 v[124:127], v[148:151], v[204:207], v[124:127]
	v_mfma_f32_16x16x32_bf16 v[120:123], v[156:159], v[204:207], v[120:123]
	v_mfma_f32_16x16x32_bf16 v[108:111], v[148:151], v[212:215], v[108:111]
	v_mfma_f32_16x16x32_bf16 v[104:107], v[156:159], v[212:215], v[104:107]
	v_mfma_f32_16x16x32_bf16 v[92:95], v[148:151], v[220:223], v[92:95]
	v_mfma_f32_16x16x32_bf16 v[88:91], v[156:159], v[220:223], v[88:91]
	v_mfma_f32_16x16x32_bf16 v[76:79], v[148:151], v[228:231], v[76:79]
	v_mfma_f32_16x16x32_bf16 v[72:75], v[156:159], v[228:231], v[72:75]
	s_setprio 0
	s_setprio 1
	v_mfma_f32_16x16x32_bf16 v[116:119], v[184:187], v[200:203], v[116:119]
	v_mfma_f32_16x16x32_bf16 v[112:115], v[192:195], v[200:203], v[112:115]
	v_mfma_f32_16x16x32_bf16 v[100:103], v[184:187], v[208:211], v[100:103]
	v_mfma_f32_16x16x32_bf16 v[96:99], v[192:195], v[208:211], v[96:99]
	v_mfma_f32_16x16x32_bf16 v[84:87], v[184:187], v[216:219], v[84:87]
	v_mfma_f32_16x16x32_bf16 v[80:83], v[192:195], v[216:219], v[80:83]
	v_mfma_f32_16x16x32_bf16 v[68:71], v[184:187], v[224:227], v[68:71]
	v_mfma_f32_16x16x32_bf16 v[64:67], v[192:195], v[224:227], v[64:67]
	v_mfma_f32_16x16x32_bf16 v[116:119], v[188:191], v[204:207], v[116:119]
	v_mfma_f32_16x16x32_bf16 v[112:115], v[196:199], v[204:207], v[112:115]
	v_mfma_f32_16x16x32_bf16 v[100:103], v[188:191], v[212:215], v[100:103]
	v_mfma_f32_16x16x32_bf16 v[96:99], v[196:199], v[212:215], v[96:99]
	v_mfma_f32_16x16x32_bf16 v[84:87], v[188:191], v[220:223], v[84:87]
	v_mfma_f32_16x16x32_bf16 v[80:83], v[196:199], v[220:223], v[80:83]
	v_mfma_f32_16x16x32_bf16 v[68:71], v[188:191], v[228:231], v[68:71]
	v_mfma_f32_16x16x32_bf16 v[64:67], v[196:199], v[228:231], v[64:67]
	s_barrier
	s_setprio 0
	s_mov_b32 m0, s29
	s_add_u32 s98, s0, s14
	s_addc_u32 s99, s1, s15
	s_add_u32 s72, s0, 0x40000
	ds_read_b128 v[200:203], v165 offset:16384
	ds_read_b128 v[204:207], v165 offset:17408
	ds_read_b128 v[208:211], v165 offset:18432
	ds_read_b128 v[212:215], v165 offset:19456
	ds_read_b128 v[216:219], v165 offset:20480
	ds_read_b128 v[220:223], v165 offset:21504
	ds_read_b128 v[224:227], v165 offset:22528
	ds_read_b128 v[228:231], v165 offset:23552
	global_load_lds_dwordx4 v130, s[0:1]
	s_mov_b32 m0, s31
	s_addc_u32 s73, s1, 0
	global_load_lds_dwordx4 v134, s[0:1]
	s_mov_b32 m0, s40
	s_nop 0
	global_load_lds_dwordx4 v130, s[72:73]
	s_mov_b32 m0, s41
	s_nop 0
	global_load_lds_dwordx4 v134, s[72:73]
	s_add_u32 s100, s34, s14
	s_addc_u32 s101, s35, s15
	s_mov_b32 m0, s39
	s_nop 0
	global_load_lds_dwordx4 v128, s[34:35]
	s_mov_b32 m0, s42
	s_nop 0
	global_load_lds_dwordx4 v132, s[34:35]
	s_waitcnt vmcnt(8)
	s_waitcnt lgkmcnt(0)
	s_setprio 1
	s_barrier
	v_mfma_f32_16x16x32_bf16 v[60:63], v[144:147], v[200:203], v[60:63]
	v_mfma_f32_16x16x32_bf16 v[56:59], v[152:155], v[200:203], v[56:59]
	v_mfma_f32_16x16x32_bf16 v[44:47], v[144:147], v[208:211], v[44:47]
	v_mfma_f32_16x16x32_bf16 v[40:43], v[152:155], v[208:211], v[40:43]
	v_mfma_f32_16x16x32_bf16 v[28:31], v[144:147], v[216:219], v[28:31]
	v_mfma_f32_16x16x32_bf16 v[24:27], v[152:155], v[216:219], v[24:27]
	v_mfma_f32_16x16x32_bf16 v[12:15], v[144:147], v[224:227], v[12:15]
	v_mfma_f32_16x16x32_bf16 v[8:11], v[152:155], v[224:227], v[8:11]
	v_mfma_f32_16x16x32_bf16 v[60:63], v[148:151], v[204:207], v[60:63]
	v_mfma_f32_16x16x32_bf16 v[56:59], v[156:159], v[204:207], v[56:59]
	v_mfma_f32_16x16x32_bf16 v[44:47], v[148:151], v[212:215], v[44:47]
	v_mfma_f32_16x16x32_bf16 v[40:43], v[156:159], v[212:215], v[40:43]
	v_mfma_f32_16x16x32_bf16 v[28:31], v[148:151], v[220:223], v[28:31]
	v_mfma_f32_16x16x32_bf16 v[24:27], v[156:159], v[220:223], v[24:27]
	v_mfma_f32_16x16x32_bf16 v[12:15], v[148:151], v[228:231], v[12:15]
	v_mfma_f32_16x16x32_bf16 v[8:11], v[156:159], v[228:231], v[8:11]
	s_setprio 0
	s_setprio 1
	v_mfma_f32_16x16x32_bf16 v[52:55], v[184:187], v[200:203], v[52:55]
	v_mfma_f32_16x16x32_bf16 v[48:51], v[192:195], v[200:203], v[48:51]
	v_mfma_f32_16x16x32_bf16 v[36:39], v[184:187], v[208:211], v[36:39]
	v_mfma_f32_16x16x32_bf16 v[32:35], v[192:195], v[208:211], v[32:35]
	v_mfma_f32_16x16x32_bf16 v[20:23], v[184:187], v[216:219], v[20:23]
	v_mfma_f32_16x16x32_bf16 v[16:19], v[192:195], v[216:219], v[16:19]
	v_mfma_f32_16x16x32_bf16 v[4:7], v[184:187], v[224:227], v[4:7]
	v_mfma_f32_16x16x32_bf16 v[0:3], v[192:195], v[224:227], v[0:3]
	v_mfma_f32_16x16x32_bf16 v[52:55], v[188:191], v[204:207], v[52:55]
	v_mfma_f32_16x16x32_bf16 v[48:51], v[196:199], v[204:207], v[48:51]
	v_mfma_f32_16x16x32_bf16 v[36:39], v[188:191], v[212:215], v[36:39]
	v_mfma_f32_16x16x32_bf16 v[32:35], v[196:199], v[212:215], v[32:35]
	v_mfma_f32_16x16x32_bf16 v[20:23], v[188:191], v[220:223], v[20:23]
	v_mfma_f32_16x16x32_bf16 v[16:19], v[196:199], v[220:223], v[16:19]
	v_mfma_f32_16x16x32_bf16 v[4:7], v[188:191], v[228:231], v[4:7]
	v_mfma_f32_16x16x32_bf16 v[0:3], v[196:199], v[228:231], v[0:3]
	s_barrier
; #define PG8_STAGE(bufoff, gbase, voff) do { _Pragma("unroll") for (int _i = 0; _i < 2; ++_i) \
;         __builtin_amdgcn_global_load_lds((const unsigned*)((const char*)(gbase) + (voff)[_i]), (PG8_LAS unsigned*)(lds + (bufoff) + ldsw + _i * 8192), 16, 0, 0); } while (0)
; #define PG8_LDA(dst, b, h) do { _Pragma("unroll") for (int m = 0; m < 4; ++m) _Pragma("unroll") for (int k = 0; k < 2; ++k) dst[m][k] = *(const PG8_LAS bf16x8*)(lds + PG8_SA(b, h) + aoff + m * 2048 + k * 1024); } while (0)
; #define PG8_LDB(dst, b, h) do { _Pragma("unroll") for (int n = 0; n < 2; ++n) _Pragma("unroll") for (int k = 0; k < 2; ++k) dst[n][k] = *(const PG8_LAS bf16x8*)(lds + PG8_SB(b, h) + boff + n * 2048 + k * 1024); } while (0)
; #define PG8_MMA(ai, bj, At, Bt) do { __builtin_amdgcn_s_setprio(1); _Pragma("unroll") for (int m = 0; m < 4; ++m) _Pragma("unroll") for (int n = 0; n < 2; ++n) _Pragma("unroll") for (int k = 0; k < 2; ++k) \
;         acc[ai][bj][m][n] = __builtin_amdgcn_mfma_f32_16x16x32_bf16(Bt[n][k], At[m][k], acc[ai][bj][m][n], 0, 0, 0); __builtin_amdgcn_s_setprio(0); } while (0)
; #define PG8_WAIT_V(n) asm volatile("s_waitcnt vmcnt(" #n ")" ::: "memory")
; #define PG8_WAIT_L(n) asm volatile("s_waitcnt lgkmcnt(" #n ")" ::: "memory")
; #define PG8_BAR __builtin_amdgcn_s_barrier()
; #define PG8_SCHED __builtin_amdgcn_sched_barrier(0)
; template <class Epi, class Sched, bool ALIGN_EPI = false, bool SP2 = false>
; __device__ __forceinline__ void gemm_phase(PG8_LAS unsigned char* lds, const Gemm g, const Sched& S, const Epi& E, const int tid_arg) {
;     ...
;         for (int t = 0; t < nt; t += 2) {
;             const bool last = (t == nt - 2);
;     ...
;             PG8_LDB(B0, 1, 0); PG8_LDB(B1, 1, 1); PG8_SCHED; PG8_LDA(At, 1, 0); PG8_STAGE(PG8_SA(0, 1), a2 + hstep, voffA);
;             PG8_WAIT_V(8); PG8_WAIT_L(0); PG8_BAR; PG8_MMA(0, 0, At, B0); PG8_MMA(0, 1, At, B1); PG8_BAR; PG8_SCHED;
;             PG8_LDA(At, 1, 1); PG8_STAGE(PG8_SB(1, 0), b3, voffB); PG8_STAGE(PG8_SB(1, 1), b3 + hstep, voffB); PG8_STAGE(PG8_SA(1, 0), a3, voffA);
;             PG8_WAIT_V(8); PG8_WAIT_L(0); PG8_BAR; PG8_MMA(1, 0, At, B0); PG8_MMA(1, 1, At, B1); PG8_BAR; PG8_SCHED;
;     ...
;         if constexpr (ALIGN_EPI) { if (wr == 0) PG8_BAR; }
	s_setprio 0
	ds_read_b128 v[144:147], v174
	ds_read_b128 v[148:151], v175
	ds_read_b128 v[152:155], v176
	ds_read_b128 v[156:159], v177
	ds_read_b128 v[184:187], v178
	ds_read_b128 v[188:191], v179
	ds_read_b128 v[192:195], v180
	ds_read_b128 v[196:199], v181
	s_add_u32 s34, s34, 0x40000
	s_addc_u32 s35, s35, 0
	s_mov_b32 m0, s43
	ds_read_b128 v[200:203], v165 offset:32768
	ds_read_b128 v[204:207], v165 offset:33792
	ds_read_b128 v[208:211], v165 offset:34816
	ds_read_b128 v[212:215], v165 offset:35840
	ds_read_b128 v[216:219], v165 offset:36864
	ds_read_b128 v[220:223], v165 offset:37888
	ds_read_b128 v[224:227], v165 offset:38912
	ds_read_b128 v[228:231], v165 offset:39936
	global_load_lds_dwordx4 v128, s[34:35]
	s_mov_b32 m0, s44
	s_nop 0
	global_load_lds_dwordx4 v132, s[34:35]
	s_waitcnt vmcnt(8)
	s_waitcnt lgkmcnt(0)
	s_setprio 1
	s_barrier
	v_mfma_f32_16x16x32_bf16 v[124:127], v[144:147], v[200:203], v[124:127]
	v_mfma_f32_16x16x32_bf16 v[120:123], v[152:155], v[200:203], v[120:123]
	v_mfma_f32_16x16x32_bf16 v[108:111], v[144:147], v[208:211], v[108:111]
	v_mfma_f32_16x16x32_bf16 v[104:107], v[152:155], v[208:211], v[104:107]
	v_mfma_f32_16x16x32_bf16 v[92:95], v[144:147], v[216:219], v[92:95]
	v_mfma_f32_16x16x32_bf16 v[88:91], v[152:155], v[216:219], v[88:91]
	v_mfma_f32_16x16x32_bf16 v[76:79], v[144:147], v[224:227], v[76:79]
	v_mfma_f32_16x16x32_bf16 v[72:75], v[152:155], v[224:227], v[72:75]
	v_mfma_f32_16x16x32_bf16 v[124:127], v[148:151], v[204:207], v[124:127]
	v_mfma_f32_16x16x32_bf16 v[120:123], v[156:159], v[204:207], v[120:123]
	v_mfma_f32_16x16x32_bf16 v[108:111], v[148:151], v[212:215], v[108:111]
	v_mfma_f32_16x16x32_bf16 v[104:107], v[156:159], v[212:215], v[104:107]
	v_mfma_f32_16x16x32_bf16 v[92:95], v[148:151], v[220:223], v[92:95]
	v_mfma_f32_16x16x32_bf16 v[88:91], v[156:159], v[220:223], v[88:91]
	v_mfma_f32_16x16x32_bf16 v[76:79], v[148:151], v[228:231], v[76:79]
	v_mfma_f32_16x16x32_bf16 v[72:75], v[156:159], v[228:231], v[72:75]
	s_setprio 0
	s_setprio 1
	v_mfma_f32_16x16x32_bf16 v[116:119], v[184:187], v[200:203], v[116:119]
	v_mfma_f32_16x16x32_bf16 v[112:115], v[192:195], v[200:203], v[112:115]
	v_mfma_f32_16x16x32_bf16 v[100:103], v[184:187], v[208:211], v[100:103]
	v_mfma_f32_16x16x32_bf16 v[96:99], v[192:195], v[208:211], v[96:99]
	v_mfma_f32_16x16x32_bf16 v[84:87], v[184:187], v[216:219], v[84:87]
	v_mfma_f32_16x16x32_bf16 v[80:83], v[192:195], v[216:219], v[80:83]
	v_mfma_f32_16x16x32_bf16 v[68:71], v[184:187], v[224:227], v[68:71]
	v_mfma_f32_16x16x32_bf16 v[64:67], v[192:195], v[224:227], v[64:67]
	v_mfma_f32_16x16x32_bf16 v[116:119], v[188:191], v[204:207], v[116:119]
	v_mfma_f32_16x16x32_bf16 v[112:115], v[196:199], v[204:207], v[112:115]
	v_mfma_f32_16x16x32_bf16 v[100:103], v[188:191], v[212:215], v[100:103]
	v_mfma_f32_16x16x32_bf16 v[96:99], v[196:199], v[212:215], v[96:99]
	v_mfma_f32_16x16x32_bf16 v[84:87], v[188:191], v[220:223], v[84:87]
	v_mfma_f32_16x16x32_bf16 v[80:83], v[196:199], v[220:223], v[80:83]
	v_mfma_f32_16x16x32_bf16 v[68:71], v[188:191], v[228:231], v[68:71]
	v_mfma_f32_16x16x32_bf16 v[64:67], v[196:199], v[228:231], v[64:67]
	s_barrier
	s_setprio 0
	s_mov_b32 m0, s47
	s_add_u32 s0, s0, 0x40080
	ds_read_b128 v[200:203], v165 offset:49152
	ds_read_b128 v[204:207], v165 offset:50176
	ds_read_b128 v[208:211], v165 offset:51200
	ds_read_b128 v[212:215], v165 offset:52224
	ds_read_b128 v[216:219], v165 offset:53248
	ds_read_b128 v[220:223], v165 offset:54272
	ds_read_b128 v[224:227], v165 offset:55296
	ds_read_b128 v[228:231], v165 offset:56320
	global_load_lds_dwordx4 v130, s[98:99]
	s_mov_b32 m0, s48
	s_addc_u32 s1, s1, 0
	global_load_lds_dwordx4 v134, s[98:99]
	s_mov_b32 m0, s51
	s_nop 0
	global_load_lds_dwordx4 v130, s[0:1]
	s_mov_b32 m0, s52
	s_nop 0
	global_load_lds_dwordx4 v134, s[0:1]
	s_mov_b32 m0, s49
	s_nop 0
	global_load_lds_dwordx4 v128, s[100:101]
	s_mov_b32 m0, s50
	s_nop 0
	global_load_lds_dwordx4 v132, s[100:101]
	s_waitcnt vmcnt(8)
	s_waitcnt lgkmcnt(0)
	s_setprio 1
	s_barrier
	v_mfma_f32_16x16x32_bf16 v[60:63], v[144:147], v[200:203], v[60:63]
	v_mfma_f32_16x16x32_bf16 v[56:59], v[152:155], v[200:203], v[56:59]
	v_mfma_f32_16x16x32_bf16 v[44:47], v[144:147], v[208:211], v[44:47]
	v_mfma_f32_16x16x32_bf16 v[40:43], v[152:155], v[208:211], v[40:43]
	v_mfma_f32_16x16x32_bf16 v[28:31], v[144:147], v[216:219], v[28:31]
	v_mfma_f32_16x16x32_bf16 v[24:27], v[152:155], v[216:219], v[24:27]
	v_mfma_f32_16x16x32_bf16 v[12:15], v[144:147], v[224:227], v[12:15]
	v_mfma_f32_16x16x32_bf16 v[8:11], v[152:155], v[224:227], v[8:11]
	v_mfma_f32_16x16x32_bf16 v[60:63], v[148:151], v[204:207], v[60:63]
	v_mfma_f32_16x16x32_bf16 v[56:59], v[156:159], v[204:207], v[56:59]
	v_mfma_f32_16x16x32_bf16 v[44:47], v[148:151], v[212:215], v[44:47]
	v_mfma_f32_16x16x32_bf16 v[40:43], v[156:159], v[212:215], v[40:43]
	v_mfma_f32_16x16x32_bf16 v[28:31], v[148:151], v[220:223], v[28:31]
	v_mfma_f32_16x16x32_bf16 v[24:27], v[156:159], v[220:223], v[24:27]
	v_mfma_f32_16x16x32_bf16 v[12:15], v[148:151], v[228:231], v[12:15]
	v_mfma_f32_16x16x32_bf16 v[8:11], v[156:159], v[228:231], v[8:11]
	s_setprio 0
	s_setprio 1
	v_mfma_f32_16x16x32_bf16 v[52:55], v[184:187], v[200:203], v[52:55]
	v_mfma_f32_16x16x32_bf16 v[48:51], v[192:195], v[200:203], v[48:51]
	v_mfma_f32_16x16x32_bf16 v[36:39], v[184:187], v[208:211], v[36:39]
	v_mfma_f32_16x16x32_bf16 v[32:35], v[192:195], v[208:211], v[32:35]
	v_mfma_f32_16x16x32_bf16 v[20:23], v[184:187], v[216:219], v[20:23]
	v_mfma_f32_16x16x32_bf16 v[16:19], v[192:195], v[216:219], v[16:19]
	v_mfma_f32_16x16x32_bf16 v[4:7], v[184:187], v[224:227], v[4:7]
	v_mfma_f32_16x16x32_bf16 v[0:3], v[192:195], v[224:227], v[0:3]
	v_mfma_f32_16x16x32_bf16 v[52:55], v[188:191], v[204:207], v[52:55]
	v_mfma_f32_16x16x32_bf16 v[48:51], v[196:199], v[204:207], v[48:51]
	v_mfma_f32_16x16x32_bf16 v[36:39], v[188:191], v[212:215], v[36:39]
	v_mfma_f32_16x16x32_bf16 v[32:35], v[196:199], v[212:215], v[32:35]
	v_mfma_f32_16x16x32_bf16 v[20:23], v[188:191], v[220:223], v[20:23]
	v_mfma_f32_16x16x32_bf16 v[16:19], v[196:199], v[220:223], v[16:19]
	v_mfma_f32_16x16x32_bf16 v[4:7], v[188:191], v[228:231], v[4:7]
	v_mfma_f32_16x16x32_bf16 v[0:3], v[196:199], v[228:231], v[0:3]
	s_barrier
	s_setprio 0
	s_add_i32 s70, s70, 2
	s_add_u32 s68, s68, 0x100
	s_addc_u32 s69, s69, 0
	s_add_u32 s8, s8, 0x100
	s_addc_u32 s9, s9, 0
	s_cmp_gt_u32 s70, 13
	s_cbranch_scc0 .LBB0_253
	s_and_b64 vcc, exec, s[16:17]
	s_cbranch_vccz .LBB0_256
	s_barrier

; #define PG8_STAGE(bufoff, gbase, voff) do { _Pragma("unroll") for (int _i = 0; _i < 2; ++_i) \
;         __builtin_amdgcn_global_load_lds((const unsigned*)((const char*)(gbase) + (voff)[_i]), (PG8_LAS unsigned*)(lds + (bufoff) + ldsw + _i * 8192), 16, 0, 0); } while (0)
; #define PG8_LDA(dst, b, h) do { _Pragma("unroll") for (int m = 0; m < 4; ++m) _Pragma("unroll") for (int k = 0; k < 2; ++k) dst[m][k] = *(const PG8_LAS bf16x8*)(lds + PG8_SA(b, h) + aoff + m * 2048 + k * 1024); } while (0)
; #define PG8_LDB(dst, b, h) do { _Pragma("unroll") for (int n = 0; n < 2; ++n) _Pragma("unroll") for (int k = 0; k < 2; ++k) dst[n][k] = *(const PG8_LAS bf16x8*)(lds + PG8_SB(b, h) + boff + n * 2048 + k * 1024); } while (0)
; #define PG8_WAIT_V(n) asm volatile("s_waitcnt vmcnt(" #n ")" ::: "memory")
; #define PG8_WAIT_L(n) asm volatile("s_waitcnt lgkmcnt(" #n ")" ::: "memory")
; #define PG8_BAR __builtin_amdgcn_s_barrier()
; #define PG8_SCHED __builtin_amdgcn_sched_barrier(0)
; template <class Epi, class Sched, bool ALIGN_EPI = false, bool SP2 = false>
; __device__ __forceinline__ void gemm_phase(PG8_LAS unsigned char* lds, const Gemm g, const Sched& S, const Epi& E, const int tid_arg) {
;     ...
;         const bool has_next = S.next(ui + 1, nxt);
;         const char* nA = has_next ? (const char*)g.A + (size_t)nxt.pm * tstep : cA; const char* nB = has_next ? (const char*)g.Bt + (size_t)nxt.pn * tstep : cB;
;         for (int t = 0; t < nt; t += 2) {
;             const bool last = (t == nt - 2);
;             const char* a1 = cA + (size_t)(t + 1) * kstep;
;             const char* a2 = last ? nA : cA + (size_t)(t + 2) * kstep; const char* b2 = last ? nB : cB + (size_t)(t + 2) * kstep;
;             const char* a3 = a2 + kstep; const char* b3 = b2 + kstep;
;             if (last && has_next) S.a_ready(nxt);
;             if constexpr (SP2) {
;             PG8_LDB(B0, 0, 0); PG8_LDB(B1, 0, 1); PG8_SCHED; PG8_LDA(At, 0, 0); PG8_STAGE(PG8_SA(1, 1), a1 + hstep, voffA);
;             PG8_WAIT_V(8); PG8_WAIT_L(0); PG8_BAR; PG8_MMA(0, 0, At, B0); PG8_MMA(0, 1, At, B1); PG8_BAR; PG8_SCHED;
;             PG8_LDA(At, 0, 1); PG8_STAGE(PG8_SB(0, 0), b2, voffB); PG8_STAGE(PG8_SB(0, 1), b2 + hstep, voffB); PG8_STAGE(PG8_SA(0, 0), a2, voffA);
;             PG8_WAIT_V(8); PG8_WAIT_L(0); PG8_BAR; PG8_MMA(1, 0, At, B0); PG8_MMA(1, 1, At, B1); PG8_BAR; PG8_SCHED;
.LBB0_533:
	ds_read_b128 v[128:131], v165
	ds_read_b128 v[132:135], v166
	ds_read_b128 v[152:155], v167
	ds_read_b128 v[156:159], v168
	ds_read_b128 v[182:185], v169
	ds_read_b128 v[186:189], v170
	ds_read_b128 v[190:193], v171
	ds_read_b128 v[194:197], v172
	s_add_u32 s0, s12, 0xfffc0080
	s_addc_u32 s1, s13, -1
	s_cmp_eq_u32 s65, 12
	s_cselect_b32 s37, s11, s1
	s_cselect_b32 s36, s29, s0
	s_cselect_b32 s1, s27, s64
	s_cselect_b32 s0, s62, s63
	s_mov_b32 m0, s59
	ds_read_b128 v[198:201], v164
	ds_read_b128 v[202:205], v164 offset:1024
	ds_read_b128 v[206:209], v164 offset:2048
	ds_read_b128 v[210:213], v164 offset:3072
	ds_read_b128 v[214:217], v164 offset:4096
	ds_read_b128 v[218:221], v164 offset:5120
	ds_read_b128 v[222:225], v164 offset:6144
	ds_read_b128 v[226:229], v164 offset:7168
	global_load_lds_dwordx4 v146, s[12:13]
	s_mov_b32 m0, s60
	s_nop 0
	global_load_lds_dwordx4 v144, s[12:13]
	s_waitcnt vmcnt(8)
	s_waitcnt lgkmcnt(0)
	s_setprio 1
	s_barrier
	v_mfma_f32_16x16x32_bf16 v[124:127], v[128:131], v[198:201], v[124:127]
	v_mfma_f32_16x16x32_bf16 v[120:123], v[152:155], v[198:201], v[120:123]
	v_mfma_f32_16x16x32_bf16 v[108:111], v[128:131], v[206:209], v[108:111]
	v_mfma_f32_16x16x32_bf16 v[104:107], v[152:155], v[206:209], v[104:107]
	v_mfma_f32_16x16x32_bf16 v[92:95], v[128:131], v[214:217], v[92:95]
	v_mfma_f32_16x16x32_bf16 v[88:91], v[152:155], v[214:217], v[88:91]
	v_mfma_f32_16x16x32_bf16 v[76:79], v[128:131], v[222:225], v[76:79]
	v_mfma_f32_16x16x32_bf16 v[72:75], v[152:155], v[222:225], v[72:75]
	v_mfma_f32_16x16x32_bf16 v[124:127], v[132:135], v[202:205], v[124:127]
	v_mfma_f32_16x16x32_bf16 v[120:123], v[156:159], v[202:205], v[120:123]
	v_mfma_f32_16x16x32_bf16 v[108:111], v[132:135], v[210:213], v[108:111]
	v_mfma_f32_16x16x32_bf16 v[104:107], v[156:159], v[210:213], v[104:107]
	v_mfma_f32_16x16x32_bf16 v[92:95], v[132:135], v[218:221], v[92:95]
	v_mfma_f32_16x16x32_bf16 v[88:91], v[156:159], v[218:221], v[88:91]
	v_mfma_f32_16x16x32_bf16 v[76:79], v[132:135], v[226:229], v[76:79]
	v_mfma_f32_16x16x32_bf16 v[72:75], v[156:159], v[226:229], v[72:75]
	s_setprio 0
	s_setprio 1
	v_mfma_f32_16x16x32_bf16 v[116:119], v[182:185], v[198:201], v[116:119]
	v_mfma_f32_16x16x32_bf16 v[112:115], v[190:193], v[198:201], v[112:115]
	v_mfma_f32_16x16x32_bf16 v[100:103], v[182:185], v[206:209], v[100:103]
	v_mfma_f32_16x16x32_bf16 v[96:99], v[190:193], v[206:209], v[96:99]
	v_mfma_f32_16x16x32_bf16 v[84:87], v[182:185], v[214:217], v[84:87]
	v_mfma_f32_16x16x32_bf16 v[80:83], v[190:193], v[214:217], v[80:83]
	v_mfma_f32_16x16x32_bf16 v[68:71], v[182:185], v[222:225], v[68:71]
	v_mfma_f32_16x16x32_bf16 v[64:67], v[190:193], v[222:225], v[64:67]
	v_mfma_f32_16x16x32_bf16 v[116:119], v[186:189], v[202:205], v[116:119]
	v_mfma_f32_16x16x32_bf16 v[112:115], v[194:197], v[202:205], v[112:115]
	v_mfma_f32_16x16x32_bf16 v[100:103], v[186:189], v[210:213], v[100:103]
	v_mfma_f32_16x16x32_bf16 v[96:99], v[194:197], v[210:213], v[96:99]
	v_mfma_f32_16x16x32_bf16 v[84:87], v[186:189], v[218:221], v[84:87]
	v_mfma_f32_16x16x32_bf16 v[80:83], v[194:197], v[218:221], v[80:83]
	v_mfma_f32_16x16x32_bf16 v[68:71], v[186:189], v[226:229], v[68:71]
	v_mfma_f32_16x16x32_bf16 v[64:67], v[194:197], v[226:229], v[64:67]
	s_barrier
	s_setprio 0
	s_mov_b32 m0, s5
	s_add_u32 s98, s0, s20
	s_addc_u32 s99, s1, s21
	s_add_u32 s66, s0, 0x40000
	ds_read_b128 v[198:201], v164 offset:16384
	ds_read_b128 v[202:205], v164 offset:17408
	ds_read_b128 v[206:209], v164 offset:18432
	ds_read_b128 v[210:213], v164 offset:19456
	ds_read_b128 v[214:217], v164 offset:20480
	ds_read_b128 v[218:221], v164 offset:21504
	ds_read_b128 v[222:225], v164 offset:22528
	ds_read_b128 v[226:229], v164 offset:23552
	global_load_lds_dwordx4 v138, s[0:1]
	s_mov_b32 m0, s40
	s_addc_u32 s67, s1, 0
	global_load_lds_dwordx4 v142, s[0:1]
	s_mov_b32 m0, s41
	s_nop 0
	global_load_lds_dwordx4 v138, s[66:67]
	s_mov_b32 m0, s42
	s_nop 0
	global_load_lds_dwordx4 v142, s[66:67]
	s_add_u32 s100, s36, s20
	s_addc_u32 s101, s37, s21
	s_mov_b32 m0, s39
	s_nop 0
	global_load_lds_dwordx4 v136, s[36:37]
	s_mov_b32 m0, s43
	s_nop 0
	global_load_lds_dwordx4 v140, s[36:37]
	s_waitcnt vmcnt(8)
	s_waitcnt lgkmcnt(0)
	s_setprio 1
	s_barrier
	v_mfma_f32_16x16x32_bf16 v[60:63], v[128:131], v[198:201], v[60:63]
	v_mfma_f32_16x16x32_bf16 v[56:59], v[152:155], v[198:201], v[56:59]
	v_mfma_f32_16x16x32_bf16 v[44:47], v[128:131], v[206:209], v[44:47]
	v_mfma_f32_16x16x32_bf16 v[40:43], v[152:155], v[206:209], v[40:43]
	v_mfma_f32_16x16x32_bf16 v[28:31], v[128:131], v[214:217], v[28:31]
	v_mfma_f32_16x16x32_bf16 v[24:27], v[152:155], v[214:217], v[24:27]
	v_mfma_f32_16x16x32_bf16 v[12:15], v[128:131], v[222:225], v[12:15]
	v_mfma_f32_16x16x32_bf16 v[8:11], v[152:155], v[222:225], v[8:11]
	v_mfma_f32_16x16x32_bf16 v[60:63], v[132:135], v[202:205], v[60:63]
	v_mfma_f32_16x16x32_bf16 v[56:59], v[156:159], v[202:205], v[56:59]
	v_mfma_f32_16x16x32_bf16 v[44:47], v[132:135], v[210:213], v[44:47]
	v_mfma_f32_16x16x32_bf16 v[40:43], v[156:159], v[210:213], v[40:43]
	v_mfma_f32_16x16x32_bf16 v[28:31], v[132:135], v[218:221], v[28:31]
	v_mfma_f32_16x16x32_bf16 v[24:27], v[156:159], v[218:221], v[24:27]
	v_mfma_f32_16x16x32_bf16 v[12:15], v[132:135], v[226:229], v[12:15]
	v_mfma_f32_16x16x32_bf16 v[8:11], v[156:159], v[226:229], v[8:11]
	s_setprio 0
	s_setprio 1
	v_mfma_f32_16x16x32_bf16 v[52:55], v[182:185], v[198:201], v[52:55]
	v_mfma_f32_16x16x32_bf16 v[48:51], v[190:193], v[198:201], v[48:51]
	v_mfma_f32_16x16x32_bf16 v[36:39], v[182:185], v[206:209], v[36:39]
	v_mfma_f32_16x16x32_bf16 v[32:35], v[190:193], v[206:209], v[32:35]
	v_mfma_f32_16x16x32_bf16 v[20:23], v[182:185], v[214:217], v[20:23]
	v_mfma_f32_16x16x32_bf16 v[16:19], v[190:193], v[214:217], v[16:19]
	v_mfma_f32_16x16x32_bf16 v[4:7], v[182:185], v[222:225], v[4:7]
	v_mfma_f32_16x16x32_bf16 v[0:3], v[190:193], v[222:225], v[0:3]
	v_mfma_f32_16x16x32_bf16 v[52:55], v[186:189], v[202:205], v[52:55]
	v_mfma_f32_16x16x32_bf16 v[48:51], v[194:197], v[202:205], v[48:51]
	v_mfma_f32_16x16x32_bf16 v[36:39], v[186:189], v[210:213], v[36:39]
	v_mfma_f32_16x16x32_bf16 v[32:35], v[194:197], v[210:213], v[32:35]
	v_mfma_f32_16x16x32_bf16 v[20:23], v[186:189], v[218:221], v[20:23]
	v_mfma_f32_16x16x32_bf16 v[16:19], v[194:197], v[218:221], v[16:19]
	v_mfma_f32_16x16x32_bf16 v[4:7], v[186:189], v[226:229], v[4:7]
	v_mfma_f32_16x16x32_bf16 v[0:3], v[194:197], v[226:229], v[0:3]
	s_barrier
; #define PG8_STAGE(bufoff, gbase, voff) do { _Pragma("unroll") for (int _i = 0; _i < 2; ++_i) \
;         __builtin_amdgcn_global_load_lds((const unsigned*)((const char*)(gbase) + (voff)[_i]), (PG8_LAS unsigned*)(lds + (bufoff) + ldsw + _i * 8192), 16, 0, 0); } while (0)
; #define PG8_LDA(dst, b, h) do { _Pragma("unroll") for (int m = 0; m < 4; ++m) _Pragma("unroll") for (int k = 0; k < 2; ++k) dst[m][k] = *(const PG8_LAS bf16x8*)(lds + PG8_SA(b, h) + aoff + m * 2048 + k * 1024); } while (0)
; #define PG8_LDB(dst, b, h) do { _Pragma("unroll") for (int n = 0; n < 2; ++n) _Pragma("unroll") for (int k = 0; k < 2; ++k) dst[n][k] = *(const PG8_LAS bf16x8*)(lds + PG8_SB(b, h) + boff + n * 2048 + k * 1024); } while (0)
; #define PG8_MMA(ai, bj, At, Bt) do { __builtin_amdgcn_s_setprio(1); _Pragma("unroll") for (int m = 0; m < 4; ++m) _Pragma("unroll") for (int n = 0; n < 2; ++n) _Pragma("unroll") for (int k = 0; k < 2; ++k) \
;         acc[ai][bj][m][n] = __builtin_amdgcn_mfma_f32_16x16x32_bf16(Bt[n][k], At[m][k], acc[ai][bj][m][n], 0, 0, 0); __builtin_amdgcn_s_setprio(0); } while (0)
; #define PG8_WAIT_V(n) asm volatile("s_waitcnt vmcnt(" #n ")" ::: "memory")
; #define PG8_WAIT_L(n) asm volatile("s_waitcnt lgkmcnt(" #n ")" ::: "memory")
; #define PG8_BAR __builtin_amdgcn_s_barrier()
; #define PG8_SCHED __builtin_amdgcn_sched_barrier(0)
; template <class Epi, class Sched, bool ALIGN_EPI = false, bool SP2 = false>
; __device__ __forceinline__ void gemm_phase(PG8_LAS unsigned char* lds, const Gemm g, const Sched& S, const Epi& E, const int tid_arg) {
;     ...
;         for (int t = 0; t < nt; t += 2) {
;             const bool last = (t == nt - 2);
;     ...
;             PG8_LDB(B0, 1, 0); PG8_LDB(B1, 1, 1); PG8_SCHED; PG8_LDA(At, 1, 0); PG8_STAGE(PG8_SA(0, 1), a2 + hstep, voffA);
;             PG8_WAIT_V(8); PG8_WAIT_L(0); PG8_BAR; PG8_MMA(0, 0, At, B0); PG8_MMA(0, 1, At, B1); PG8_BAR; PG8_SCHED;
;             PG8_LDA(At, 1, 1); PG8_STAGE(PG8_SB(1, 0), b3, voffB); PG8_STAGE(PG8_SB(1, 1), b3 + hstep, voffB); PG8_STAGE(PG8_SA(1, 0), a3, voffA);
;             PG8_WAIT_V(8); PG8_WAIT_L(0); PG8_BAR; PG8_MMA(1, 0, At, B0); PG8_MMA(1, 1, At, B1); PG8_BAR; PG8_SCHED;
;     ...
;         if constexpr (ALIGN_EPI) { if (wr == 0) PG8_BAR; }
	s_setprio 0
	ds_read_b128 v[128:131], v173
	ds_read_b128 v[132:135], v174
	ds_read_b128 v[152:155], v175
	ds_read_b128 v[156:159], v176
	ds_read_b128 v[182:185], v177
	ds_read_b128 v[186:189], v178
	ds_read_b128 v[190:193], v179
	ds_read_b128 v[194:197], v180
	s_add_u32 s36, s36, 0x40000
	s_addc_u32 s37, s37, 0
	s_mov_b32 m0, s44
	ds_read_b128 v[198:201], v164 offset:32768
	ds_read_b128 v[202:205], v164 offset:33792
	ds_read_b128 v[206:209], v164 offset:34816
	ds_read_b128 v[210:213], v164 offset:35840
	ds_read_b128 v[214:217], v164 offset:36864
	ds_read_b128 v[218:221], v164 offset:37888
	ds_read_b128 v[222:225], v164 offset:38912
	ds_read_b128 v[226:229], v164 offset:39936
	global_load_lds_dwordx4 v136, s[36:37]
	s_mov_b32 m0, s45
	s_nop 0
	global_load_lds_dwordx4 v140, s[36:37]
	s_waitcnt vmcnt(8)
	s_waitcnt lgkmcnt(0)
	s_setprio 1
	s_barrier
	v_mfma_f32_16x16x32_bf16 v[124:127], v[128:131], v[198:201], v[124:127]
	v_mfma_f32_16x16x32_bf16 v[120:123], v[152:155], v[198:201], v[120:123]
	v_mfma_f32_16x16x32_bf16 v[108:111], v[128:131], v[206:209], v[108:111]
	v_mfma_f32_16x16x32_bf16 v[104:107], v[152:155], v[206:209], v[104:107]
	v_mfma_f32_16x16x32_bf16 v[92:95], v[128:131], v[214:217], v[92:95]
	v_mfma_f32_16x16x32_bf16 v[88:91], v[152:155], v[214:217], v[88:91]
	v_mfma_f32_16x16x32_bf16 v[76:79], v[128:131], v[222:225], v[76:79]
	v_mfma_f32_16x16x32_bf16 v[72:75], v[152:155], v[222:225], v[72:75]
	v_mfma_f32_16x16x32_bf16 v[124:127], v[132:135], v[202:205], v[124:127]
	v_mfma_f32_16x16x32_bf16 v[120:123], v[156:159], v[202:205], v[120:123]
	v_mfma_f32_16x16x32_bf16 v[108:111], v[132:135], v[210:213], v[108:111]
	v_mfma_f32_16x16x32_bf16 v[104:107], v[156:159], v[210:213], v[104:107]
	v_mfma_f32_16x16x32_bf16 v[92:95], v[132:135], v[218:221], v[92:95]
	v_mfma_f32_16x16x32_bf16 v[88:91], v[156:159], v[218:221], v[88:91]
	v_mfma_f32_16x16x32_bf16 v[76:79], v[132:135], v[226:229], v[76:79]
	v_mfma_f32_16x16x32_bf16 v[72:75], v[156:159], v[226:229], v[72:75]
	s_setprio 0
	s_setprio 1
	v_mfma_f32_16x16x32_bf16 v[116:119], v[182:185], v[198:201], v[116:119]
	v_mfma_f32_16x16x32_bf16 v[112:115], v[190:193], v[198:201], v[112:115]
	v_mfma_f32_16x16x32_bf16 v[100:103], v[182:185], v[206:209], v[100:103]
	v_mfma_f32_16x16x32_bf16 v[96:99], v[190:193], v[206:209], v[96:99]
	v_mfma_f32_16x16x32_bf16 v[84:87], v[182:185], v[214:217], v[84:87]
	v_mfma_f32_16x16x32_bf16 v[80:83], v[190:193], v[214:217], v[80:83]
	v_mfma_f32_16x16x32_bf16 v[68:71], v[182:185], v[222:225], v[68:71]
	v_mfma_f32_16x16x32_bf16 v[64:67], v[190:193], v[222:225], v[64:67]
	v_mfma_f32_16x16x32_bf16 v[116:119], v[186:189], v[202:205], v[116:119]
	v_mfma_f32_16x16x32_bf16 v[112:115], v[194:197], v[202:205], v[112:115]
	v_mfma_f32_16x16x32_bf16 v[100:103], v[186:189], v[210:213], v[100:103]
	v_mfma_f32_16x16x32_bf16 v[96:99], v[194:197], v[210:213], v[96:99]
	v_mfma_f32_16x16x32_bf16 v[84:87], v[186:189], v[218:221], v[84:87]
	v_mfma_f32_16x16x32_bf16 v[80:83], v[194:197], v[218:221], v[80:83]
	v_mfma_f32_16x16x32_bf16 v[68:71], v[186:189], v[226:229], v[68:71]
	v_mfma_f32_16x16x32_bf16 v[64:67], v[194:197], v[226:229], v[64:67]
	s_barrier
	s_setprio 0
	s_mov_b32 m0, s49
	s_add_u32 s0, s0, 0x40080
	ds_read_b128 v[198:201], v164 offset:49152
	ds_read_b128 v[202:205], v164 offset:50176
	ds_read_b128 v[206:209], v164 offset:51200
	ds_read_b128 v[210:213], v164 offset:52224
	ds_read_b128 v[214:217], v164 offset:53248
	ds_read_b128 v[218:221], v164 offset:54272
	ds_read_b128 v[222:225], v164 offset:55296
	ds_read_b128 v[226:229], v164 offset:56320
	global_load_lds_dwordx4 v138, s[98:99]
	s_mov_b32 m0, s50
	s_addc_u32 s1, s1, 0
	global_load_lds_dwordx4 v142, s[98:99]
	s_mov_b32 m0, s53
	s_nop 0
	global_load_lds_dwordx4 v138, s[0:1]
	s_mov_b32 m0, s54
	s_nop 0
	global_load_lds_dwordx4 v142, s[0:1]
	s_mov_b32 m0, s51
	s_nop 0
	global_load_lds_dwordx4 v136, s[100:101]
	s_mov_b32 m0, s52
	s_nop 0
	global_load_lds_dwordx4 v140, s[100:101]
	s_waitcnt vmcnt(8)
	s_waitcnt lgkmcnt(0)
	s_setprio 1
	s_barrier
	v_mfma_f32_16x16x32_bf16 v[60:63], v[128:131], v[198:201], v[60:63]
	v_mfma_f32_16x16x32_bf16 v[56:59], v[152:155], v[198:201], v[56:59]
	v_mfma_f32_16x16x32_bf16 v[44:47], v[128:131], v[206:209], v[44:47]
	v_mfma_f32_16x16x32_bf16 v[40:43], v[152:155], v[206:209], v[40:43]
	v_mfma_f32_16x16x32_bf16 v[28:31], v[128:131], v[214:217], v[28:31]
	v_mfma_f32_16x16x32_bf16 v[24:27], v[152:155], v[214:217], v[24:27]
	v_mfma_f32_16x16x32_bf16 v[12:15], v[128:131], v[222:225], v[12:15]
	v_mfma_f32_16x16x32_bf16 v[8:11], v[152:155], v[222:225], v[8:11]
	v_mfma_f32_16x16x32_bf16 v[60:63], v[132:135], v[202:205], v[60:63]
	v_mfma_f32_16x16x32_bf16 v[56:59], v[156:159], v[202:205], v[56:59]
	v_mfma_f32_16x16x32_bf16 v[44:47], v[132:135], v[210:213], v[44:47]
	v_mfma_f32_16x16x32_bf16 v[40:43], v[156:159], v[210:213], v[40:43]
	v_mfma_f32_16x16x32_bf16 v[28:31], v[132:135], v[218:221], v[28:31]
	v_mfma_f32_16x16x32_bf16 v[24:27], v[156:159], v[218:221], v[24:27]
	v_mfma_f32_16x16x32_bf16 v[12:15], v[132:135], v[226:229], v[12:15]
	v_mfma_f32_16x16x32_bf16 v[8:11], v[156:159], v[226:229], v[8:11]
	s_setprio 0
	s_setprio 1
	v_mfma_f32_16x16x32_bf16 v[52:55], v[182:185], v[198:201], v[52:55]
	v_mfma_f32_16x16x32_bf16 v[48:51], v[190:193], v[198:201], v[48:51]
	v_mfma_f32_16x16x32_bf16 v[36:39], v[182:185], v[206:209], v[36:39]
	v_mfma_f32_16x16x32_bf16 v[32:35], v[190:193], v[206:209], v[32:35]
	v_mfma_f32_16x16x32_bf16 v[20:23], v[182:185], v[214:217], v[20:23]
	v_mfma_f32_16x16x32_bf16 v[16:19], v[190:193], v[214:217], v[16:19]
	v_mfma_f32_16x16x32_bf16 v[4:7], v[182:185], v[222:225], v[4:7]
	v_mfma_f32_16x16x32_bf16 v[0:3], v[190:193], v[222:225], v[0:3]
	v_mfma_f32_16x16x32_bf16 v[52:55], v[186:189], v[202:205], v[52:55]
	v_mfma_f32_16x16x32_bf16 v[48:51], v[194:197], v[202:205], v[48:51]
	v_mfma_f32_16x16x32_bf16 v[36:39], v[186:189], v[210:213], v[36:39]
	v_mfma_f32_16x16x32_bf16 v[32:35], v[194:197], v[210:213], v[32:35]
	v_mfma_f32_16x16x32_bf16 v[20:23], v[186:189], v[218:221], v[20:23]
	v_mfma_f32_16x16x32_bf16 v[16:19], v[194:197], v[218:221], v[16:19]
	v_mfma_f32_16x16x32_bf16 v[4:7], v[186:189], v[226:229], v[4:7]
	v_mfma_f32_16x16x32_bf16 v[0:3], v[194:197], v[226:229], v[0:3]
	s_barrier
	s_setprio 0
	s_add_i32 s65, s65, 2
	s_add_u32 s63, s63, 0x100
	s_addc_u32 s64, s64, 0
	s_add_u32 s12, s12, 0x100
	s_addc_u32 s13, s13, 0
	s_cmp_gt_u32 s65, 13
	s_cbranch_scc0 .LBB0_533
	s_and_b64 vcc, exec, s[22:23]
	s_cbranch_vccz .LBB0_536
	s_barrier

; #define PG8_STAGE(bufoff, gbase, voff) do { _Pragma("unroll") for (int _i = 0; _i < 2; ++_i) \
;         __builtin_amdgcn_global_load_lds((const unsigned*)((const char*)(gbase) + (voff)[_i]), (PG8_LAS unsigned*)(lds + (bufoff) + ldsw + _i * 8192), 16, 0, 0); } while (0)
; #define PG8_LDA(dst, b, h) do { _Pragma("unroll") for (int m = 0; m < 4; ++m) _Pragma("unroll") for (int k = 0; k < 2; ++k) dst[m][k] = *(const PG8_LAS bf16x8*)(lds + PG8_SA(b, h) + aoff + m * 2048 + k * 1024); } while (0)
; #define PG8_LDB(dst, b, h) do { _Pragma("unroll") for (int n = 0; n < 2; ++n) _Pragma("unroll") for (int k = 0; k < 2; ++k) dst[n][k] = *(const PG8_LAS bf16x8*)(lds + PG8_SB(b, h) + boff + n * 2048 + k * 1024); } while (0)
; #define PG8_WAIT_V(n) asm volatile("s_waitcnt vmcnt(" #n ")" ::: "memory")
; #define PG8_WAIT_L(n) asm volatile("s_waitcnt lgkmcnt(" #n ")" ::: "memory")
; #define PG8_BAR __builtin_amdgcn_s_barrier()
; #define PG8_SCHED __builtin_amdgcn_sched_barrier(0)
; template <class Epi, class Sched, bool ALIGN_EPI = false, bool SP2 = false>
; __device__ __forceinline__ void gemm_phase(PG8_LAS unsigned char* lds, const Gemm g, const Sched& S, const Epi& E, const int tid_arg) {
;     ...
;         const bool has_next = S.next(ui + 1, nxt);
;         const char* nA = has_next ? (const char*)g.A + (size_t)nxt.pm * tstep : cA; const char* nB = has_next ? (const char*)g.Bt + (size_t)nxt.pn * tstep : cB;
;         for (int t = 0; t < nt; t += 2) {
;             const bool last = (t == nt - 2);
;             const char* a1 = cA + (size_t)(t + 1) * kstep;
;             const char* a2 = last ? nA : cA + (size_t)(t + 2) * kstep; const char* b2 = last ? nB : cB + (size_t)(t + 2) * kstep;
;             const char* a3 = a2 + kstep; const char* b3 = b2 + kstep;
;             if (last && has_next) S.a_ready(nxt);
;             if constexpr (SP2) {
;             PG8_LDB(B0, 0, 0); PG8_LDB(B1, 0, 1); PG8_SCHED; PG8_LDA(At, 0, 0); PG8_STAGE(PG8_SA(1, 1), a1 + hstep, voffA);
;             PG8_WAIT_V(8); PG8_WAIT_L(0); PG8_BAR; PG8_MMA(0, 0, At, B0); PG8_MMA(0, 1, At, B1); PG8_BAR; PG8_SCHED;
;             PG8_LDA(At, 0, 1); PG8_STAGE(PG8_SB(0, 0), b2, voffB); PG8_STAGE(PG8_SB(0, 1), b2 + hstep, voffB); PG8_STAGE(PG8_SA(0, 0), a2, voffA);
;             PG8_WAIT_V(8); PG8_WAIT_L(0); PG8_BAR; PG8_MMA(1, 0, At, B0); PG8_MMA(1, 1, At, B1); PG8_BAR; PG8_SCHED;
.LBB0_685:
	ds_read_b128 v[72:75], v207
	ds_read_b128 v[100:103], v208
	ds_read_b128 v[136:139], v209
	ds_read_b128 v[140:143], v210
	ds_read_b128 v[144:147], v211
	ds_read_b128 v[148:151], v212
	ds_read_b128 v[152:155], v213
	ds_read_b128 v[156:159], v214
	s_add_u32 s10, s4, 0x100
	s_addc_u32 s11, s5, 0
	s_cmp_eq_u32 s79, 12
	s_cselect_b32 s15, s17, s11
	s_cselect_b32 s14, s37, s10
	s_cselect_b32 s1, s35, s78
	s_cselect_b32 s0, s46, s47
	s_mov_b32 m0, s72
	ds_read_b128 v[160:163], v206
	ds_read_b128 v[164:167], v206 offset:1024
	ds_read_b128 v[168:171], v206 offset:2048
	ds_read_b128 v[172:175], v206 offset:3072
	ds_read_b128 v[176:179], v206 offset:4096
	ds_read_b128 v[180:183], v206 offset:5120
	ds_read_b128 v[226:229], v206 offset:6144
	ds_read_b128 v[230:233], v206 offset:7168
	global_load_lds_dwordx4 v196, s[4:5]
	s_mov_b32 m0, s73
	s_nop 0
	global_load_lds_dwordx4 v194, s[4:5]
	s_waitcnt vmcnt(8)
	s_waitcnt lgkmcnt(0)
	s_setprio 1
	s_barrier
	v_mfma_f32_16x16x32_bf16 v[132:135], v[72:75], v[160:163], v[132:135]
	v_mfma_f32_16x16x32_bf16 v[60:63], v[136:139], v[160:163], v[60:63]
	v_mfma_f32_16x16x32_bf16 v[124:127], v[72:75], v[168:171], v[124:127]
	v_mfma_f32_16x16x32_bf16 v[52:55], v[136:139], v[168:171], v[52:55]
	v_mfma_f32_16x16x32_bf16 v[116:119], v[72:75], v[176:179], v[116:119]
	v_mfma_f32_16x16x32_bf16 v[44:47], v[136:139], v[176:179], v[44:47]
	v_mfma_f32_16x16x32_bf16 v[108:111], v[72:75], v[226:229], v[108:111]
	v_mfma_f32_16x16x32_bf16 v[36:39], v[136:139], v[226:229], v[36:39]
	v_mfma_f32_16x16x32_bf16 v[132:135], v[100:103], v[164:167], v[132:135]
	v_mfma_f32_16x16x32_bf16 v[60:63], v[140:143], v[164:167], v[60:63]
	v_mfma_f32_16x16x32_bf16 v[124:127], v[100:103], v[172:175], v[124:127]
	v_mfma_f32_16x16x32_bf16 v[52:55], v[140:143], v[172:175], v[52:55]
	v_mfma_f32_16x16x32_bf16 v[116:119], v[100:103], v[180:183], v[116:119]
	v_mfma_f32_16x16x32_bf16 v[44:47], v[140:143], v[180:183], v[44:47]
	v_mfma_f32_16x16x32_bf16 v[108:111], v[100:103], v[230:233], v[108:111]
	v_mfma_f32_16x16x32_bf16 v[36:39], v[140:143], v[230:233], v[36:39]
	s_setprio 0
	s_setprio 1
	v_mfma_f32_16x16x32_bf16 v[128:131], v[144:147], v[160:163], v[128:131]
	v_mfma_f32_16x16x32_bf16 v[56:59], v[152:155], v[160:163], v[56:59]
	v_mfma_f32_16x16x32_bf16 v[120:123], v[144:147], v[168:171], v[120:123]
	v_mfma_f32_16x16x32_bf16 v[48:51], v[152:155], v[168:171], v[48:51]
	v_mfma_f32_16x16x32_bf16 v[112:115], v[144:147], v[176:179], v[112:115]
	v_mfma_f32_16x16x32_bf16 v[40:43], v[152:155], v[176:179], v[40:43]
	v_mfma_f32_16x16x32_bf16 v[104:107], v[144:147], v[226:229], v[104:107]
	v_mfma_f32_16x16x32_bf16 v[32:35], v[152:155], v[226:229], v[32:35]
	v_mfma_f32_16x16x32_bf16 v[128:131], v[148:151], v[164:167], v[128:131]
	v_mfma_f32_16x16x32_bf16 v[56:59], v[156:159], v[164:167], v[56:59]
	v_mfma_f32_16x16x32_bf16 v[120:123], v[148:151], v[172:175], v[120:123]
	v_mfma_f32_16x16x32_bf16 v[48:51], v[156:159], v[172:175], v[48:51]
	v_mfma_f32_16x16x32_bf16 v[112:115], v[148:151], v[180:183], v[112:115]
	v_mfma_f32_16x16x32_bf16 v[40:43], v[156:159], v[180:183], v[40:43]
	v_mfma_f32_16x16x32_bf16 v[104:107], v[148:151], v[230:233], v[104:107]
	v_mfma_f32_16x16x32_bf16 v[32:35], v[156:159], v[230:233], v[32:35]
	s_barrier
	s_setprio 0
	s_mov_b32 m0, s43
	s_add_u32 s98, s0, s24
	s_addc_u32 s99, s1, s25
	s_add_u32 s4, s0, 0x40000
	ds_read_b128 v[160:163], v206 offset:16384
	ds_read_b128 v[164:167], v206 offset:17408
	ds_read_b128 v[168:171], v206 offset:18432
	ds_read_b128 v[172:175], v206 offset:19456
	ds_read_b128 v[176:179], v206 offset:20480
	ds_read_b128 v[180:183], v206 offset:21504
	ds_read_b128 v[226:229], v206 offset:22528
	ds_read_b128 v[230:233], v206 offset:23552
	global_load_lds_dwordx4 v188, s[0:1]
	s_mov_b32 m0, s45
	s_addc_u32 s5, s1, 0
	global_load_lds_dwordx4 v192, s[0:1]
	s_mov_b32 m0, s50
	s_nop 0
	global_load_lds_dwordx4 v188, s[4:5]
	s_mov_b32 m0, s51
	s_nop 0
	global_load_lds_dwordx4 v192, s[4:5]
	s_add_u32 s100, s14, s24
	s_addc_u32 s101, s15, s25
	s_mov_b32 m0, s49
	s_nop 0
	global_load_lds_dwordx4 v186, s[14:15]
	s_mov_b32 m0, s52
	s_nop 0
	global_load_lds_dwordx4 v190, s[14:15]
	s_waitcnt vmcnt(8)
	s_waitcnt lgkmcnt(0)
	s_setprio 1
	s_barrier
	v_mfma_f32_16x16x32_bf16 v[96:99], v[72:75], v[160:163], v[96:99]
	v_mfma_f32_16x16x32_bf16 v[28:31], v[136:139], v[160:163], v[28:31]
	v_mfma_f32_16x16x32_bf16 v[88:91], v[72:75], v[168:171], v[88:91]
	v_mfma_f32_16x16x32_bf16 v[20:23], v[136:139], v[168:171], v[20:23]
	v_mfma_f32_16x16x32_bf16 v[80:83], v[72:75], v[176:179], v[80:83]
	v_mfma_f32_16x16x32_bf16 v[12:15], v[136:139], v[176:179], v[12:15]
	v_mfma_f32_16x16x32_bf16 v[68:71], v[72:75], v[226:229], v[68:71]
	v_mfma_f32_16x16x32_bf16 v[4:7], v[136:139], v[226:229], v[4:7]
	v_mfma_f32_16x16x32_bf16 v[96:99], v[100:103], v[164:167], v[96:99]
	v_mfma_f32_16x16x32_bf16 v[28:31], v[140:143], v[164:167], v[28:31]
	v_mfma_f32_16x16x32_bf16 v[88:91], v[100:103], v[172:175], v[88:91]
	v_mfma_f32_16x16x32_bf16 v[20:23], v[140:143], v[172:175], v[20:23]
	v_mfma_f32_16x16x32_bf16 v[80:83], v[100:103], v[180:183], v[80:83]
	v_mfma_f32_16x16x32_bf16 v[12:15], v[140:143], v[180:183], v[12:15]
	v_mfma_f32_16x16x32_bf16 v[68:71], v[100:103], v[230:233], v[68:71]
	v_mfma_f32_16x16x32_bf16 v[4:7], v[140:143], v[230:233], v[4:7]
	s_setprio 0
	s_setprio 1
	v_mfma_f32_16x16x32_bf16 v[24:27], v[152:155], v[160:163], v[24:27]
	v_mfma_f32_16x16x32_bf16 v[84:87], v[144:147], v[168:171], v[84:87]
	v_mfma_f32_16x16x32_bf16 v[16:19], v[152:155], v[168:171], v[16:19]
	v_mfma_f32_16x16x32_bf16 v[76:79], v[144:147], v[176:179], v[76:79]
	v_mfma_f32_16x16x32_bf16 v[8:11], v[152:155], v[176:179], v[8:11]
	v_mfma_f32_16x16x32_bf16 v[64:67], v[144:147], v[226:229], v[64:67]
	v_mfma_f32_16x16x32_bf16 v[0:3], v[152:155], v[226:229], v[0:3]
	v_mfma_f32_16x16x32_bf16 v[72:75], v[144:147], v[160:163], v[92:95]
	v_mfma_f32_16x16x32_bf16 v[24:27], v[156:159], v[164:167], v[24:27]
	v_mfma_f32_16x16x32_bf16 v[84:87], v[148:151], v[172:175], v[84:87]
	v_mfma_f32_16x16x32_bf16 v[16:19], v[156:159], v[172:175], v[16:19]
	v_mfma_f32_16x16x32_bf16 v[76:79], v[148:151], v[180:183], v[76:79]
	v_mfma_f32_16x16x32_bf16 v[8:11], v[156:159], v[180:183], v[8:11]
	v_mfma_f32_16x16x32_bf16 v[64:67], v[148:151], v[230:233], v[64:67]
	v_mfma_f32_16x16x32_bf16 v[0:3], v[156:159], v[230:233], v[0:3]
	v_mfma_f32_16x16x32_bf16 v[72:75], v[148:151], v[164:167], v[72:75]
	s_barrier
; #define PG8_STAGE(bufoff, gbase, voff) do { _Pragma("unroll") for (int _i = 0; _i < 2; ++_i) \
;         __builtin_amdgcn_global_load_lds((const unsigned*)((const char*)(gbase) + (voff)[_i]), (PG8_LAS unsigned*)(lds + (bufoff) + ldsw + _i * 8192), 16, 0, 0); } while (0)
; #define PG8_LDA(dst, b, h) do { _Pragma("unroll") for (int m = 0; m < 4; ++m) _Pragma("unroll") for (int k = 0; k < 2; ++k) dst[m][k] = *(const PG8_LAS bf16x8*)(lds + PG8_SA(b, h) + aoff + m * 2048 + k * 1024); } while (0)
; #define PG8_LDB(dst, b, h) do { _Pragma("unroll") for (int n = 0; n < 2; ++n) _Pragma("unroll") for (int k = 0; k < 2; ++k) dst[n][k] = *(const PG8_LAS bf16x8*)(lds + PG8_SB(b, h) + boff + n * 2048 + k * 1024); } while (0)
; #define PG8_MMA(ai, bj, At, Bt) do { __builtin_amdgcn_s_setprio(1); _Pragma("unroll") for (int m = 0; m < 4; ++m) _Pragma("unroll") for (int n = 0; n < 2; ++n) _Pragma("unroll") for (int k = 0; k < 2; ++k) \
;         acc[ai][bj][m][n] = __builtin_amdgcn_mfma_f32_16x16x32_bf16(Bt[n][k], At[m][k], acc[ai][bj][m][n], 0, 0, 0); __builtin_amdgcn_s_setprio(0); } while (0)
; #define PG8_WAIT_V(n) asm volatile("s_waitcnt vmcnt(" #n ")" ::: "memory")
; #define PG8_WAIT_L(n) asm volatile("s_waitcnt lgkmcnt(" #n ")" ::: "memory")
; #define PG8_BAR __builtin_amdgcn_s_barrier()
; #define PG8_SCHED __builtin_amdgcn_sched_barrier(0)
; template <class Epi, class Sched, bool ALIGN_EPI = false, bool SP2 = false>
; __device__ __forceinline__ void gemm_phase(PG8_LAS unsigned char* lds, const Gemm g, const Sched& S, const Epi& E, const int tid_arg) {
;     ...
;         for (int t = 0; t < nt; t += 2) {
;             const bool last = (t == nt - 2);
;     ...
;             PG8_LDB(B0, 1, 0); PG8_LDB(B1, 1, 1); PG8_SCHED; PG8_LDA(At, 1, 0); PG8_STAGE(PG8_SA(0, 1), a2 + hstep, voffA);
;             PG8_WAIT_V(8); PG8_WAIT_L(0); PG8_BAR; PG8_MMA(0, 0, At, B0); PG8_MMA(0, 1, At, B1); PG8_BAR; PG8_SCHED;
;             PG8_LDA(At, 1, 1); PG8_STAGE(PG8_SB(1, 0), b3, voffB); PG8_STAGE(PG8_SB(1, 1), b3 + hstep, voffB); PG8_STAGE(PG8_SA(1, 0), a3, voffA);
;             PG8_WAIT_V(8); PG8_WAIT_L(0); PG8_BAR; PG8_MMA(1, 0, At, B0); PG8_MMA(1, 1, At, B1); PG8_BAR; PG8_SCHED;
;     ...
;         if constexpr (ALIGN_EPI) { if (wr == 0) PG8_BAR; }
	s_setprio 0
	ds_read_b128 v[92:95], v215
	ds_read_b128 v[100:103], v216
	ds_read_b128 v[136:139], v217
	ds_read_b128 v[140:143], v218
	ds_read_b128 v[144:147], v219
	ds_read_b128 v[148:151], v220
	ds_read_b128 v[152:155], v221
	ds_read_b128 v[156:159], v222
	s_add_u32 s4, s14, 0x40000
	s_addc_u32 s5, s15, 0
	s_mov_b32 m0, s53
	ds_read_b128 v[160:163], v206 offset:32768
	ds_read_b128 v[164:167], v206 offset:33792
	ds_read_b128 v[168:171], v206 offset:34816
	ds_read_b128 v[172:175], v206 offset:35840
	ds_read_b128 v[176:179], v206 offset:36864
	ds_read_b128 v[180:183], v206 offset:37888
	ds_read_b128 v[226:229], v206 offset:38912
	ds_read_b128 v[230:233], v206 offset:39936
	global_load_lds_dwordx4 v186, s[4:5]
	s_mov_b32 m0, s54
	s_nop 0
	global_load_lds_dwordx4 v190, s[4:5]
	s_waitcnt vmcnt(8)
	s_waitcnt lgkmcnt(0)
	s_setprio 1
	s_barrier
	v_mfma_f32_16x16x32_bf16 v[132:135], v[92:95], v[160:163], v[132:135]
	v_mfma_f32_16x16x32_bf16 v[60:63], v[136:139], v[160:163], v[60:63]
	v_mfma_f32_16x16x32_bf16 v[124:127], v[92:95], v[168:171], v[124:127]
	v_mfma_f32_16x16x32_bf16 v[52:55], v[136:139], v[168:171], v[52:55]
	v_mfma_f32_16x16x32_bf16 v[116:119], v[92:95], v[176:179], v[116:119]
	v_mfma_f32_16x16x32_bf16 v[44:47], v[136:139], v[176:179], v[44:47]
	v_mfma_f32_16x16x32_bf16 v[108:111], v[92:95], v[226:229], v[108:111]
	v_mfma_f32_16x16x32_bf16 v[36:39], v[136:139], v[226:229], v[36:39]
	v_mfma_f32_16x16x32_bf16 v[132:135], v[100:103], v[164:167], v[132:135]
	v_mfma_f32_16x16x32_bf16 v[60:63], v[140:143], v[164:167], v[60:63]
	v_mfma_f32_16x16x32_bf16 v[124:127], v[100:103], v[172:175], v[124:127]
	v_mfma_f32_16x16x32_bf16 v[52:55], v[140:143], v[172:175], v[52:55]
	v_mfma_f32_16x16x32_bf16 v[116:119], v[100:103], v[180:183], v[116:119]
	v_mfma_f32_16x16x32_bf16 v[44:47], v[140:143], v[180:183], v[44:47]
	v_mfma_f32_16x16x32_bf16 v[108:111], v[100:103], v[230:233], v[108:111]
	v_mfma_f32_16x16x32_bf16 v[36:39], v[140:143], v[230:233], v[36:39]
	s_setprio 0
	s_setprio 1
	v_mfma_f32_16x16x32_bf16 v[128:131], v[144:147], v[160:163], v[128:131]
	v_mfma_f32_16x16x32_bf16 v[56:59], v[152:155], v[160:163], v[56:59]
	v_mfma_f32_16x16x32_bf16 v[120:123], v[144:147], v[168:171], v[120:123]
	v_mfma_f32_16x16x32_bf16 v[48:51], v[152:155], v[168:171], v[48:51]
	v_mfma_f32_16x16x32_bf16 v[112:115], v[144:147], v[176:179], v[112:115]
	v_mfma_f32_16x16x32_bf16 v[40:43], v[152:155], v[176:179], v[40:43]
	v_mfma_f32_16x16x32_bf16 v[104:107], v[144:147], v[226:229], v[104:107]
	v_mfma_f32_16x16x32_bf16 v[32:35], v[152:155], v[226:229], v[32:35]
	v_mfma_f32_16x16x32_bf16 v[128:131], v[148:151], v[164:167], v[128:131]
	v_mfma_f32_16x16x32_bf16 v[56:59], v[156:159], v[164:167], v[56:59]
	v_mfma_f32_16x16x32_bf16 v[120:123], v[148:151], v[172:175], v[120:123]
	v_mfma_f32_16x16x32_bf16 v[48:51], v[156:159], v[172:175], v[48:51]
	v_mfma_f32_16x16x32_bf16 v[112:115], v[148:151], v[180:183], v[112:115]
	v_mfma_f32_16x16x32_bf16 v[40:43], v[156:159], v[180:183], v[40:43]
	v_mfma_f32_16x16x32_bf16 v[104:107], v[148:151], v[230:233], v[104:107]
	v_mfma_f32_16x16x32_bf16 v[32:35], v[156:159], v[230:233], v[32:35]
	s_barrier
	s_setprio 0
	s_mov_b32 m0, s59
	s_add_u32 s0, s0, 0x40080
	ds_read_b128 v[160:163], v206 offset:49152
	ds_read_b128 v[164:167], v206 offset:50176
	ds_read_b128 v[168:171], v206 offset:51200
	ds_read_b128 v[172:175], v206 offset:52224
	ds_read_b128 v[176:179], v206 offset:53248
	ds_read_b128 v[180:183], v206 offset:54272
	ds_read_b128 v[226:229], v206 offset:55296
	ds_read_b128 v[230:233], v206 offset:56320
	global_load_lds_dwordx4 v188, s[98:99]
	s_mov_b32 m0, s60
	s_addc_u32 s1, s1, 0
	global_load_lds_dwordx4 v192, s[98:99]
	s_mov_b32 m0, s63
	s_nop 0
	global_load_lds_dwordx4 v188, s[0:1]
	s_mov_b32 m0, s64
	s_nop 0
	global_load_lds_dwordx4 v192, s[0:1]
	s_mov_b32 m0, s61
	s_nop 0
	global_load_lds_dwordx4 v186, s[100:101]
	s_mov_b32 m0, s62
	s_nop 0
	global_load_lds_dwordx4 v190, s[100:101]
	s_waitcnt vmcnt(8)
	s_waitcnt lgkmcnt(0)
	s_setprio 1
	s_barrier
	v_mfma_f32_16x16x32_bf16 v[96:99], v[92:95], v[160:163], v[96:99]
	v_mfma_f32_16x16x32_bf16 v[28:31], v[136:139], v[160:163], v[28:31]
	v_mfma_f32_16x16x32_bf16 v[88:91], v[92:95], v[168:171], v[88:91]
	v_mfma_f32_16x16x32_bf16 v[20:23], v[136:139], v[168:171], v[20:23]
	v_mfma_f32_16x16x32_bf16 v[80:83], v[92:95], v[176:179], v[80:83]
	v_mfma_f32_16x16x32_bf16 v[12:15], v[136:139], v[176:179], v[12:15]
	v_mfma_f32_16x16x32_bf16 v[68:71], v[92:95], v[226:229], v[68:71]
	v_mfma_f32_16x16x32_bf16 v[4:7], v[136:139], v[226:229], v[4:7]
	v_mfma_f32_16x16x32_bf16 v[96:99], v[100:103], v[164:167], v[96:99]
	v_mfma_f32_16x16x32_bf16 v[28:31], v[140:143], v[164:167], v[28:31]
	v_mfma_f32_16x16x32_bf16 v[88:91], v[100:103], v[172:175], v[88:91]
	v_mfma_f32_16x16x32_bf16 v[20:23], v[140:143], v[172:175], v[20:23]
	v_mfma_f32_16x16x32_bf16 v[80:83], v[100:103], v[180:183], v[80:83]
	v_mfma_f32_16x16x32_bf16 v[12:15], v[140:143], v[180:183], v[12:15]
	v_mfma_f32_16x16x32_bf16 v[68:71], v[100:103], v[230:233], v[68:71]
	v_mfma_f32_16x16x32_bf16 v[4:7], v[140:143], v[230:233], v[4:7]
	s_setprio 0
	s_setprio 1
	v_mfma_f32_16x16x32_bf16 v[72:75], v[144:147], v[160:163], v[72:75]
	v_mfma_f32_16x16x32_bf16 v[92:95], v[148:151], v[164:167], v[72:75]
	v_mfma_f32_16x16x32_bf16 v[72:75], v[144:147], v[168:171], v[84:87]
	v_mfma_f32_16x16x32_bf16 v[24:27], v[152:155], v[160:163], v[24:27]
	v_mfma_f32_16x16x32_bf16 v[84:87], v[148:151], v[172:175], v[72:75]
	v_mfma_f32_16x16x32_bf16 v[16:19], v[152:155], v[168:171], v[16:19]
	v_mfma_f32_16x16x32_bf16 v[72:75], v[144:147], v[176:179], v[76:79]
	v_mfma_f32_16x16x32_bf16 v[8:11], v[152:155], v[176:179], v[8:11]
	v_mfma_f32_16x16x32_bf16 v[64:67], v[144:147], v[226:229], v[64:67]
	v_mfma_f32_16x16x32_bf16 v[0:3], v[152:155], v[226:229], v[0:3]
	v_mfma_f32_16x16x32_bf16 v[24:27], v[156:159], v[164:167], v[24:27]
	v_mfma_f32_16x16x32_bf16 v[16:19], v[156:159], v[172:175], v[16:19]
	v_mfma_f32_16x16x32_bf16 v[76:79], v[148:151], v[180:183], v[72:75]
	v_mfma_f32_16x16x32_bf16 v[8:11], v[156:159], v[180:183], v[8:11]
	v_mfma_f32_16x16x32_bf16 v[64:67], v[148:151], v[230:233], v[64:67]
	v_mfma_f32_16x16x32_bf16 v[0:3], v[156:159], v[230:233], v[0:3]
	s_barrier
	s_setprio 0
	s_add_i32 s79, s79, 2
	s_add_u32 s47, s47, 0x100
	s_addc_u32 s78, s78, 0
	s_cmp_gt_u32 s79, 13
	s_mov_b64 s[4:5], s[10:11]
	s_cbranch_scc0 .LBB0_685
	s_and_b64 vcc, exec, s[26:27]
	s_cbranch_vccz .LBB0_688
	s_barrier

; #define PG8_STAGE(bufoff, gbase, voff) do { _Pragma("unroll") for (int _i = 0; _i < 2; ++_i) \
;         __builtin_amdgcn_global_load_lds((const unsigned*)((const char*)(gbase) + (voff)[_i]), (PG8_LAS unsigned*)(lds + (bufoff) + ldsw + _i * 8192), 16, 0, 0); } while (0)
; #define PG8_LDA(dst, b, h) do { _Pragma("unroll") for (int m = 0; m < 4; ++m) _Pragma("unroll") for (int k = 0; k < 2; ++k) dst[m][k] = *(const PG8_LAS bf16x8*)(lds + PG8_SA(b, h) + aoff + m * 2048 + k * 1024); } while (0)
; #define PG8_LDB(dst, b, h) do { _Pragma("unroll") for (int n = 0; n < 2; ++n) _Pragma("unroll") for (int k = 0; k < 2; ++k) dst[n][k] = *(const PG8_LAS bf16x8*)(lds + PG8_SB(b, h) + boff + n * 2048 + k * 1024); } while (0)
; #define PG8_MMA(ai, bj, At, Bt) do { __builtin_amdgcn_s_setprio(1); _Pragma("unroll") for (int m = 0; m < 4; ++m) _Pragma("unroll") for (int n = 0; n < 2; ++n) _Pragma("unroll") for (int k = 0; k < 2; ++k) \
;         acc[ai][bj][m][n] = __builtin_amdgcn_mfma_f32_16x16x32_bf16(Bt[n][k], At[m][k], acc[ai][bj][m][n], 0, 0, 0); __builtin_amdgcn_s_setprio(0); } while (0)
; #define PG8_WAIT_V(n) asm volatile("s_waitcnt vmcnt(" #n ")" ::: "memory")
; #define PG8_BAR __builtin_amdgcn_s_barrier()
; template <class Epi, class Sched, bool ALIGN_EPI = false, bool SP2 = false>
; __device__ __forceinline__ void gemm_phase(PG8_LAS unsigned char* lds, const Gemm g, const Sched& S, const Epi& E, const int tid_arg) {
;     ...
;         for (int t = 0; t < nt; t += 2) {
;             const bool last = (t == nt - 2);
;             const char* a1 = cA + (size_t)(t + 1) * kstep;
;             const char* a2 = last ? nA : cA + (size_t)(t + 2) * kstep; const char* b2 = last ? nB : cB + (size_t)(t + 2) * kstep;
;             const char* a3 = a2 + kstep; const char* b3 = b2 + kstep;
;             if (last && has_next) S.a_ready(nxt);
;             if constexpr (SP2) {
;             PG8_LDB(B0, 0, 0); PG8_LDB(B1, 0, 1); PG8_SCHED; PG8_LDA(At, 0, 0); PG8_STAGE(PG8_SA(1, 1), a1 + hstep, voffA);
;             PG8_WAIT_V(8); PG8_WAIT_L(0); PG8_BAR; PG8_MMA(0, 0, At, B0); PG8_MMA(0, 1, At, B1); PG8_BAR; PG8_SCHED;
;             PG8_LDA(At, 0, 1); PG8_STAGE(PG8_SB(0, 0), b2, voffB); PG8_STAGE(PG8_SB(0, 1), b2 + hstep, voffB); PG8_STAGE(PG8_SA(0, 0), a2, voffA);
;             PG8_WAIT_V(8); PG8_WAIT_L(0); PG8_BAR; PG8_MMA(1, 0, At, B0); PG8_MMA(1, 1, At, B1); PG8_BAR; PG8_SCHED;
.LBB0_871:
	ds_read_b128 v[144:147], v151
	ds_read_b128 v[168:171], v152
	ds_read_b128 v[172:175], v153
	ds_read_b128 v[176:179], v154
	ds_read_b128 v[180:183], v155
	ds_read_b128 v[184:187], v156
	ds_read_b128 v[188:191], v157
	ds_read_b128 v[192:195], v158
	s_add_u32 s22, s4, 0x100
	s_addc_u32 s23, s5, 0
	s_cmp_eq_u32 s57, 40
	s_cselect_b32 s25, s13, s23
	s_cselect_b32 s24, s12, s22
	s_cselect_b32 s1, s21, s56
	s_cselect_b32 s0, s20, s55
	s_mov_b32 m0, s48
	ds_read_b128 v[196:199], v150
	ds_read_b128 v[200:203], v150 offset:1024
	ds_read_b128 v[204:207], v150 offset:2048
	ds_read_b128 v[208:211], v150 offset:3072
	ds_read_b128 v[212:215], v150 offset:4096
	ds_read_b128 v[216:219], v150 offset:5120
	ds_read_b128 v[220:223], v150 offset:6144
	ds_read_b128 v[224:227], v150 offset:7168
	global_load_lds_dwordx4 v138, s[4:5]
	s_mov_b32 m0, s49
	s_nop 0
	global_load_lds_dwordx4 v136, s[4:5]
	s_waitcnt vmcnt(8)
	s_waitcnt lgkmcnt(0)
	s_setprio 1
	s_barrier
	v_mfma_f32_16x16x32_bf16 v[124:127], v[144:147], v[196:199], v[124:127]
	v_mfma_f32_16x16x32_bf16 v[120:123], v[172:175], v[196:199], v[120:123]
	v_mfma_f32_16x16x32_bf16 v[108:111], v[144:147], v[204:207], v[108:111]
	v_mfma_f32_16x16x32_bf16 v[104:107], v[172:175], v[204:207], v[104:107]
	v_mfma_f32_16x16x32_bf16 v[92:95], v[144:147], v[212:215], v[92:95]
	v_mfma_f32_16x16x32_bf16 v[88:91], v[172:175], v[212:215], v[88:91]
	v_mfma_f32_16x16x32_bf16 v[76:79], v[144:147], v[220:223], v[76:79]
	v_mfma_f32_16x16x32_bf16 v[72:75], v[172:175], v[220:223], v[72:75]
	v_mfma_f32_16x16x32_bf16 v[124:127], v[168:171], v[200:203], v[124:127]
	v_mfma_f32_16x16x32_bf16 v[120:123], v[176:179], v[200:203], v[120:123]
	v_mfma_f32_16x16x32_bf16 v[108:111], v[168:171], v[208:211], v[108:111]
	v_mfma_f32_16x16x32_bf16 v[104:107], v[176:179], v[208:211], v[104:107]
	v_mfma_f32_16x16x32_bf16 v[92:95], v[168:171], v[216:219], v[92:95]
	v_mfma_f32_16x16x32_bf16 v[88:91], v[176:179], v[216:219], v[88:91]
	v_mfma_f32_16x16x32_bf16 v[76:79], v[168:171], v[224:227], v[76:79]
	v_mfma_f32_16x16x32_bf16 v[72:75], v[176:179], v[224:227], v[72:75]
	s_setprio 0
	s_setprio 1
	v_mfma_f32_16x16x32_bf16 v[116:119], v[180:183], v[196:199], v[116:119]
	v_mfma_f32_16x16x32_bf16 v[112:115], v[188:191], v[196:199], v[112:115]
	v_mfma_f32_16x16x32_bf16 v[100:103], v[180:183], v[204:207], v[100:103]
	v_mfma_f32_16x16x32_bf16 v[96:99], v[188:191], v[204:207], v[96:99]
	v_mfma_f32_16x16x32_bf16 v[84:87], v[180:183], v[212:215], v[84:87]
	v_mfma_f32_16x16x32_bf16 v[80:83], v[188:191], v[212:215], v[80:83]
	v_mfma_f32_16x16x32_bf16 v[68:71], v[180:183], v[220:223], v[68:71]
	v_mfma_f32_16x16x32_bf16 v[64:67], v[188:191], v[220:223], v[64:67]
	v_mfma_f32_16x16x32_bf16 v[116:119], v[184:187], v[200:203], v[116:119]
	v_mfma_f32_16x16x32_bf16 v[112:115], v[192:195], v[200:203], v[112:115]
	v_mfma_f32_16x16x32_bf16 v[100:103], v[184:187], v[208:211], v[100:103]
	v_mfma_f32_16x16x32_bf16 v[96:99], v[192:195], v[208:211], v[96:99]
	v_mfma_f32_16x16x32_bf16 v[84:87], v[184:187], v[216:219], v[84:87]
	v_mfma_f32_16x16x32_bf16 v[80:83], v[192:195], v[216:219], v[80:83]
	v_mfma_f32_16x16x32_bf16 v[68:71], v[184:187], v[224:227], v[68:71]
	v_mfma_f32_16x16x32_bf16 v[64:67], v[192:195], v[224:227], v[64:67]
	s_barrier
	s_setprio 0
	s_mov_b32 m0, s29
	s_add_u32 s98, s0, s16
	s_addc_u32 s99, s1, s17
	s_add_u32 s4, s0, 0xb0000
	ds_read_b128 v[196:199], v150 offset:16384
	ds_read_b128 v[200:203], v150 offset:17408
	ds_read_b128 v[204:207], v150 offset:18432
	ds_read_b128 v[208:211], v150 offset:19456
	ds_read_b128 v[212:215], v150 offset:20480
	ds_read_b128 v[216:219], v150 offset:21504
	ds_read_b128 v[220:223], v150 offset:22528
	ds_read_b128 v[224:227], v150 offset:23552
	global_load_lds_dwordx4 v130, s[0:1]
	s_mov_b32 m0, s30
	s_addc_u32 s5, s1, 0
	global_load_lds_dwordx4 v134, s[0:1]
	s_mov_b32 m0, s31
	s_nop 0
	global_load_lds_dwordx4 v130, s[4:5]
	s_mov_b32 m0, s33
	s_nop 0
	global_load_lds_dwordx4 v134, s[4:5]
	s_add_u32 s100, s24, s16
	s_addc_u32 s101, s25, s17
	s_mov_b32 m0, s28
	s_nop 0
	global_load_lds_dwordx4 v128, s[24:25]
	s_mov_b32 m0, s34
	s_nop 0
	global_load_lds_dwordx4 v132, s[24:25]
	s_waitcnt vmcnt(8)
	s_waitcnt lgkmcnt(0)
	s_setprio 1
	s_barrier
	v_mfma_f32_16x16x32_bf16 v[60:63], v[144:147], v[196:199], v[60:63]
	v_mfma_f32_16x16x32_bf16 v[56:59], v[172:175], v[196:199], v[56:59]
	v_mfma_f32_16x16x32_bf16 v[44:47], v[144:147], v[204:207], v[44:47]
	v_mfma_f32_16x16x32_bf16 v[40:43], v[172:175], v[204:207], v[40:43]
	v_mfma_f32_16x16x32_bf16 v[28:31], v[144:147], v[212:215], v[28:31]
	v_mfma_f32_16x16x32_bf16 v[24:27], v[172:175], v[212:215], v[24:27]
	v_mfma_f32_16x16x32_bf16 v[12:15], v[144:147], v[220:223], v[12:15]
	v_mfma_f32_16x16x32_bf16 v[8:11], v[172:175], v[220:223], v[8:11]
	v_mfma_f32_16x16x32_bf16 v[60:63], v[168:171], v[200:203], v[60:63]
	v_mfma_f32_16x16x32_bf16 v[56:59], v[176:179], v[200:203], v[56:59]
	v_mfma_f32_16x16x32_bf16 v[44:47], v[168:171], v[208:211], v[44:47]
	v_mfma_f32_16x16x32_bf16 v[40:43], v[176:179], v[208:211], v[40:43]
	v_mfma_f32_16x16x32_bf16 v[28:31], v[168:171], v[216:219], v[28:31]
	v_mfma_f32_16x16x32_bf16 v[24:27], v[176:179], v[216:219], v[24:27]
	v_mfma_f32_16x16x32_bf16 v[12:15], v[168:171], v[224:227], v[12:15]
	v_mfma_f32_16x16x32_bf16 v[8:11], v[176:179], v[224:227], v[8:11]
	s_setprio 0
	s_setprio 1
	v_mfma_f32_16x16x32_bf16 v[52:55], v[180:183], v[196:199], v[52:55]
	v_mfma_f32_16x16x32_bf16 v[48:51], v[188:191], v[196:199], v[48:51]
	v_mfma_f32_16x16x32_bf16 v[36:39], v[180:183], v[204:207], v[36:39]
	v_mfma_f32_16x16x32_bf16 v[32:35], v[188:191], v[204:207], v[32:35]
	v_mfma_f32_16x16x32_bf16 v[20:23], v[180:183], v[212:215], v[20:23]
	v_mfma_f32_16x16x32_bf16 v[16:19], v[188:191], v[212:215], v[16:19]
	v_mfma_f32_16x16x32_bf16 v[4:7], v[180:183], v[220:223], v[4:7]
	v_mfma_f32_16x16x32_bf16 v[0:3], v[188:191], v[220:223], v[0:3]
	v_mfma_f32_16x16x32_bf16 v[52:55], v[184:187], v[200:203], v[52:55]
	v_mfma_f32_16x16x32_bf16 v[48:51], v[192:195], v[200:203], v[48:51]
	v_mfma_f32_16x16x32_bf16 v[36:39], v[184:187], v[208:211], v[36:39]
	v_mfma_f32_16x16x32_bf16 v[32:35], v[192:195], v[208:211], v[32:35]
	v_mfma_f32_16x16x32_bf16 v[20:23], v[184:187], v[216:219], v[20:23]
	v_mfma_f32_16x16x32_bf16 v[16:19], v[192:195], v[216:219], v[16:19]
	v_mfma_f32_16x16x32_bf16 v[4:7], v[184:187], v[224:227], v[4:7]
	v_mfma_f32_16x16x32_bf16 v[0:3], v[192:195], v[224:227], v[0:3]
	s_barrier
; #define PG8_STAGE(bufoff, gbase, voff) do { _Pragma("unroll") for (int _i = 0; _i < 2; ++_i) \
;         __builtin_amdgcn_global_load_lds((const unsigned*)((const char*)(gbase) + (voff)[_i]), (PG8_LAS unsigned*)(lds + (bufoff) + ldsw + _i * 8192), 16, 0, 0); } while (0)
; #define PG8_LDA(dst, b, h) do { _Pragma("unroll") for (int m = 0; m < 4; ++m) _Pragma("unroll") for (int k = 0; k < 2; ++k) dst[m][k] = *(const PG8_LAS bf16x8*)(lds + PG8_SA(b, h) + aoff + m * 2048 + k * 1024); } while (0)
; #define PG8_LDB(dst, b, h) do { _Pragma("unroll") for (int n = 0; n < 2; ++n) _Pragma("unroll") for (int k = 0; k < 2; ++k) dst[n][k] = *(const PG8_LAS bf16x8*)(lds + PG8_SB(b, h) + boff + n * 2048 + k * 1024); } while (0)
; #define PG8_MMA(ai, bj, At, Bt) do { __builtin_amdgcn_s_setprio(1); _Pragma("unroll") for (int m = 0; m < 4; ++m) _Pragma("unroll") for (int n = 0; n < 2; ++n) _Pragma("unroll") for (int k = 0; k < 2; ++k) \
;         acc[ai][bj][m][n] = __builtin_amdgcn_mfma_f32_16x16x32_bf16(Bt[n][k], At[m][k], acc[ai][bj][m][n], 0, 0, 0); __builtin_amdgcn_s_setprio(0); } while (0)
; #define PG8_WAIT_V(n) asm volatile("s_waitcnt vmcnt(" #n ")" ::: "memory")
; #define PG8_WAIT_L(n) asm volatile("s_waitcnt lgkmcnt(" #n ")" ::: "memory")
; #define PG8_BAR __builtin_amdgcn_s_barrier()
; #define PG8_SCHED __builtin_amdgcn_sched_barrier(0)
; template <class Epi, class Sched, bool ALIGN_EPI = false, bool SP2 = false>
; __device__ __forceinline__ void gemm_phase(PG8_LAS unsigned char* lds, const Gemm g, const Sched& S, const Epi& E, const int tid_arg) {
;     ...
;             PG8_LDB(B0, 1, 0); PG8_LDB(B1, 1, 1); PG8_SCHED; PG8_LDA(At, 1, 0); PG8_STAGE(PG8_SA(0, 1), a2 + hstep, voffA);
;             PG8_WAIT_V(8); PG8_WAIT_L(0); PG8_BAR; PG8_MMA(0, 0, At, B0); PG8_MMA(0, 1, At, B1); PG8_BAR; PG8_SCHED;
;             PG8_LDA(At, 1, 1); PG8_STAGE(PG8_SB(1, 0), b3, voffB); PG8_STAGE(PG8_SB(1, 1), b3 + hstep, voffB); PG8_STAGE(PG8_SA(1, 0), a3, voffA);
;             PG8_WAIT_V(8); PG8_WAIT_L(0); PG8_BAR; PG8_MMA(1, 0, At, B0); PG8_MMA(1, 1, At, B1); PG8_BAR; PG8_SCHED;
	s_setprio 0
	ds_read_b128 v[144:147], v159
	ds_read_b128 v[168:171], v160
	ds_read_b128 v[172:175], v161
	ds_read_b128 v[176:179], v162
	ds_read_b128 v[180:183], v163
	ds_read_b128 v[184:187], v164
	ds_read_b128 v[188:191], v165
	ds_read_b128 v[192:195], v166
	s_add_u32 s4, s24, 0xb0000
	s_addc_u32 s5, s25, 0
	s_mov_b32 m0, s35
	ds_read_b128 v[196:199], v150 offset:32768
	ds_read_b128 v[200:203], v150 offset:33792
	ds_read_b128 v[204:207], v150 offset:34816
	ds_read_b128 v[208:211], v150 offset:35840
	ds_read_b128 v[212:215], v150 offset:36864
	ds_read_b128 v[216:219], v150 offset:37888
	ds_read_b128 v[220:223], v150 offset:38912
	ds_read_b128 v[224:227], v150 offset:39936
	global_load_lds_dwordx4 v128, s[4:5]
	s_mov_b32 m0, s36
	s_nop 0
	global_load_lds_dwordx4 v132, s[4:5]
	s_waitcnt vmcnt(8)
	s_waitcnt lgkmcnt(0)
	s_setprio 1
	s_barrier
	v_mfma_f32_16x16x32_bf16 v[124:127], v[144:147], v[196:199], v[124:127]
	v_mfma_f32_16x16x32_bf16 v[120:123], v[172:175], v[196:199], v[120:123]
	v_mfma_f32_16x16x32_bf16 v[108:111], v[144:147], v[204:207], v[108:111]
	v_mfma_f32_16x16x32_bf16 v[104:107], v[172:175], v[204:207], v[104:107]
	v_mfma_f32_16x16x32_bf16 v[92:95], v[144:147], v[212:215], v[92:95]
	v_mfma_f32_16x16x32_bf16 v[88:91], v[172:175], v[212:215], v[88:91]
	v_mfma_f32_16x16x32_bf16 v[76:79], v[144:147], v[220:223], v[76:79]
	v_mfma_f32_16x16x32_bf16 v[72:75], v[172:175], v[220:223], v[72:75]
	v_mfma_f32_16x16x32_bf16 v[124:127], v[168:171], v[200:203], v[124:127]
	v_mfma_f32_16x16x32_bf16 v[120:123], v[176:179], v[200:203], v[120:123]
	v_mfma_f32_16x16x32_bf16 v[108:111], v[168:171], v[208:211], v[108:111]
	v_mfma_f32_16x16x32_bf16 v[104:107], v[176:179], v[208:211], v[104:107]
	v_mfma_f32_16x16x32_bf16 v[92:95], v[168:171], v[216:219], v[92:95]
	v_mfma_f32_16x16x32_bf16 v[88:91], v[176:179], v[216:219], v[88:91]
	v_mfma_f32_16x16x32_bf16 v[76:79], v[168:171], v[224:227], v[76:79]
	v_mfma_f32_16x16x32_bf16 v[72:75], v[176:179], v[224:227], v[72:75]
	s_setprio 0
	s_setprio 1
	v_mfma_f32_16x16x32_bf16 v[116:119], v[180:183], v[196:199], v[116:119]
	v_mfma_f32_16x16x32_bf16 v[112:115], v[188:191], v[196:199], v[112:115]
	v_mfma_f32_16x16x32_bf16 v[100:103], v[180:183], v[204:207], v[100:103]
	v_mfma_f32_16x16x32_bf16 v[96:99], v[188:191], v[204:207], v[96:99]
	v_mfma_f32_16x16x32_bf16 v[84:87], v[180:183], v[212:215], v[84:87]
	v_mfma_f32_16x16x32_bf16 v[80:83], v[188:191], v[212:215], v[80:83]
	v_mfma_f32_16x16x32_bf16 v[68:71], v[180:183], v[220:223], v[68:71]
	v_mfma_f32_16x16x32_bf16 v[64:67], v[188:191], v[220:223], v[64:67]
	v_mfma_f32_16x16x32_bf16 v[116:119], v[184:187], v[200:203], v[116:119]
	v_mfma_f32_16x16x32_bf16 v[112:115], v[192:195], v[200:203], v[112:115]
	v_mfma_f32_16x16x32_bf16 v[100:103], v[184:187], v[208:211], v[100:103]
	v_mfma_f32_16x16x32_bf16 v[96:99], v[192:195], v[208:211], v[96:99]
	v_mfma_f32_16x16x32_bf16 v[84:87], v[184:187], v[216:219], v[84:87]
	v_mfma_f32_16x16x32_bf16 v[80:83], v[192:195], v[216:219], v[80:83]
	v_mfma_f32_16x16x32_bf16 v[68:71], v[184:187], v[224:227], v[68:71]
	v_mfma_f32_16x16x32_bf16 v[64:67], v[192:195], v[224:227], v[64:67]
	s_barrier
	s_setprio 0
	s_mov_b32 m0, s40
	s_add_u32 s0, s0, 0xb0080
	ds_read_b128 v[196:199], v150 offset:49152
	ds_read_b128 v[200:203], v150 offset:50176
	ds_read_b128 v[204:207], v150 offset:51200
	ds_read_b128 v[208:211], v150 offset:52224
	ds_read_b128 v[212:215], v150 offset:53248
	ds_read_b128 v[216:219], v150 offset:54272
	ds_read_b128 v[220:223], v150 offset:55296
	ds_read_b128 v[224:227], v150 offset:56320
	global_load_lds_dwordx4 v130, s[98:99]
	s_mov_b32 m0, s41
	s_addc_u32 s1, s1, 0
	global_load_lds_dwordx4 v134, s[98:99]
	s_mov_b32 m0, s44
	s_nop 0
	global_load_lds_dwordx4 v130, s[0:1]
	s_mov_b32 m0, s45
	s_nop 0
	global_load_lds_dwordx4 v134, s[0:1]
	s_mov_b32 m0, s42
	s_nop 0
	global_load_lds_dwordx4 v128, s[100:101]
	s_mov_b32 m0, s43
	s_nop 0
	global_load_lds_dwordx4 v132, s[100:101]
	s_waitcnt vmcnt(8)
	s_waitcnt lgkmcnt(0)
	s_setprio 1
	s_barrier
	v_mfma_f32_16x16x32_bf16 v[60:63], v[144:147], v[196:199], v[60:63]
	v_mfma_f32_16x16x32_bf16 v[56:59], v[172:175], v[196:199], v[56:59]
	v_mfma_f32_16x16x32_bf16 v[44:47], v[144:147], v[204:207], v[44:47]
	v_mfma_f32_16x16x32_bf16 v[40:43], v[172:175], v[204:207], v[40:43]
	v_mfma_f32_16x16x32_bf16 v[28:31], v[144:147], v[212:215], v[28:31]
	v_mfma_f32_16x16x32_bf16 v[24:27], v[172:175], v[212:215], v[24:27]
	v_mfma_f32_16x16x32_bf16 v[12:15], v[144:147], v[220:223], v[12:15]
	v_mfma_f32_16x16x32_bf16 v[8:11], v[172:175], v[220:223], v[8:11]
	v_mfma_f32_16x16x32_bf16 v[60:63], v[168:171], v[200:203], v[60:63]
	v_mfma_f32_16x16x32_bf16 v[56:59], v[176:179], v[200:203], v[56:59]
	v_mfma_f32_16x16x32_bf16 v[44:47], v[168:171], v[208:211], v[44:47]
	v_mfma_f32_16x16x32_bf16 v[40:43], v[176:179], v[208:211], v[40:43]
	v_mfma_f32_16x16x32_bf16 v[28:31], v[168:171], v[216:219], v[28:31]
	v_mfma_f32_16x16x32_bf16 v[24:27], v[176:179], v[216:219], v[24:27]
	v_mfma_f32_16x16x32_bf16 v[12:15], v[168:171], v[224:227], v[12:15]
	v_mfma_f32_16x16x32_bf16 v[8:11], v[176:179], v[224:227], v[8:11]
	s_setprio 0
	s_setprio 1
	v_mfma_f32_16x16x32_bf16 v[52:55], v[180:183], v[196:199], v[52:55]
	v_mfma_f32_16x16x32_bf16 v[48:51], v[188:191], v[196:199], v[48:51]
	v_mfma_f32_16x16x32_bf16 v[36:39], v[180:183], v[204:207], v[36:39]
	v_mfma_f32_16x16x32_bf16 v[32:35], v[188:191], v[204:207], v[32:35]
	v_mfma_f32_16x16x32_bf16 v[20:23], v[180:183], v[212:215], v[20:23]
	v_mfma_f32_16x16x32_bf16 v[16:19], v[188:191], v[212:215], v[16:19]
	v_mfma_f32_16x16x32_bf16 v[4:7], v[180:183], v[220:223], v[4:7]
	v_mfma_f32_16x16x32_bf16 v[0:3], v[188:191], v[220:223], v[0:3]
	v_mfma_f32_16x16x32_bf16 v[52:55], v[184:187], v[200:203], v[52:55]
	v_mfma_f32_16x16x32_bf16 v[48:51], v[192:195], v[200:203], v[48:51]
	v_mfma_f32_16x16x32_bf16 v[36:39], v[184:187], v[208:211], v[36:39]
	v_mfma_f32_16x16x32_bf16 v[32:35], v[192:195], v[208:211], v[32:35]
	v_mfma_f32_16x16x32_bf16 v[20:23], v[184:187], v[216:219], v[20:23]
	v_mfma_f32_16x16x32_bf16 v[16:19], v[192:195], v[216:219], v[16:19]
	v_mfma_f32_16x16x32_bf16 v[4:7], v[184:187], v[224:227], v[4:7]
	v_mfma_f32_16x16x32_bf16 v[0:3], v[192:195], v[224:227], v[0:3]
	s_barrier
	s_setprio 0
	s_add_i32 s57, s57, 2
	s_add_u32 s55, s55, 0x100
	s_addc_u32 s56, s56, 0
	s_cmp_gt_u32 s57, 41
	s_mov_b64 s[4:5], s[22:23]
	s_cbranch_scc0 .LBB0_871
	s_and_b64 vcc, exec, s[18:19]
	s_cbranch_vccz .LBB0_874
	s_barrier

; #define PG8_STAGE(bufoff, gbase, voff) do { _Pragma("unroll") for (int _i = 0; _i < 2; ++_i) \
;         __builtin_amdgcn_global_load_lds((const unsigned*)((const char*)(gbase) + (voff)[_i]), (PG8_LAS unsigned*)(lds + (bufoff) + ldsw + _i * 8192), 16, 0, 0); } while (0)
; #define PG8_LDA(dst, b, h) do { _Pragma("unroll") for (int m = 0; m < 4; ++m) _Pragma("unroll") for (int k = 0; k < 2; ++k) dst[m][k] = *(const PG8_LAS bf16x8*)(lds + PG8_SA(b, h) + aoff + m * 2048 + k * 1024); } while (0)
; #define PG8_LDB(dst, b, h) do { _Pragma("unroll") for (int n = 0; n < 2; ++n) _Pragma("unroll") for (int k = 0; k < 2; ++k) dst[n][k] = *(const PG8_LAS bf16x8*)(lds + PG8_SB(b, h) + boff + n * 2048 + k * 1024); } while (0)
; #define PG8_MMA(ai, bj, At, Bt) do { __builtin_amdgcn_s_setprio(1); _Pragma("unroll") for (int m = 0; m < 4; ++m) _Pragma("unroll") for (int n = 0; n < 2; ++n) _Pragma("unroll") for (int k = 0; k < 2; ++k) \
;         acc[ai][bj][m][n] = __builtin_amdgcn_mfma_f32_16x16x32_bf16(Bt[n][k], At[m][k], acc[ai][bj][m][n], 0, 0, 0); __builtin_amdgcn_s_setprio(0); } while (0)
; #define PG8_WAIT_V(n) asm volatile("s_waitcnt vmcnt(" #n ")" ::: "memory")
; #define PG8_BAR __builtin_amdgcn_s_barrier()
; template <class Epi, class Sched, bool ALIGN_EPI = false, bool SP2 = false>
; __device__ __forceinline__ void gemm_phase(PG8_LAS unsigned char* lds, const Gemm g, const Sched& S, const Epi& E, const int tid_arg) {
;     ...
;         for (int t = 0; t < nt; t += 2) {
;             const bool last = (t == nt - 2);
;             const char* a1 = cA + (size_t)(t + 1) * kstep;
;             const char* a2 = last ? nA : cA + (size_t)(t + 2) * kstep; const char* b2 = last ? nB : cB + (size_t)(t + 2) * kstep;
;             const char* a3 = a2 + kstep; const char* b3 = b2 + kstep;
;             if (last && has_next) S.a_ready(nxt);
;             if constexpr (SP2) {
;             PG8_LDB(B0, 0, 0); PG8_LDB(B1, 0, 1); PG8_SCHED; PG8_LDA(At, 0, 0); PG8_STAGE(PG8_SA(1, 1), a1 + hstep, voffA);
;             PG8_WAIT_V(8); PG8_WAIT_L(0); PG8_BAR; PG8_MMA(0, 0, At, B0); PG8_MMA(0, 1, At, B1); PG8_BAR; PG8_SCHED;
;             PG8_LDA(At, 0, 1); PG8_STAGE(PG8_SB(0, 0), b2, voffB); PG8_STAGE(PG8_SB(0, 1), b2 + hstep, voffB); PG8_STAGE(PG8_SA(0, 0), a2, voffA);
;             PG8_WAIT_V(8); PG8_WAIT_L(0); PG8_BAR; PG8_MMA(1, 0, At, B0); PG8_MMA(1, 1, At, B1); PG8_BAR; PG8_SCHED;
.LBB0_965:
	ds_read_b128 v[170:173], v151
	ds_read_b128 v[174:177], v153
	ds_read_b128 v[178:181], v155
	ds_read_b128 v[182:185], v156
	ds_read_b128 v[186:189], v157
	ds_read_b128 v[190:193], v158
	ds_read_b128 v[194:197], v159
	ds_read_b128 v[198:201], v160
	s_add_u32 s0, s40, 0xfffc0080
	s_addc_u32 s1, s41, -1
	s_cmp_eq_u32 s72, 12
	s_cselect_b32 s43, s35, s1
	s_cselect_b32 s42, s68, s0
	s_cselect_b32 s1, s31, s71
	s_cselect_b32 s0, s69, s70
	s_mov_b32 m0, s60
	ds_read_b128 v[202:205], v149
	ds_read_b128 v[206:209], v149 offset:1024
	ds_read_b128 v[210:213], v149 offset:2048
	ds_read_b128 v[214:217], v149 offset:3072
	ds_read_b128 v[218:221], v149 offset:4096
	ds_read_b128 v[222:225], v149 offset:5120
	ds_read_b128 v[226:229], v149 offset:6144
	ds_read_b128 v[230:233], v149 offset:7168
	global_load_lds_dwordx4 v138, s[40:41]
	s_mov_b32 m0, s61
	s_nop 0
	global_load_lds_dwordx4 v136, s[40:41]
	s_waitcnt vmcnt(8)
	s_waitcnt lgkmcnt(0)
	s_setprio 1
	s_barrier
	v_mfma_f32_16x16x32_bf16 v[124:127], v[170:173], v[202:205], v[124:127]
	v_mfma_f32_16x16x32_bf16 v[120:123], v[178:181], v[202:205], v[120:123]
	v_mfma_f32_16x16x32_bf16 v[108:111], v[170:173], v[210:213], v[108:111]
	v_mfma_f32_16x16x32_bf16 v[104:107], v[178:181], v[210:213], v[104:107]
	v_mfma_f32_16x16x32_bf16 v[92:95], v[170:173], v[218:221], v[92:95]
	v_mfma_f32_16x16x32_bf16 v[88:91], v[178:181], v[218:221], v[88:91]
	v_mfma_f32_16x16x32_bf16 v[76:79], v[170:173], v[226:229], v[76:79]
	v_mfma_f32_16x16x32_bf16 v[72:75], v[178:181], v[226:229], v[72:75]
	v_mfma_f32_16x16x32_bf16 v[124:127], v[174:177], v[206:209], v[124:127]
	v_mfma_f32_16x16x32_bf16 v[120:123], v[182:185], v[206:209], v[120:123]
	v_mfma_f32_16x16x32_bf16 v[108:111], v[174:177], v[214:217], v[108:111]
	v_mfma_f32_16x16x32_bf16 v[104:107], v[182:185], v[214:217], v[104:107]
	v_mfma_f32_16x16x32_bf16 v[92:95], v[174:177], v[222:225], v[92:95]
	v_mfma_f32_16x16x32_bf16 v[88:91], v[182:185], v[222:225], v[88:91]
	v_mfma_f32_16x16x32_bf16 v[76:79], v[174:177], v[230:233], v[76:79]
	v_mfma_f32_16x16x32_bf16 v[72:75], v[182:185], v[230:233], v[72:75]
	s_setprio 0
	s_setprio 1
	v_mfma_f32_16x16x32_bf16 v[116:119], v[186:189], v[202:205], v[116:119]
	v_mfma_f32_16x16x32_bf16 v[112:115], v[194:197], v[202:205], v[112:115]
	v_mfma_f32_16x16x32_bf16 v[100:103], v[186:189], v[210:213], v[100:103]
	v_mfma_f32_16x16x32_bf16 v[96:99], v[194:197], v[210:213], v[96:99]
	v_mfma_f32_16x16x32_bf16 v[84:87], v[186:189], v[218:221], v[84:87]
	v_mfma_f32_16x16x32_bf16 v[80:83], v[194:197], v[218:221], v[80:83]
	v_mfma_f32_16x16x32_bf16 v[68:71], v[186:189], v[226:229], v[68:71]
	v_mfma_f32_16x16x32_bf16 v[64:67], v[194:197], v[226:229], v[64:67]
	v_mfma_f32_16x16x32_bf16 v[116:119], v[190:193], v[206:209], v[116:119]
	v_mfma_f32_16x16x32_bf16 v[112:115], v[198:201], v[206:209], v[112:115]
	v_mfma_f32_16x16x32_bf16 v[100:103], v[190:193], v[214:217], v[100:103]
	v_mfma_f32_16x16x32_bf16 v[96:99], v[198:201], v[214:217], v[96:99]
	v_mfma_f32_16x16x32_bf16 v[84:87], v[190:193], v[222:225], v[84:87]
	v_mfma_f32_16x16x32_bf16 v[80:83], v[198:201], v[222:225], v[80:83]
	v_mfma_f32_16x16x32_bf16 v[68:71], v[190:193], v[230:233], v[68:71]
	v_mfma_f32_16x16x32_bf16 v[64:67], v[198:201], v[230:233], v[64:67]
	s_barrier
	s_setprio 0
	s_mov_b32 m0, s5
	s_add_u32 s98, s0, s12
	s_addc_u32 s99, s1, s13
	s_add_u32 s74, s0, 0x40000
	ds_read_b128 v[202:205], v149 offset:16384
	ds_read_b128 v[206:209], v149 offset:17408
	ds_read_b128 v[210:213], v149 offset:18432
	ds_read_b128 v[214:217], v149 offset:19456
	ds_read_b128 v[218:221], v149 offset:20480
	ds_read_b128 v[222:225], v149 offset:21504
	ds_read_b128 v[226:229], v149 offset:22528
	ds_read_b128 v[230:233], v149 offset:23552
	global_load_lds_dwordx4 v130, s[0:1]
	s_mov_b32 m0, s47
	s_addc_u32 s75, s1, 0
	global_load_lds_dwordx4 v134, s[0:1]
	s_mov_b32 m0, s48
	s_nop 0
	global_load_lds_dwordx4 v130, s[74:75]
	s_mov_b32 m0, s49
	s_nop 0
	global_load_lds_dwordx4 v134, s[74:75]
	s_add_u32 s100, s42, s12
	s_addc_u32 s101, s43, s13
	s_mov_b32 m0, s46
	s_nop 0
	global_load_lds_dwordx4 v128, s[42:43]
	s_mov_b32 m0, s50
	s_nop 0
	global_load_lds_dwordx4 v132, s[42:43]
	s_waitcnt vmcnt(8)
	s_waitcnt lgkmcnt(0)
	s_setprio 1
	s_barrier
	v_mfma_f32_16x16x32_bf16 v[60:63], v[170:173], v[202:205], v[60:63]
	v_mfma_f32_16x16x32_bf16 v[56:59], v[178:181], v[202:205], v[56:59]
	v_mfma_f32_16x16x32_bf16 v[44:47], v[170:173], v[210:213], v[44:47]
	v_mfma_f32_16x16x32_bf16 v[40:43], v[178:181], v[210:213], v[40:43]
	v_mfma_f32_16x16x32_bf16 v[28:31], v[170:173], v[218:221], v[28:31]
	v_mfma_f32_16x16x32_bf16 v[24:27], v[178:181], v[218:221], v[24:27]
	v_mfma_f32_16x16x32_bf16 v[12:15], v[170:173], v[226:229], v[12:15]
	v_mfma_f32_16x16x32_bf16 v[8:11], v[178:181], v[226:229], v[8:11]
	v_mfma_f32_16x16x32_bf16 v[60:63], v[174:177], v[206:209], v[60:63]
	v_mfma_f32_16x16x32_bf16 v[56:59], v[182:185], v[206:209], v[56:59]
	v_mfma_f32_16x16x32_bf16 v[44:47], v[174:177], v[214:217], v[44:47]
	v_mfma_f32_16x16x32_bf16 v[40:43], v[182:185], v[214:217], v[40:43]
	v_mfma_f32_16x16x32_bf16 v[28:31], v[174:177], v[222:225], v[28:31]
	v_mfma_f32_16x16x32_bf16 v[24:27], v[182:185], v[222:225], v[24:27]
	v_mfma_f32_16x16x32_bf16 v[12:15], v[174:177], v[230:233], v[12:15]
	v_mfma_f32_16x16x32_bf16 v[8:11], v[182:185], v[230:233], v[8:11]
	s_setprio 0
	s_setprio 1
	v_mfma_f32_16x16x32_bf16 v[52:55], v[186:189], v[202:205], v[52:55]
	v_mfma_f32_16x16x32_bf16 v[48:51], v[194:197], v[202:205], v[48:51]
	v_mfma_f32_16x16x32_bf16 v[36:39], v[186:189], v[210:213], v[36:39]
	v_mfma_f32_16x16x32_bf16 v[32:35], v[194:197], v[210:213], v[32:35]
	v_mfma_f32_16x16x32_bf16 v[20:23], v[186:189], v[218:221], v[20:23]
	v_mfma_f32_16x16x32_bf16 v[16:19], v[194:197], v[218:221], v[16:19]
	v_mfma_f32_16x16x32_bf16 v[4:7], v[186:189], v[226:229], v[4:7]
	v_mfma_f32_16x16x32_bf16 v[0:3], v[194:197], v[226:229], v[0:3]
	v_mfma_f32_16x16x32_bf16 v[52:55], v[190:193], v[206:209], v[52:55]
	v_mfma_f32_16x16x32_bf16 v[48:51], v[198:201], v[206:209], v[48:51]
	v_mfma_f32_16x16x32_bf16 v[36:39], v[190:193], v[214:217], v[36:39]
	v_mfma_f32_16x16x32_bf16 v[32:35], v[198:201], v[214:217], v[32:35]
	v_mfma_f32_16x16x32_bf16 v[20:23], v[190:193], v[222:225], v[20:23]
	v_mfma_f32_16x16x32_bf16 v[16:19], v[198:201], v[222:225], v[16:19]
	v_mfma_f32_16x16x32_bf16 v[4:7], v[190:193], v[230:233], v[4:7]
	v_mfma_f32_16x16x32_bf16 v[0:3], v[198:201], v[230:233], v[0:3]
	s_barrier
; #define PG8_STAGE(bufoff, gbase, voff) do { _Pragma("unroll") for (int _i = 0; _i < 2; ++_i) \
;         __builtin_amdgcn_global_load_lds((const unsigned*)((const char*)(gbase) + (voff)[_i]), (PG8_LAS unsigned*)(lds + (bufoff) + ldsw + _i * 8192), 16, 0, 0); } while (0)
; #define PG8_LDA(dst, b, h) do { _Pragma("unroll") for (int m = 0; m < 4; ++m) _Pragma("unroll") for (int k = 0; k < 2; ++k) dst[m][k] = *(const PG8_LAS bf16x8*)(lds + PG8_SA(b, h) + aoff + m * 2048 + k * 1024); } while (0)
; #define PG8_LDB(dst, b, h) do { _Pragma("unroll") for (int n = 0; n < 2; ++n) _Pragma("unroll") for (int k = 0; k < 2; ++k) dst[n][k] = *(const PG8_LAS bf16x8*)(lds + PG8_SB(b, h) + boff + n * 2048 + k * 1024); } while (0)
; #define PG8_MMA(ai, bj, At, Bt) do { __builtin_amdgcn_s_setprio(1); _Pragma("unroll") for (int m = 0; m < 4; ++m) _Pragma("unroll") for (int n = 0; n < 2; ++n) _Pragma("unroll") for (int k = 0; k < 2; ++k) \
;         acc[ai][bj][m][n] = __builtin_amdgcn_mfma_f32_16x16x32_bf16(Bt[n][k], At[m][k], acc[ai][bj][m][n], 0, 0, 0); __builtin_amdgcn_s_setprio(0); } while (0)
; #define PG8_WAIT_V(n) asm volatile("s_waitcnt vmcnt(" #n ")" ::: "memory")
; #define PG8_WAIT_L(n) asm volatile("s_waitcnt lgkmcnt(" #n ")" ::: "memory")
; #define PG8_BAR __builtin_amdgcn_s_barrier()
; #define PG8_SCHED __builtin_amdgcn_sched_barrier(0)
; template <class Epi, class Sched, bool ALIGN_EPI = false, bool SP2 = false>
; __device__ __forceinline__ void gemm_phase(PG8_LAS unsigned char* lds, const Gemm g, const Sched& S, const Epi& E, const int tid_arg) {
;     ...
;             PG8_LDB(B0, 1, 0); PG8_LDB(B1, 1, 1); PG8_SCHED; PG8_LDA(At, 1, 0); PG8_STAGE(PG8_SA(0, 1), a2 + hstep, voffA);
;             PG8_WAIT_V(8); PG8_WAIT_L(0); PG8_BAR; PG8_MMA(0, 0, At, B0); PG8_MMA(0, 1, At, B1); PG8_BAR; PG8_SCHED;
;             PG8_LDA(At, 1, 1); PG8_STAGE(PG8_SB(1, 0), b3, voffB); PG8_STAGE(PG8_SB(1, 1), b3 + hstep, voffB); PG8_STAGE(PG8_SA(1, 0), a3, voffA);
;             PG8_WAIT_V(8); PG8_WAIT_L(0); PG8_BAR; PG8_MMA(1, 0, At, B0); PG8_MMA(1, 1, At, B1); PG8_BAR; PG8_SCHED;
	s_setprio 0
	ds_read_b128 v[170:173], v161
	ds_read_b128 v[174:177], v162
	ds_read_b128 v[178:181], v163
	ds_read_b128 v[182:185], v164
	ds_read_b128 v[186:189], v165
	ds_read_b128 v[190:193], v166
	ds_read_b128 v[194:197], v167
	ds_read_b128 v[198:201], v168
	s_add_u32 s42, s42, 0x40000
	s_addc_u32 s43, s43, 0
	s_mov_b32 m0, s51
	ds_read_b128 v[202:205], v149 offset:32768
	ds_read_b128 v[206:209], v149 offset:33792
	ds_read_b128 v[210:213], v149 offset:34816
	ds_read_b128 v[214:217], v149 offset:35840
	ds_read_b128 v[218:221], v149 offset:36864
	ds_read_b128 v[222:225], v149 offset:37888
	ds_read_b128 v[226:229], v149 offset:38912
	ds_read_b128 v[230:233], v149 offset:39936
	global_load_lds_dwordx4 v128, s[42:43]
	s_mov_b32 m0, s52
	s_nop 0
	global_load_lds_dwordx4 v132, s[42:43]
	s_waitcnt vmcnt(8)
	s_waitcnt lgkmcnt(0)
	s_setprio 1
	s_barrier
	v_mfma_f32_16x16x32_bf16 v[124:127], v[170:173], v[202:205], v[124:127]
	v_mfma_f32_16x16x32_bf16 v[120:123], v[178:181], v[202:205], v[120:123]
	v_mfma_f32_16x16x32_bf16 v[108:111], v[170:173], v[210:213], v[108:111]
	v_mfma_f32_16x16x32_bf16 v[104:107], v[178:181], v[210:213], v[104:107]
	v_mfma_f32_16x16x32_bf16 v[92:95], v[170:173], v[218:221], v[92:95]
	v_mfma_f32_16x16x32_bf16 v[88:91], v[178:181], v[218:221], v[88:91]
	v_mfma_f32_16x16x32_bf16 v[76:79], v[170:173], v[226:229], v[76:79]
	v_mfma_f32_16x16x32_bf16 v[72:75], v[178:181], v[226:229], v[72:75]
	v_mfma_f32_16x16x32_bf16 v[124:127], v[174:177], v[206:209], v[124:127]
	v_mfma_f32_16x16x32_bf16 v[120:123], v[182:185], v[206:209], v[120:123]
	v_mfma_f32_16x16x32_bf16 v[108:111], v[174:177], v[214:217], v[108:111]
	v_mfma_f32_16x16x32_bf16 v[104:107], v[182:185], v[214:217], v[104:107]
	v_mfma_f32_16x16x32_bf16 v[92:95], v[174:177], v[222:225], v[92:95]
	v_mfma_f32_16x16x32_bf16 v[88:91], v[182:185], v[222:225], v[88:91]
	v_mfma_f32_16x16x32_bf16 v[76:79], v[174:177], v[230:233], v[76:79]
	v_mfma_f32_16x16x32_bf16 v[72:75], v[182:185], v[230:233], v[72:75]
	s_setprio 0
	s_setprio 1
	v_mfma_f32_16x16x32_bf16 v[116:119], v[186:189], v[202:205], v[116:119]
	v_mfma_f32_16x16x32_bf16 v[112:115], v[194:197], v[202:205], v[112:115]
	v_mfma_f32_16x16x32_bf16 v[100:103], v[186:189], v[210:213], v[100:103]
	v_mfma_f32_16x16x32_bf16 v[96:99], v[194:197], v[210:213], v[96:99]
	v_mfma_f32_16x16x32_bf16 v[84:87], v[186:189], v[218:221], v[84:87]
	v_mfma_f32_16x16x32_bf16 v[80:83], v[194:197], v[218:221], v[80:83]
	v_mfma_f32_16x16x32_bf16 v[68:71], v[186:189], v[226:229], v[68:71]
	v_mfma_f32_16x16x32_bf16 v[64:67], v[194:197], v[226:229], v[64:67]
	v_mfma_f32_16x16x32_bf16 v[116:119], v[190:193], v[206:209], v[116:119]
	v_mfma_f32_16x16x32_bf16 v[112:115], v[198:201], v[206:209], v[112:115]
	v_mfma_f32_16x16x32_bf16 v[100:103], v[190:193], v[214:217], v[100:103]
	v_mfma_f32_16x16x32_bf16 v[96:99], v[198:201], v[214:217], v[96:99]
	v_mfma_f32_16x16x32_bf16 v[84:87], v[190:193], v[222:225], v[84:87]
	v_mfma_f32_16x16x32_bf16 v[80:83], v[198:201], v[222:225], v[80:83]
	v_mfma_f32_16x16x32_bf16 v[68:71], v[190:193], v[230:233], v[68:71]
	v_mfma_f32_16x16x32_bf16 v[64:67], v[198:201], v[230:233], v[64:67]
	s_barrier
	s_setprio 0
	s_mov_b32 m0, s54
	s_add_u32 s0, s0, 0x40080
	ds_read_b128 v[202:205], v149 offset:49152
	ds_read_b128 v[206:209], v149 offset:50176
	ds_read_b128 v[210:213], v149 offset:51200
	ds_read_b128 v[214:217], v149 offset:52224
	ds_read_b128 v[218:221], v149 offset:53248
	ds_read_b128 v[222:225], v149 offset:54272
	ds_read_b128 v[226:229], v149 offset:55296
	ds_read_b128 v[230:233], v149 offset:56320
	global_load_lds_dwordx4 v130, s[98:99]
	s_mov_b32 m0, s55
	s_addc_u32 s1, s1, 0
	global_load_lds_dwordx4 v134, s[98:99]
	s_mov_b32 m0, s58
	s_nop 0
	global_load_lds_dwordx4 v130, s[0:1]
	s_mov_b32 m0, s59
	s_nop 0
	global_load_lds_dwordx4 v134, s[0:1]
	s_mov_b32 m0, s56
	s_nop 0
	global_load_lds_dwordx4 v128, s[100:101]
	s_mov_b32 m0, s57
	s_nop 0
	global_load_lds_dwordx4 v132, s[100:101]
	s_waitcnt vmcnt(8)
	s_waitcnt lgkmcnt(0)
	s_setprio 1
	s_barrier
	v_mfma_f32_16x16x32_bf16 v[60:63], v[170:173], v[202:205], v[60:63]
	v_mfma_f32_16x16x32_bf16 v[56:59], v[178:181], v[202:205], v[56:59]
	v_mfma_f32_16x16x32_bf16 v[44:47], v[170:173], v[210:213], v[44:47]
	v_mfma_f32_16x16x32_bf16 v[40:43], v[178:181], v[210:213], v[40:43]
	v_mfma_f32_16x16x32_bf16 v[28:31], v[170:173], v[218:221], v[28:31]
	v_mfma_f32_16x16x32_bf16 v[24:27], v[178:181], v[218:221], v[24:27]
	v_mfma_f32_16x16x32_bf16 v[12:15], v[170:173], v[226:229], v[12:15]
	v_mfma_f32_16x16x32_bf16 v[8:11], v[178:181], v[226:229], v[8:11]
	v_mfma_f32_16x16x32_bf16 v[60:63], v[174:177], v[206:209], v[60:63]
	v_mfma_f32_16x16x32_bf16 v[56:59], v[182:185], v[206:209], v[56:59]
	v_mfma_f32_16x16x32_bf16 v[44:47], v[174:177], v[214:217], v[44:47]
	v_mfma_f32_16x16x32_bf16 v[40:43], v[182:185], v[214:217], v[40:43]
	v_mfma_f32_16x16x32_bf16 v[28:31], v[174:177], v[222:225], v[28:31]
	v_mfma_f32_16x16x32_bf16 v[24:27], v[182:185], v[222:225], v[24:27]
	v_mfma_f32_16x16x32_bf16 v[12:15], v[174:177], v[230:233], v[12:15]
	v_mfma_f32_16x16x32_bf16 v[8:11], v[182:185], v[230:233], v[8:11]
	s_setprio 0
	s_setprio 1
	v_mfma_f32_16x16x32_bf16 v[52:55], v[186:189], v[202:205], v[52:55]
	v_mfma_f32_16x16x32_bf16 v[48:51], v[194:197], v[202:205], v[48:51]
	v_mfma_f32_16x16x32_bf16 v[36:39], v[186:189], v[210:213], v[36:39]
	v_mfma_f32_16x16x32_bf16 v[32:35], v[194:197], v[210:213], v[32:35]
	v_mfma_f32_16x16x32_bf16 v[20:23], v[186:189], v[218:221], v[20:23]
	v_mfma_f32_16x16x32_bf16 v[16:19], v[194:197], v[218:221], v[16:19]
	v_mfma_f32_16x16x32_bf16 v[4:7], v[186:189], v[226:229], v[4:7]
	v_mfma_f32_16x16x32_bf16 v[0:3], v[194:197], v[226:229], v[0:3]
	v_mfma_f32_16x16x32_bf16 v[52:55], v[190:193], v[206:209], v[52:55]
	v_mfma_f32_16x16x32_bf16 v[48:51], v[198:201], v[206:209], v[48:51]
	v_mfma_f32_16x16x32_bf16 v[36:39], v[190:193], v[214:217], v[36:39]
	v_mfma_f32_16x16x32_bf16 v[32:35], v[198:201], v[214:217], v[32:35]
	v_mfma_f32_16x16x32_bf16 v[20:23], v[190:193], v[222:225], v[20:23]
	v_mfma_f32_16x16x32_bf16 v[16:19], v[198:201], v[222:225], v[16:19]
	v_mfma_f32_16x16x32_bf16 v[4:7], v[190:193], v[230:233], v[4:7]
	v_mfma_f32_16x16x32_bf16 v[0:3], v[198:201], v[230:233], v[0:3]
	s_barrier
	s_setprio 0
	s_add_i32 s72, s72, 2
	s_add_u32 s70, s70, 0x100
	s_addc_u32 s71, s71, 0
	s_add_u32 s40, s40, 0x100
	s_addc_u32 s41, s41, 0
	s_cmp_gt_u32 s72, 13
	s_cbranch_scc0 .LBB0_965
	s_and_b64 vcc, exec, s[14:15]
	s_cbranch_vccz .LBB0_968
	s_barrier

; #define PG8_STAGE(bufoff, gbase, voff) do { _Pragma("unroll") for (int _i = 0; _i < 2; ++_i) \
;         __builtin_amdgcn_global_load_lds((const unsigned*)((const char*)(gbase) + (voff)[_i]), (PG8_LAS unsigned*)(lds + (bufoff) + ldsw + _i * 8192), 16, 0, 0); } while (0)
; #define PG8_LDA(dst, b, h) do { _Pragma("unroll") for (int m = 0; m < 4; ++m) _Pragma("unroll") for (int k = 0; k < 2; ++k) dst[m][k] = *(const PG8_LAS bf16x8*)(lds + PG8_SA(b, h) + aoff + m * 2048 + k * 1024); } while (0)
; #define PG8_LDB(dst, b, h) do { _Pragma("unroll") for (int n = 0; n < 2; ++n) _Pragma("unroll") for (int k = 0; k < 2; ++k) dst[n][k] = *(const PG8_LAS bf16x8*)(lds + PG8_SB(b, h) + boff + n * 2048 + k * 1024); } while (0)
; #define PG8_MMA(ai, bj, At, Bt) do { __builtin_amdgcn_s_setprio(1); _Pragma("unroll") for (int m = 0; m < 4; ++m) _Pragma("unroll") for (int n = 0; n < 2; ++n) _Pragma("unroll") for (int k = 0; k < 2; ++k) \
;         acc[ai][bj][m][n] = __builtin_amdgcn_mfma_f32_16x16x32_bf16(Bt[n][k], At[m][k], acc[ai][bj][m][n], 0, 0, 0); __builtin_amdgcn_s_setprio(0); } while (0)
; #define PG8_WAIT_V(n) asm volatile("s_waitcnt vmcnt(" #n ")" ::: "memory")
; #define PG8_BAR __builtin_amdgcn_s_barrier()
; template <class Epi, class Sched, bool ALIGN_EPI = false, bool SP2 = false>
; __device__ __forceinline__ void gemm_phase(PG8_LAS unsigned char* lds, const Gemm g, const Sched& S, const Epi& E, const int tid_arg) {
;     ...
;         for (int t = 0; t < nt; t += 2) {
;             const bool last = (t == nt - 2);
;             const char* a1 = cA + (size_t)(t + 1) * kstep;
;             const char* a2 = last ? nA : cA + (size_t)(t + 2) * kstep; const char* b2 = last ? nB : cB + (size_t)(t + 2) * kstep;
;             const char* a3 = a2 + kstep; const char* b3 = b2 + kstep;
;             if (last && has_next) S.a_ready(nxt);
;             if constexpr (SP2) {
;             PG8_LDB(B0, 0, 0); PG8_LDB(B1, 0, 1); PG8_SCHED; PG8_LDA(At, 0, 0); PG8_STAGE(PG8_SA(1, 1), a1 + hstep, voffA);
;             PG8_WAIT_V(8); PG8_WAIT_L(0); PG8_BAR; PG8_MMA(0, 0, At, B0); PG8_MMA(0, 1, At, B1); PG8_BAR; PG8_SCHED;
;             PG8_LDA(At, 0, 1); PG8_STAGE(PG8_SB(0, 0), b2, voffB); PG8_STAGE(PG8_SB(0, 1), b2 + hstep, voffB); PG8_STAGE(PG8_SA(0, 0), a2, voffA);
;             PG8_WAIT_V(8); PG8_WAIT_L(0); PG8_BAR; PG8_MMA(1, 0, At, B0); PG8_MMA(1, 1, At, B1); PG8_BAR; PG8_SCHED;
.LBB0_1046:
	ds_read_b128 v[144:147], v151
	ds_read_b128 v[168:171], v152
	ds_read_b128 v[172:175], v153
	ds_read_b128 v[176:179], v154
	ds_read_b128 v[180:183], v155
	ds_read_b128 v[184:187], v156
	ds_read_b128 v[188:191], v157
	ds_read_b128 v[192:195], v158
	s_add_i32 s30, s0, 2
	s_add_u32 s31, s4, 0x80
	s_addc_u32 s1, s5, 0
	s_cmp_eq_u32 s52, s0
	s_cselect_b32 s0, s14, s31
	s_cselect_b32 s1, s15, s1
	s_cselect_b32 s63, s29, s61
	s_cselect_b32 s62, s28, s60
	s_mov_b32 m0, s53
	ds_read_b128 v[196:199], v150
	ds_read_b128 v[200:203], v150 offset:1024
	ds_read_b128 v[204:207], v150 offset:2048
	ds_read_b128 v[208:211], v150 offset:3072
	ds_read_b128 v[212:215], v150 offset:4096
	ds_read_b128 v[216:219], v150 offset:5120
	ds_read_b128 v[220:223], v150 offset:6144
	ds_read_b128 v[224:227], v150 offset:7168
	global_load_lds_dwordx4 v138, s[4:5]
	s_mov_b32 m0, s54
	s_nop 0
	global_load_lds_dwordx4 v136, s[4:5]
	s_waitcnt vmcnt(8)
	s_waitcnt lgkmcnt(0)
	s_setprio 1
	s_barrier
	v_mfma_f32_16x16x32_bf16 v[124:127], v[144:147], v[196:199], v[124:127]
	v_mfma_f32_16x16x32_bf16 v[120:123], v[172:175], v[196:199], v[120:123]
	v_mfma_f32_16x16x32_bf16 v[108:111], v[144:147], v[204:207], v[108:111]
	v_mfma_f32_16x16x32_bf16 v[104:107], v[172:175], v[204:207], v[104:107]
	v_mfma_f32_16x16x32_bf16 v[92:95], v[144:147], v[212:215], v[92:95]
	v_mfma_f32_16x16x32_bf16 v[88:91], v[172:175], v[212:215], v[88:91]
	v_mfma_f32_16x16x32_bf16 v[76:79], v[144:147], v[220:223], v[76:79]
	v_mfma_f32_16x16x32_bf16 v[72:75], v[172:175], v[220:223], v[72:75]
	v_mfma_f32_16x16x32_bf16 v[124:127], v[168:171], v[200:203], v[124:127]
	v_mfma_f32_16x16x32_bf16 v[120:123], v[176:179], v[200:203], v[120:123]
	v_mfma_f32_16x16x32_bf16 v[108:111], v[168:171], v[208:211], v[108:111]
	v_mfma_f32_16x16x32_bf16 v[104:107], v[176:179], v[208:211], v[104:107]
	v_mfma_f32_16x16x32_bf16 v[92:95], v[168:171], v[216:219], v[92:95]
	v_mfma_f32_16x16x32_bf16 v[88:91], v[176:179], v[216:219], v[88:91]
	v_mfma_f32_16x16x32_bf16 v[76:79], v[168:171], v[224:227], v[76:79]
	v_mfma_f32_16x16x32_bf16 v[72:75], v[176:179], v[224:227], v[72:75]
	s_setprio 0
	s_setprio 1
	v_mfma_f32_16x16x32_bf16 v[116:119], v[180:183], v[196:199], v[116:119]
	v_mfma_f32_16x16x32_bf16 v[112:115], v[188:191], v[196:199], v[112:115]
	v_mfma_f32_16x16x32_bf16 v[100:103], v[180:183], v[204:207], v[100:103]
	v_mfma_f32_16x16x32_bf16 v[96:99], v[188:191], v[204:207], v[96:99]
	v_mfma_f32_16x16x32_bf16 v[84:87], v[180:183], v[212:215], v[84:87]
	v_mfma_f32_16x16x32_bf16 v[80:83], v[188:191], v[212:215], v[80:83]
	v_mfma_f32_16x16x32_bf16 v[68:71], v[180:183], v[220:223], v[68:71]
	v_mfma_f32_16x16x32_bf16 v[64:67], v[188:191], v[220:223], v[64:67]
	v_mfma_f32_16x16x32_bf16 v[116:119], v[184:187], v[200:203], v[116:119]
	v_mfma_f32_16x16x32_bf16 v[112:115], v[192:195], v[200:203], v[112:115]
	v_mfma_f32_16x16x32_bf16 v[100:103], v[184:187], v[208:211], v[100:103]
	v_mfma_f32_16x16x32_bf16 v[96:99], v[192:195], v[208:211], v[96:99]
	v_mfma_f32_16x16x32_bf16 v[84:87], v[184:187], v[216:219], v[84:87]
	v_mfma_f32_16x16x32_bf16 v[80:83], v[192:195], v[216:219], v[80:83]
	v_mfma_f32_16x16x32_bf16 v[68:71], v[184:187], v[224:227], v[68:71]
	v_mfma_f32_16x16x32_bf16 v[64:67], v[192:195], v[224:227], v[64:67]
	s_barrier
	s_setprio 0
	s_mov_b32 m0, s37
	s_add_u32 s98, s62, s22
	s_addc_u32 s99, s63, s23
	v_lshl_add_u64 v[228:229], s[62:63], 0, v[130:131]
	v_lshl_add_u64 v[230:231], s[62:63], 0, v[134:135]
	s_add_u32 s62, s62, s6
	ds_read_b128 v[196:199], v150 offset:16384
	ds_read_b128 v[200:203], v150 offset:17408
	ds_read_b128 v[204:207], v150 offset:18432
	ds_read_b128 v[208:211], v150 offset:19456
	ds_read_b128 v[212:215], v150 offset:20480
	ds_read_b128 v[216:219], v150 offset:21504
	ds_read_b128 v[220:223], v150 offset:22528
	ds_read_b128 v[224:227], v150 offset:23552
	global_load_lds_dwordx4 v[228:229], off
	s_mov_b32 m0, s38
	s_addc_u32 s63, s63, s7
	global_load_lds_dwordx4 v[230:231], off
	s_add_u32 s100, s62, s22
	s_addc_u32 s101, s63, s23
	s_mov_b32 m0, s39
	s_nop 0
	global_load_lds_dwordx4 v130, s[62:63]
	s_mov_b32 m0, s40
	v_lshl_add_u64 v[236:237], s[0:1], 0, v[128:129]
	global_load_lds_dwordx4 v134, s[62:63]
	s_mov_b32 m0, s36
	v_lshl_add_u64 v[238:239], s[0:1], 0, v[132:133]
	global_load_lds_dwordx4 v128, s[0:1]
	s_mov_b32 m0, s41
	s_nop 0
	global_load_lds_dwordx4 v132, s[0:1]
	s_waitcnt vmcnt(8)
	s_waitcnt lgkmcnt(0)
	s_setprio 1
	s_barrier
	v_mfma_f32_16x16x32_bf16 v[60:63], v[144:147], v[196:199], v[60:63]
	v_mfma_f32_16x16x32_bf16 v[56:59], v[172:175], v[196:199], v[56:59]
	v_mfma_f32_16x16x32_bf16 v[44:47], v[144:147], v[204:207], v[44:47]
	v_mfma_f32_16x16x32_bf16 v[40:43], v[172:175], v[204:207], v[40:43]
	v_mfma_f32_16x16x32_bf16 v[28:31], v[144:147], v[212:215], v[28:31]
	v_mfma_f32_16x16x32_bf16 v[24:27], v[172:175], v[212:215], v[24:27]
	v_mfma_f32_16x16x32_bf16 v[12:15], v[144:147], v[220:223], v[12:15]
	v_mfma_f32_16x16x32_bf16 v[8:11], v[172:175], v[220:223], v[8:11]
	v_mfma_f32_16x16x32_bf16 v[60:63], v[168:171], v[200:203], v[60:63]
	v_mfma_f32_16x16x32_bf16 v[56:59], v[176:179], v[200:203], v[56:59]
	v_mfma_f32_16x16x32_bf16 v[44:47], v[168:171], v[208:211], v[44:47]
	v_mfma_f32_16x16x32_bf16 v[40:43], v[176:179], v[208:211], v[40:43]
	v_mfma_f32_16x16x32_bf16 v[28:31], v[168:171], v[216:219], v[28:31]
	v_mfma_f32_16x16x32_bf16 v[24:27], v[176:179], v[216:219], v[24:27]
	v_mfma_f32_16x16x32_bf16 v[12:15], v[168:171], v[224:227], v[12:15]
	v_mfma_f32_16x16x32_bf16 v[8:11], v[176:179], v[224:227], v[8:11]
	s_setprio 0
	s_setprio 1
	v_mfma_f32_16x16x32_bf16 v[52:55], v[180:183], v[196:199], v[52:55]
	v_mfma_f32_16x16x32_bf16 v[48:51], v[188:191], v[196:199], v[48:51]
	v_mfma_f32_16x16x32_bf16 v[36:39], v[180:183], v[204:207], v[36:39]
	v_mfma_f32_16x16x32_bf16 v[32:35], v[188:191], v[204:207], v[32:35]
	v_mfma_f32_16x16x32_bf16 v[20:23], v[180:183], v[212:215], v[20:23]
	v_mfma_f32_16x16x32_bf16 v[16:19], v[188:191], v[212:215], v[16:19]
	v_mfma_f32_16x16x32_bf16 v[4:7], v[180:183], v[220:223], v[4:7]
	v_mfma_f32_16x16x32_bf16 v[0:3], v[188:191], v[220:223], v[0:3]
	v_mfma_f32_16x16x32_bf16 v[52:55], v[184:187], v[200:203], v[52:55]
	v_mfma_f32_16x16x32_bf16 v[48:51], v[192:195], v[200:203], v[48:51]
	v_mfma_f32_16x16x32_bf16 v[36:39], v[184:187], v[208:211], v[36:39]
	v_mfma_f32_16x16x32_bf16 v[32:35], v[192:195], v[208:211], v[32:35]
	v_mfma_f32_16x16x32_bf16 v[20:23], v[184:187], v[216:219], v[20:23]
	v_mfma_f32_16x16x32_bf16 v[16:19], v[192:195], v[216:219], v[16:19]
	v_mfma_f32_16x16x32_bf16 v[4:7], v[184:187], v[224:227], v[4:7]
	v_mfma_f32_16x16x32_bf16 v[0:3], v[192:195], v[224:227], v[0:3]
	s_barrier
; #define PG8_STAGE(bufoff, gbase, voff) do { _Pragma("unroll") for (int _i = 0; _i < 2; ++_i) \
;         __builtin_amdgcn_global_load_lds((const unsigned*)((const char*)(gbase) + (voff)[_i]), (PG8_LAS unsigned*)(lds + (bufoff) + ldsw + _i * 8192), 16, 0, 0); } while (0)
; #define PG8_LDA(dst, b, h) do { _Pragma("unroll") for (int m = 0; m < 4; ++m) _Pragma("unroll") for (int k = 0; k < 2; ++k) dst[m][k] = *(const PG8_LAS bf16x8*)(lds + PG8_SA(b, h) + aoff + m * 2048 + k * 1024); } while (0)
; #define PG8_LDB(dst, b, h) do { _Pragma("unroll") for (int n = 0; n < 2; ++n) _Pragma("unroll") for (int k = 0; k < 2; ++k) dst[n][k] = *(const PG8_LAS bf16x8*)(lds + PG8_SB(b, h) + boff + n * 2048 + k * 1024); } while (0)
; #define PG8_MMA(ai, bj, At, Bt) do { __builtin_amdgcn_s_setprio(1); _Pragma("unroll") for (int m = 0; m < 4; ++m) _Pragma("unroll") for (int n = 0; n < 2; ++n) _Pragma("unroll") for (int k = 0; k < 2; ++k) \
;         acc[ai][bj][m][n] = __builtin_amdgcn_mfma_f32_16x16x32_bf16(Bt[n][k], At[m][k], acc[ai][bj][m][n], 0, 0, 0); __builtin_amdgcn_s_setprio(0); } while (0)
; #define PG8_WAIT_V(n) asm volatile("s_waitcnt vmcnt(" #n ")" ::: "memory")
; #define PG8_WAIT_L(n) asm volatile("s_waitcnt lgkmcnt(" #n ")" ::: "memory")
; #define PG8_BAR __builtin_amdgcn_s_barrier()
; #define PG8_SCHED __builtin_amdgcn_sched_barrier(0)
; template <class Epi, class Sched, bool ALIGN_EPI = false, bool SP2 = false>
; __device__ __forceinline__ void gemm_phase(PG8_LAS unsigned char* lds, const Gemm g, const Sched& S, const Epi& E, const int tid_arg) {
;     ...
;             PG8_LDB(B0, 1, 0); PG8_LDB(B1, 1, 1); PG8_SCHED; PG8_LDA(At, 1, 0); PG8_STAGE(PG8_SA(0, 1), a2 + hstep, voffA);
;             PG8_WAIT_V(8); PG8_WAIT_L(0); PG8_BAR; PG8_MMA(0, 0, At, B0); PG8_MMA(0, 1, At, B1); PG8_BAR; PG8_SCHED;
;             PG8_LDA(At, 1, 1); PG8_STAGE(PG8_SB(1, 0), b3, voffB); PG8_STAGE(PG8_SB(1, 1), b3 + hstep, voffB); PG8_STAGE(PG8_SA(1, 0), a3, voffA);
;             PG8_WAIT_V(8); PG8_WAIT_L(0); PG8_BAR; PG8_MMA(1, 0, At, B0); PG8_MMA(1, 1, At, B1); PG8_BAR; PG8_SCHED;
	s_setprio 0
	ds_read_b128 v[144:147], v159
	ds_read_b128 v[168:171], v160
	ds_read_b128 v[172:175], v161
	ds_read_b128 v[176:179], v162
	ds_read_b128 v[180:183], v163
	ds_read_b128 v[184:187], v164
	ds_read_b128 v[188:191], v165
	ds_read_b128 v[192:195], v166
	s_add_u32 s0, s0, s6
	s_addc_u32 s1, s1, s7
	s_mov_b32 m0, s42
	ds_read_b128 v[196:199], v150 offset:32768
	ds_read_b128 v[200:203], v150 offset:33792
	ds_read_b128 v[204:207], v150 offset:34816
	ds_read_b128 v[208:211], v150 offset:35840
	ds_read_b128 v[212:215], v150 offset:36864
	ds_read_b128 v[216:219], v150 offset:37888
	ds_read_b128 v[220:223], v150 offset:38912
	ds_read_b128 v[224:227], v150 offset:39936
	global_load_lds_dwordx4 v128, s[0:1]
	s_mov_b32 m0, s43
	s_nop 0
	global_load_lds_dwordx4 v132, s[0:1]
	s_waitcnt vmcnt(8)
	s_waitcnt lgkmcnt(0)
	s_setprio 1
	s_barrier
	v_mfma_f32_16x16x32_bf16 v[124:127], v[144:147], v[196:199], v[124:127]
	v_mfma_f32_16x16x32_bf16 v[120:123], v[172:175], v[196:199], v[120:123]
	v_mfma_f32_16x16x32_bf16 v[108:111], v[144:147], v[204:207], v[108:111]
	v_mfma_f32_16x16x32_bf16 v[104:107], v[172:175], v[204:207], v[104:107]
	v_mfma_f32_16x16x32_bf16 v[92:95], v[144:147], v[212:215], v[92:95]
	v_mfma_f32_16x16x32_bf16 v[88:91], v[172:175], v[212:215], v[88:91]
	v_mfma_f32_16x16x32_bf16 v[76:79], v[144:147], v[220:223], v[76:79]
	v_mfma_f32_16x16x32_bf16 v[72:75], v[172:175], v[220:223], v[72:75]
	v_mfma_f32_16x16x32_bf16 v[124:127], v[168:171], v[200:203], v[124:127]
	v_mfma_f32_16x16x32_bf16 v[120:123], v[176:179], v[200:203], v[120:123]
	v_mfma_f32_16x16x32_bf16 v[108:111], v[168:171], v[208:211], v[108:111]
	v_mfma_f32_16x16x32_bf16 v[104:107], v[176:179], v[208:211], v[104:107]
	v_mfma_f32_16x16x32_bf16 v[92:95], v[168:171], v[216:219], v[92:95]
	v_mfma_f32_16x16x32_bf16 v[88:91], v[176:179], v[216:219], v[88:91]
	v_mfma_f32_16x16x32_bf16 v[76:79], v[168:171], v[224:227], v[76:79]
	v_mfma_f32_16x16x32_bf16 v[72:75], v[176:179], v[224:227], v[72:75]
	s_setprio 0
	s_setprio 1
	v_mfma_f32_16x16x32_bf16 v[116:119], v[180:183], v[196:199], v[116:119]
	v_mfma_f32_16x16x32_bf16 v[112:115], v[188:191], v[196:199], v[112:115]
	v_mfma_f32_16x16x32_bf16 v[100:103], v[180:183], v[204:207], v[100:103]
	v_mfma_f32_16x16x32_bf16 v[96:99], v[188:191], v[204:207], v[96:99]
	v_mfma_f32_16x16x32_bf16 v[84:87], v[180:183], v[212:215], v[84:87]
	v_mfma_f32_16x16x32_bf16 v[80:83], v[188:191], v[212:215], v[80:83]
	v_mfma_f32_16x16x32_bf16 v[68:71], v[180:183], v[220:223], v[68:71]
	v_mfma_f32_16x16x32_bf16 v[64:67], v[188:191], v[220:223], v[64:67]
	v_mfma_f32_16x16x32_bf16 v[116:119], v[184:187], v[200:203], v[116:119]
	v_mfma_f32_16x16x32_bf16 v[112:115], v[192:195], v[200:203], v[112:115]
	v_mfma_f32_16x16x32_bf16 v[100:103], v[184:187], v[208:211], v[100:103]
	v_mfma_f32_16x16x32_bf16 v[96:99], v[192:195], v[208:211], v[96:99]
	v_mfma_f32_16x16x32_bf16 v[84:87], v[184:187], v[216:219], v[84:87]
	v_mfma_f32_16x16x32_bf16 v[80:83], v[192:195], v[216:219], v[80:83]
	v_mfma_f32_16x16x32_bf16 v[68:71], v[184:187], v[224:227], v[68:71]
	v_mfma_f32_16x16x32_bf16 v[64:67], v[192:195], v[224:227], v[64:67]
	s_barrier
	s_setprio 0
	s_mov_b32 m0, s44
	ds_read_b128 v[196:199], v150 offset:49152
	ds_read_b128 v[200:203], v150 offset:50176
	ds_read_b128 v[204:207], v150 offset:51200
	ds_read_b128 v[208:211], v150 offset:52224
	ds_read_b128 v[212:215], v150 offset:53248
	ds_read_b128 v[216:219], v150 offset:54272
	ds_read_b128 v[220:223], v150 offset:55296
	ds_read_b128 v[224:227], v150 offset:56320
	global_load_lds_dwordx4 v130, s[98:99]
	s_mov_b32 m0, s45
	s_nop 0
	global_load_lds_dwordx4 v134, s[98:99]
	s_mov_b32 m0, s48
	s_nop 0
	global_load_lds_dwordx4 v130, s[100:101]
	s_mov_b32 m0, s49
	s_nop 0
	global_load_lds_dwordx4 v134, s[100:101]
	v_lshl_add_u64 v[228:229], v[236:237], 0, s[22:23]
	s_mov_b32 m0, s46
	s_nop 0
	global_load_lds_dwordx4 v[228:229], off
	v_lshl_add_u64 v[228:229], v[238:239], 0, s[22:23]
	s_mov_b32 m0, s47
	s_nop 0
	global_load_lds_dwordx4 v[228:229], off
	s_waitcnt vmcnt(8)
	s_waitcnt lgkmcnt(0)
	s_setprio 1
	s_barrier
	v_mfma_f32_16x16x32_bf16 v[60:63], v[144:147], v[196:199], v[60:63]
	v_mfma_f32_16x16x32_bf16 v[56:59], v[172:175], v[196:199], v[56:59]
	v_mfma_f32_16x16x32_bf16 v[44:47], v[144:147], v[204:207], v[44:47]
	v_mfma_f32_16x16x32_bf16 v[40:43], v[172:175], v[204:207], v[40:43]
	v_mfma_f32_16x16x32_bf16 v[28:31], v[144:147], v[212:215], v[28:31]
	v_mfma_f32_16x16x32_bf16 v[24:27], v[172:175], v[212:215], v[24:27]
	v_mfma_f32_16x16x32_bf16 v[12:15], v[144:147], v[220:223], v[12:15]
	v_mfma_f32_16x16x32_bf16 v[8:11], v[172:175], v[220:223], v[8:11]
	v_mfma_f32_16x16x32_bf16 v[60:63], v[168:171], v[200:203], v[60:63]
	v_mfma_f32_16x16x32_bf16 v[56:59], v[176:179], v[200:203], v[56:59]
	v_mfma_f32_16x16x32_bf16 v[44:47], v[168:171], v[208:211], v[44:47]
	v_mfma_f32_16x16x32_bf16 v[40:43], v[176:179], v[208:211], v[40:43]
	v_mfma_f32_16x16x32_bf16 v[28:31], v[168:171], v[216:219], v[28:31]
	v_mfma_f32_16x16x32_bf16 v[24:27], v[176:179], v[216:219], v[24:27]
	v_mfma_f32_16x16x32_bf16 v[12:15], v[168:171], v[224:227], v[12:15]
	v_mfma_f32_16x16x32_bf16 v[8:11], v[176:179], v[224:227], v[8:11]
	s_setprio 0
	s_setprio 1
	v_mfma_f32_16x16x32_bf16 v[52:55], v[180:183], v[196:199], v[52:55]
	v_mfma_f32_16x16x32_bf16 v[48:51], v[188:191], v[196:199], v[48:51]
	v_mfma_f32_16x16x32_bf16 v[36:39], v[180:183], v[204:207], v[36:39]
	v_mfma_f32_16x16x32_bf16 v[32:35], v[188:191], v[204:207], v[32:35]
	v_mfma_f32_16x16x32_bf16 v[20:23], v[180:183], v[212:215], v[20:23]
	v_mfma_f32_16x16x32_bf16 v[16:19], v[188:191], v[212:215], v[16:19]
	v_mfma_f32_16x16x32_bf16 v[4:7], v[180:183], v[220:223], v[4:7]
	v_mfma_f32_16x16x32_bf16 v[0:3], v[188:191], v[220:223], v[0:3]
	v_mfma_f32_16x16x32_bf16 v[52:55], v[184:187], v[200:203], v[52:55]
	v_mfma_f32_16x16x32_bf16 v[48:51], v[192:195], v[200:203], v[48:51]
	v_mfma_f32_16x16x32_bf16 v[36:39], v[184:187], v[208:211], v[36:39]
	v_mfma_f32_16x16x32_bf16 v[32:35], v[192:195], v[208:211], v[32:35]
	v_mfma_f32_16x16x32_bf16 v[20:23], v[184:187], v[216:219], v[20:23]
	v_mfma_f32_16x16x32_bf16 v[16:19], v[192:195], v[216:219], v[16:19]
	v_mfma_f32_16x16x32_bf16 v[4:7], v[184:187], v[224:227], v[4:7]
	v_mfma_f32_16x16x32_bf16 v[0:3], v[192:195], v[224:227], v[0:3]
	s_barrier
	s_setprio 0
	s_add_u32 s60, s60, 0x100
	s_addc_u32 s61, s61, 0
	s_add_u32 s4, s4, 0x100
	s_addc_u32 s5, s5, 0
	s_cmp_ge_i32 s30, s50
	s_mov_b32 s0, s30
	s_cbranch_scc0 .LBB0_1046

; #define PG8_STAGE(bufoff, gbase, voff) do { _Pragma("unroll") for (int _i = 0; _i < 2; ++_i) \
;         __builtin_amdgcn_global_load_lds((const unsigned*)((const char*)(gbase) + (voff)[_i]), (PG8_LAS unsigned*)(lds + (bufoff) + ldsw + _i * 8192), 16, 0, 0); } while (0)
; #define PG8_LDA(dst, b, h) do { _Pragma("unroll") for (int m = 0; m < 4; ++m) _Pragma("unroll") for (int k = 0; k < 2; ++k) dst[m][k] = *(const PG8_LAS bf16x8*)(lds + PG8_SA(b, h) + aoff + m * 2048 + k * 1024); } while (0)
; #define PG8_LDB(dst, b, h) do { _Pragma("unroll") for (int n = 0; n < 2; ++n) _Pragma("unroll") for (int k = 0; k < 2; ++k) dst[n][k] = *(const PG8_LAS bf16x8*)(lds + PG8_SB(b, h) + boff + n * 2048 + k * 1024); } while (0)
; #define PG8_MMA(ai, bj, At, Bt) do { __builtin_amdgcn_s_setprio(1); _Pragma("unroll") for (int m = 0; m < 4; ++m) _Pragma("unroll") for (int n = 0; n < 2; ++n) _Pragma("unroll") for (int k = 0; k < 2; ++k) \
;         acc[ai][bj][m][n] = __builtin_amdgcn_mfma_f32_16x16x32_bf16(Bt[n][k], At[m][k], acc[ai][bj][m][n], 0, 0, 0); __builtin_amdgcn_s_setprio(0); } while (0)
; #define PG8_WAIT_V(n) asm volatile("s_waitcnt vmcnt(" #n ")" ::: "memory")
; #define PG8_BAR __builtin_amdgcn_s_barrier()
; template <class Epi, class Sched, bool ALIGN_EPI = false, bool SP2 = false>
; __device__ __forceinline__ void gemm_phase(PG8_LAS unsigned char* lds, const Gemm g, const Sched& S, const Epi& E, const int tid_arg) {
;     ...
;         for (int t = 0; t < nt; t += 2) {
;             const bool last = (t == nt - 2);
;             const char* a1 = cA + (size_t)(t + 1) * kstep;
;             const char* a2 = last ? nA : cA + (size_t)(t + 2) * kstep; const char* b2 = last ? nB : cB + (size_t)(t + 2) * kstep;
;             const char* a3 = a2 + kstep; const char* b3 = b2 + kstep;
;             if (last && has_next) S.a_ready(nxt);
;             if constexpr (SP2) {
;             PG8_LDB(B0, 0, 0); PG8_LDB(B1, 0, 1); PG8_SCHED; PG8_LDA(At, 0, 0); PG8_STAGE(PG8_SA(1, 1), a1 + hstep, voffA);
;             PG8_WAIT_V(8); PG8_WAIT_L(0); PG8_BAR; PG8_MMA(0, 0, At, B0); PG8_MMA(0, 1, At, B1); PG8_BAR; PG8_SCHED;
;             PG8_LDA(At, 0, 1); PG8_STAGE(PG8_SB(0, 0), b2, voffB); PG8_STAGE(PG8_SB(0, 1), b2 + hstep, voffB); PG8_STAGE(PG8_SA(0, 0), a2, voffA);
;             PG8_WAIT_V(8); PG8_WAIT_L(0); PG8_BAR; PG8_MMA(1, 0, At, B0); PG8_MMA(1, 1, At, B1); PG8_BAR; PG8_SCHED;
.LBB0_1179:
	ds_read_b128 v[144:147], v166
	ds_read_b128 v[148:151], v167
	ds_read_b128 v[152:155], v168
	ds_read_b128 v[156:159], v169
	ds_read_b128 v[184:187], v170
	ds_read_b128 v[188:191], v171
	ds_read_b128 v[192:195], v172
	ds_read_b128 v[196:199], v173
	s_add_u32 s0, s4, 0xfffc0080
	s_addc_u32 s1, s5, -1
	s_cmp_eq_u32 s68, 12
	s_cselect_b32 s11, s25, s1
	s_cselect_b32 s10, s36, s0
	s_cselect_b32 s1, s23, s67
	s_cselect_b32 s0, s37, s66
	s_mov_b32 m0, s55
	ds_read_b128 v[200:203], v165
	ds_read_b128 v[204:207], v165 offset:1024
	ds_read_b128 v[208:211], v165 offset:2048
	ds_read_b128 v[212:215], v165 offset:3072
	ds_read_b128 v[216:219], v165 offset:4096
	ds_read_b128 v[220:223], v165 offset:5120
	ds_read_b128 v[224:227], v165 offset:6144
	ds_read_b128 v[228:231], v165 offset:7168
	global_load_lds_dwordx4 v138, s[4:5]
	s_mov_b32 m0, s56
	s_nop 0
	global_load_lds_dwordx4 v136, s[4:5]
	s_waitcnt vmcnt(8)
	s_waitcnt lgkmcnt(0)
	s_setprio 1
	s_barrier
	v_mfma_f32_16x16x32_bf16 v[124:127], v[144:147], v[200:203], v[124:127]
	v_mfma_f32_16x16x32_bf16 v[120:123], v[152:155], v[200:203], v[120:123]
	v_mfma_f32_16x16x32_bf16 v[108:111], v[144:147], v[208:211], v[108:111]
	v_mfma_f32_16x16x32_bf16 v[104:107], v[152:155], v[208:211], v[104:107]
	v_mfma_f32_16x16x32_bf16 v[92:95], v[144:147], v[216:219], v[92:95]
	v_mfma_f32_16x16x32_bf16 v[88:91], v[152:155], v[216:219], v[88:91]
	v_mfma_f32_16x16x32_bf16 v[76:79], v[144:147], v[224:227], v[76:79]
	v_mfma_f32_16x16x32_bf16 v[72:75], v[152:155], v[224:227], v[72:75]
	v_mfma_f32_16x16x32_bf16 v[124:127], v[148:151], v[204:207], v[124:127]
	v_mfma_f32_16x16x32_bf16 v[120:123], v[156:159], v[204:207], v[120:123]
	v_mfma_f32_16x16x32_bf16 v[108:111], v[148:151], v[212:215], v[108:111]
	v_mfma_f32_16x16x32_bf16 v[104:107], v[156:159], v[212:215], v[104:107]
	v_mfma_f32_16x16x32_bf16 v[92:95], v[148:151], v[220:223], v[92:95]
	v_mfma_f32_16x16x32_bf16 v[88:91], v[156:159], v[220:223], v[88:91]
	v_mfma_f32_16x16x32_bf16 v[76:79], v[148:151], v[228:231], v[76:79]
	v_mfma_f32_16x16x32_bf16 v[72:75], v[156:159], v[228:231], v[72:75]
	s_setprio 0
	s_setprio 1
	v_mfma_f32_16x16x32_bf16 v[116:119], v[184:187], v[200:203], v[116:119]
	v_mfma_f32_16x16x32_bf16 v[112:115], v[192:195], v[200:203], v[112:115]
	v_mfma_f32_16x16x32_bf16 v[100:103], v[184:187], v[208:211], v[100:103]
	v_mfma_f32_16x16x32_bf16 v[96:99], v[192:195], v[208:211], v[96:99]
	v_mfma_f32_16x16x32_bf16 v[84:87], v[184:187], v[216:219], v[84:87]
	v_mfma_f32_16x16x32_bf16 v[80:83], v[192:195], v[216:219], v[80:83]
	v_mfma_f32_16x16x32_bf16 v[68:71], v[184:187], v[224:227], v[68:71]
	v_mfma_f32_16x16x32_bf16 v[64:67], v[192:195], v[224:227], v[64:67]
	v_mfma_f32_16x16x32_bf16 v[116:119], v[188:191], v[204:207], v[116:119]
	v_mfma_f32_16x16x32_bf16 v[112:115], v[196:199], v[204:207], v[112:115]
	v_mfma_f32_16x16x32_bf16 v[100:103], v[188:191], v[212:215], v[100:103]
	v_mfma_f32_16x16x32_bf16 v[96:99], v[196:199], v[212:215], v[96:99]
	v_mfma_f32_16x16x32_bf16 v[84:87], v[188:191], v[220:223], v[84:87]
	v_mfma_f32_16x16x32_bf16 v[80:83], v[196:199], v[220:223], v[80:83]
	v_mfma_f32_16x16x32_bf16 v[68:71], v[188:191], v[228:231], v[68:71]
	v_mfma_f32_16x16x32_bf16 v[64:67], v[196:199], v[228:231], v[64:67]
	s_barrier
	s_setprio 0
	s_mov_b32 m0, s31
	s_add_u32 s98, s0, s16
	s_addc_u32 s99, s1, s17
	s_add_u32 s70, s0, 0x40000
	ds_read_b128 v[200:203], v165 offset:16384
	ds_read_b128 v[204:207], v165 offset:17408
	ds_read_b128 v[208:211], v165 offset:18432
	ds_read_b128 v[212:215], v165 offset:19456
	ds_read_b128 v[216:219], v165 offset:20480
	ds_read_b128 v[220:223], v165 offset:21504
	ds_read_b128 v[224:227], v165 offset:22528
	ds_read_b128 v[228:231], v165 offset:23552
	global_load_lds_dwordx4 v130, s[0:1]
	s_mov_b32 m0, s35
	s_addc_u32 s71, s1, 0
	global_load_lds_dwordx4 v134, s[0:1]
	s_mov_b32 m0, s40
	s_nop 0
	global_load_lds_dwordx4 v130, s[70:71]
	s_mov_b32 m0, s41
	s_nop 0
	global_load_lds_dwordx4 v134, s[70:71]
	s_add_u32 s100, s10, s16
	s_addc_u32 s101, s11, s17
	s_mov_b32 m0, s39
	s_nop 0
	global_load_lds_dwordx4 v128, s[10:11]
	s_mov_b32 m0, s42
	s_nop 0
	global_load_lds_dwordx4 v132, s[10:11]
	s_waitcnt vmcnt(8)
	s_waitcnt lgkmcnt(0)
	s_setprio 1
	s_barrier
	v_mfma_f32_16x16x32_bf16 v[60:63], v[144:147], v[200:203], v[60:63]
	v_mfma_f32_16x16x32_bf16 v[56:59], v[152:155], v[200:203], v[56:59]
	v_mfma_f32_16x16x32_bf16 v[44:47], v[144:147], v[208:211], v[44:47]
	v_mfma_f32_16x16x32_bf16 v[40:43], v[152:155], v[208:211], v[40:43]
	v_mfma_f32_16x16x32_bf16 v[28:31], v[144:147], v[216:219], v[28:31]
	v_mfma_f32_16x16x32_bf16 v[24:27], v[152:155], v[216:219], v[24:27]
	v_mfma_f32_16x16x32_bf16 v[12:15], v[144:147], v[224:227], v[12:15]
	v_mfma_f32_16x16x32_bf16 v[8:11], v[152:155], v[224:227], v[8:11]
	v_mfma_f32_16x16x32_bf16 v[60:63], v[148:151], v[204:207], v[60:63]
	v_mfma_f32_16x16x32_bf16 v[56:59], v[156:159], v[204:207], v[56:59]
	v_mfma_f32_16x16x32_bf16 v[44:47], v[148:151], v[212:215], v[44:47]
	v_mfma_f32_16x16x32_bf16 v[40:43], v[156:159], v[212:215], v[40:43]
	v_mfma_f32_16x16x32_bf16 v[28:31], v[148:151], v[220:223], v[28:31]
	v_mfma_f32_16x16x32_bf16 v[24:27], v[156:159], v[220:223], v[24:27]
	v_mfma_f32_16x16x32_bf16 v[12:15], v[148:151], v[228:231], v[12:15]
	v_mfma_f32_16x16x32_bf16 v[8:11], v[156:159], v[228:231], v[8:11]
	s_setprio 0
	s_setprio 1
	v_mfma_f32_16x16x32_bf16 v[52:55], v[184:187], v[200:203], v[52:55]
	v_mfma_f32_16x16x32_bf16 v[48:51], v[192:195], v[200:203], v[48:51]
	v_mfma_f32_16x16x32_bf16 v[36:39], v[184:187], v[208:211], v[36:39]
	v_mfma_f32_16x16x32_bf16 v[32:35], v[192:195], v[208:211], v[32:35]
	v_mfma_f32_16x16x32_bf16 v[20:23], v[184:187], v[216:219], v[20:23]
	v_mfma_f32_16x16x32_bf16 v[16:19], v[192:195], v[216:219], v[16:19]
	v_mfma_f32_16x16x32_bf16 v[4:7], v[184:187], v[224:227], v[4:7]
	v_mfma_f32_16x16x32_bf16 v[0:3], v[192:195], v[224:227], v[0:3]
	v_mfma_f32_16x16x32_bf16 v[52:55], v[188:191], v[204:207], v[52:55]
	v_mfma_f32_16x16x32_bf16 v[48:51], v[196:199], v[204:207], v[48:51]
	v_mfma_f32_16x16x32_bf16 v[36:39], v[188:191], v[212:215], v[36:39]
	v_mfma_f32_16x16x32_bf16 v[32:35], v[196:199], v[212:215], v[32:35]
	v_mfma_f32_16x16x32_bf16 v[20:23], v[188:191], v[220:223], v[20:23]
	v_mfma_f32_16x16x32_bf16 v[16:19], v[196:199], v[220:223], v[16:19]
	v_mfma_f32_16x16x32_bf16 v[4:7], v[188:191], v[228:231], v[4:7]
	v_mfma_f32_16x16x32_bf16 v[0:3], v[196:199], v[228:231], v[0:3]
	s_barrier
; #define PG8_STAGE(bufoff, gbase, voff) do { _Pragma("unroll") for (int _i = 0; _i < 2; ++_i) \
;         __builtin_amdgcn_global_load_lds((const unsigned*)((const char*)(gbase) + (voff)[_i]), (PG8_LAS unsigned*)(lds + (bufoff) + ldsw + _i * 8192), 16, 0, 0); } while (0)
; #define PG8_LDA(dst, b, h) do { _Pragma("unroll") for (int m = 0; m < 4; ++m) _Pragma("unroll") for (int k = 0; k < 2; ++k) dst[m][k] = *(const PG8_LAS bf16x8*)(lds + PG8_SA(b, h) + aoff + m * 2048 + k * 1024); } while (0)
; #define PG8_LDB(dst, b, h) do { _Pragma("unroll") for (int n = 0; n < 2; ++n) _Pragma("unroll") for (int k = 0; k < 2; ++k) dst[n][k] = *(const PG8_LAS bf16x8*)(lds + PG8_SB(b, h) + boff + n * 2048 + k * 1024); } while (0)
; #define PG8_MMA(ai, bj, At, Bt) do { __builtin_amdgcn_s_setprio(1); _Pragma("unroll") for (int m = 0; m < 4; ++m) _Pragma("unroll") for (int n = 0; n < 2; ++n) _Pragma("unroll") for (int k = 0; k < 2; ++k) \
;         acc[ai][bj][m][n] = __builtin_amdgcn_mfma_f32_16x16x32_bf16(Bt[n][k], At[m][k], acc[ai][bj][m][n], 0, 0, 0); __builtin_amdgcn_s_setprio(0); } while (0)
; #define PG8_WAIT_V(n) asm volatile("s_waitcnt vmcnt(" #n ")" ::: "memory")
; #define PG8_WAIT_L(n) asm volatile("s_waitcnt lgkmcnt(" #n ")" ::: "memory")
; #define PG8_BAR __builtin_amdgcn_s_barrier()
; #define PG8_SCHED __builtin_amdgcn_sched_barrier(0)
; template <class Epi, class Sched, bool ALIGN_EPI = false, bool SP2 = false>
; __device__ __forceinline__ void gemm_phase(PG8_LAS unsigned char* lds, const Gemm g, const Sched& S, const Epi& E, const int tid_arg) {
;     ...
;             PG8_LDB(B0, 1, 0); PG8_LDB(B1, 1, 1); PG8_SCHED; PG8_LDA(At, 1, 0); PG8_STAGE(PG8_SA(0, 1), a2 + hstep, voffA);
;             PG8_WAIT_V(8); PG8_WAIT_L(0); PG8_BAR; PG8_MMA(0, 0, At, B0); PG8_MMA(0, 1, At, B1); PG8_BAR; PG8_SCHED;
;             PG8_LDA(At, 1, 1); PG8_STAGE(PG8_SB(1, 0), b3, voffB); PG8_STAGE(PG8_SB(1, 1), b3 + hstep, voffB); PG8_STAGE(PG8_SA(1, 0), a3, voffA);
;             PG8_WAIT_V(8); PG8_WAIT_L(0); PG8_BAR; PG8_MMA(1, 0, At, B0); PG8_MMA(1, 1, At, B1); PG8_BAR; PG8_SCHED;
	s_setprio 0
	ds_read_b128 v[144:147], v174
	ds_read_b128 v[148:151], v175
	ds_read_b128 v[152:155], v176
	ds_read_b128 v[156:159], v177
	ds_read_b128 v[184:187], v178
	ds_read_b128 v[188:191], v179
	ds_read_b128 v[192:195], v180
	ds_read_b128 v[196:199], v181
	s_add_u32 s10, s10, 0x40000
	s_addc_u32 s11, s11, 0
	s_mov_b32 m0, s43
	ds_read_b128 v[200:203], v165 offset:32768
	ds_read_b128 v[204:207], v165 offset:33792
	ds_read_b128 v[208:211], v165 offset:34816
	ds_read_b128 v[212:215], v165 offset:35840
	ds_read_b128 v[216:219], v165 offset:36864
	ds_read_b128 v[220:223], v165 offset:37888
	ds_read_b128 v[224:227], v165 offset:38912
	ds_read_b128 v[228:231], v165 offset:39936
	global_load_lds_dwordx4 v128, s[10:11]
	s_mov_b32 m0, s44
	s_nop 0
	global_load_lds_dwordx4 v132, s[10:11]
	s_waitcnt vmcnt(8)
	s_waitcnt lgkmcnt(0)
	s_setprio 1
	s_barrier
	v_mfma_f32_16x16x32_bf16 v[124:127], v[144:147], v[200:203], v[124:127]
	v_mfma_f32_16x16x32_bf16 v[120:123], v[152:155], v[200:203], v[120:123]
	v_mfma_f32_16x16x32_bf16 v[108:111], v[144:147], v[208:211], v[108:111]
	v_mfma_f32_16x16x32_bf16 v[104:107], v[152:155], v[208:211], v[104:107]
	v_mfma_f32_16x16x32_bf16 v[92:95], v[144:147], v[216:219], v[92:95]
	v_mfma_f32_16x16x32_bf16 v[88:91], v[152:155], v[216:219], v[88:91]
	v_mfma_f32_16x16x32_bf16 v[76:79], v[144:147], v[224:227], v[76:79]
	v_mfma_f32_16x16x32_bf16 v[72:75], v[152:155], v[224:227], v[72:75]
	v_mfma_f32_16x16x32_bf16 v[124:127], v[148:151], v[204:207], v[124:127]
	v_mfma_f32_16x16x32_bf16 v[120:123], v[156:159], v[204:207], v[120:123]
	v_mfma_f32_16x16x32_bf16 v[108:111], v[148:151], v[212:215], v[108:111]
	v_mfma_f32_16x16x32_bf16 v[104:107], v[156:159], v[212:215], v[104:107]
	v_mfma_f32_16x16x32_bf16 v[92:95], v[148:151], v[220:223], v[92:95]
	v_mfma_f32_16x16x32_bf16 v[88:91], v[156:159], v[220:223], v[88:91]
	v_mfma_f32_16x16x32_bf16 v[76:79], v[148:151], v[228:231], v[76:79]
	v_mfma_f32_16x16x32_bf16 v[72:75], v[156:159], v[228:231], v[72:75]
	s_setprio 0
	s_setprio 1
	v_mfma_f32_16x16x32_bf16 v[116:119], v[184:187], v[200:203], v[116:119]
	v_mfma_f32_16x16x32_bf16 v[112:115], v[192:195], v[200:203], v[112:115]
	v_mfma_f32_16x16x32_bf16 v[100:103], v[184:187], v[208:211], v[100:103]
	v_mfma_f32_16x16x32_bf16 v[96:99], v[192:195], v[208:211], v[96:99]
	v_mfma_f32_16x16x32_bf16 v[84:87], v[184:187], v[216:219], v[84:87]
	v_mfma_f32_16x16x32_bf16 v[80:83], v[192:195], v[216:219], v[80:83]
	v_mfma_f32_16x16x32_bf16 v[68:71], v[184:187], v[224:227], v[68:71]
	v_mfma_f32_16x16x32_bf16 v[64:67], v[192:195], v[224:227], v[64:67]
	v_mfma_f32_16x16x32_bf16 v[116:119], v[188:191], v[204:207], v[116:119]
	v_mfma_f32_16x16x32_bf16 v[112:115], v[196:199], v[204:207], v[112:115]
	v_mfma_f32_16x16x32_bf16 v[100:103], v[188:191], v[212:215], v[100:103]
	v_mfma_f32_16x16x32_bf16 v[96:99], v[196:199], v[212:215], v[96:99]
	v_mfma_f32_16x16x32_bf16 v[84:87], v[188:191], v[220:223], v[84:87]
	v_mfma_f32_16x16x32_bf16 v[80:83], v[196:199], v[220:223], v[80:83]
	v_mfma_f32_16x16x32_bf16 v[68:71], v[188:191], v[228:231], v[68:71]
	v_mfma_f32_16x16x32_bf16 v[64:67], v[196:199], v[228:231], v[64:67]
	s_barrier
	s_setprio 0
	s_mov_b32 m0, s47
	s_add_u32 s0, s0, 0x40080
	ds_read_b128 v[200:203], v165 offset:49152
	ds_read_b128 v[204:207], v165 offset:50176
	ds_read_b128 v[208:211], v165 offset:51200
	ds_read_b128 v[212:215], v165 offset:52224
	ds_read_b128 v[216:219], v165 offset:53248
	ds_read_b128 v[220:223], v165 offset:54272
	ds_read_b128 v[224:227], v165 offset:55296
	ds_read_b128 v[228:231], v165 offset:56320
	global_load_lds_dwordx4 v130, s[98:99]
	s_mov_b32 m0, s48
	s_addc_u32 s1, s1, 0
	global_load_lds_dwordx4 v134, s[98:99]
	s_mov_b32 m0, s51
	s_nop 0
	global_load_lds_dwordx4 v130, s[0:1]
	s_mov_b32 m0, s52
	s_nop 0
	global_load_lds_dwordx4 v134, s[0:1]
	s_mov_b32 m0, s49
	s_nop 0
	global_load_lds_dwordx4 v128, s[100:101]
	s_mov_b32 m0, s50
	s_nop 0
	global_load_lds_dwordx4 v132, s[100:101]
	s_waitcnt vmcnt(8)
	s_waitcnt lgkmcnt(0)
	s_setprio 1
	s_barrier
	v_mfma_f32_16x16x32_bf16 v[60:63], v[144:147], v[200:203], v[60:63]
	v_mfma_f32_16x16x32_bf16 v[56:59], v[152:155], v[200:203], v[56:59]
	v_mfma_f32_16x16x32_bf16 v[44:47], v[144:147], v[208:211], v[44:47]
	v_mfma_f32_16x16x32_bf16 v[40:43], v[152:155], v[208:211], v[40:43]
	v_mfma_f32_16x16x32_bf16 v[28:31], v[144:147], v[216:219], v[28:31]
	v_mfma_f32_16x16x32_bf16 v[24:27], v[152:155], v[216:219], v[24:27]
	v_mfma_f32_16x16x32_bf16 v[12:15], v[144:147], v[224:227], v[12:15]
	v_mfma_f32_16x16x32_bf16 v[8:11], v[152:155], v[224:227], v[8:11]
	v_mfma_f32_16x16x32_bf16 v[60:63], v[148:151], v[204:207], v[60:63]
	v_mfma_f32_16x16x32_bf16 v[56:59], v[156:159], v[204:207], v[56:59]
	v_mfma_f32_16x16x32_bf16 v[44:47], v[148:151], v[212:215], v[44:47]
	v_mfma_f32_16x16x32_bf16 v[40:43], v[156:159], v[212:215], v[40:43]
	v_mfma_f32_16x16x32_bf16 v[28:31], v[148:151], v[220:223], v[28:31]
	v_mfma_f32_16x16x32_bf16 v[24:27], v[156:159], v[220:223], v[24:27]
	v_mfma_f32_16x16x32_bf16 v[12:15], v[148:151], v[228:231], v[12:15]
	v_mfma_f32_16x16x32_bf16 v[8:11], v[156:159], v[228:231], v[8:11]
	s_setprio 0
	s_setprio 1
	v_mfma_f32_16x16x32_bf16 v[52:55], v[184:187], v[200:203], v[52:55]
	v_mfma_f32_16x16x32_bf16 v[48:51], v[192:195], v[200:203], v[48:51]
	v_mfma_f32_16x16x32_bf16 v[36:39], v[184:187], v[208:211], v[36:39]
	v_mfma_f32_16x16x32_bf16 v[32:35], v[192:195], v[208:211], v[32:35]
	v_mfma_f32_16x16x32_bf16 v[20:23], v[184:187], v[216:219], v[20:23]
	v_mfma_f32_16x16x32_bf16 v[16:19], v[192:195], v[216:219], v[16:19]
	v_mfma_f32_16x16x32_bf16 v[4:7], v[184:187], v[224:227], v[4:7]
	v_mfma_f32_16x16x32_bf16 v[0:3], v[192:195], v[224:227], v[0:3]
	v_mfma_f32_16x16x32_bf16 v[52:55], v[188:191], v[204:207], v[52:55]
	v_mfma_f32_16x16x32_bf16 v[48:51], v[196:199], v[204:207], v[48:51]
	v_mfma_f32_16x16x32_bf16 v[36:39], v[188:191], v[212:215], v[36:39]
	v_mfma_f32_16x16x32_bf16 v[32:35], v[196:199], v[212:215], v[32:35]
	v_mfma_f32_16x16x32_bf16 v[20:23], v[188:191], v[220:223], v[20:23]
	v_mfma_f32_16x16x32_bf16 v[16:19], v[196:199], v[220:223], v[16:19]
	v_mfma_f32_16x16x32_bf16 v[4:7], v[188:191], v[228:231], v[4:7]
	v_mfma_f32_16x16x32_bf16 v[0:3], v[196:199], v[228:231], v[0:3]
	s_barrier
	s_setprio 0
	s_add_i32 s68, s68, 2
	s_add_u32 s66, s66, 0x100
	s_addc_u32 s67, s67, 0
	s_add_u32 s4, s4, 0x100
	s_addc_u32 s5, s5, 0
	s_cmp_gt_u32 s68, 13
	s_cbranch_scc0 .LBB0_1179
	s_and_b64 vcc, exec, s[18:19]
	s_cbranch_vccz .LBB0_1182
	s_barrier

; #define PG8_STAGE(bufoff, gbase, voff) do { _Pragma("unroll") for (int _i = 0; _i < 2; ++_i) \
;         __builtin_amdgcn_global_load_lds((const unsigned*)((const char*)(gbase) + (voff)[_i]), (PG8_LAS unsigned*)(lds + (bufoff) + ldsw + _i * 8192), 16, 0, 0); } while (0)
; #define PG8_LDA(dst, b, h) do { _Pragma("unroll") for (int m = 0; m < 4; ++m) _Pragma("unroll") for (int k = 0; k < 2; ++k) dst[m][k] = *(const PG8_LAS bf16x8*)(lds + PG8_SA(b, h) + aoff + m * 2048 + k * 1024); } while (0)
; #define PG8_LDB(dst, b, h) do { _Pragma("unroll") for (int n = 0; n < 2; ++n) _Pragma("unroll") for (int k = 0; k < 2; ++k) dst[n][k] = *(const PG8_LAS bf16x8*)(lds + PG8_SB(b, h) + boff + n * 2048 + k * 1024); } while (0)
; #define PG8_MMA(ai, bj, At, Bt) do { __builtin_amdgcn_s_setprio(1); _Pragma("unroll") for (int m = 0; m < 4; ++m) _Pragma("unroll") for (int n = 0; n < 2; ++n) _Pragma("unroll") for (int k = 0; k < 2; ++k) \
;         acc[ai][bj][m][n] = __builtin_amdgcn_mfma_f32_16x16x32_bf16(Bt[n][k], At[m][k], acc[ai][bj][m][n], 0, 0, 0); __builtin_amdgcn_s_setprio(0); } while (0)
; #define PG8_WAIT_V(n) asm volatile("s_waitcnt vmcnt(" #n ")" ::: "memory")
; #define PG8_BAR __builtin_amdgcn_s_barrier()
; template <class Epi, class Sched, bool ALIGN_EPI = false, bool SP2 = false>
; __device__ __forceinline__ void gemm_phase(PG8_LAS unsigned char* lds, const Gemm g, const Sched& S, const Epi& E, const int tid_arg) {
;     ...
;         for (int t = 0; t < nt; t += 2) {
;             const bool last = (t == nt - 2);
;             const char* a1 = cA + (size_t)(t + 1) * kstep;
;             const char* a2 = last ? nA : cA + (size_t)(t + 2) * kstep; const char* b2 = last ? nB : cB + (size_t)(t + 2) * kstep;
;             const char* a3 = a2 + kstep; const char* b3 = b2 + kstep;
;             if (last && has_next) S.a_ready(nxt);
;             if constexpr (SP2) {
;             PG8_LDB(B0, 0, 0); PG8_LDB(B1, 0, 1); PG8_SCHED; PG8_LDA(At, 0, 0); PG8_STAGE(PG8_SA(1, 1), a1 + hstep, voffA);
;             PG8_WAIT_V(8); PG8_WAIT_L(0); PG8_BAR; PG8_MMA(0, 0, At, B0); PG8_MMA(0, 1, At, B1); PG8_BAR; PG8_SCHED;
;             PG8_LDA(At, 0, 1); PG8_STAGE(PG8_SB(0, 0), b2, voffB); PG8_STAGE(PG8_SB(0, 1), b2 + hstep, voffB); PG8_STAGE(PG8_SA(0, 0), a2, voffA);
;             PG8_WAIT_V(8); PG8_WAIT_L(0); PG8_BAR; PG8_MMA(1, 0, At, B0); PG8_MMA(1, 1, At, B1); PG8_BAR; PG8_SCHED;
.LBB0_1459:
	ds_read_b128 v[144:147], v151
	ds_read_b128 v[168:171], v152
	ds_read_b128 v[172:175], v153
	ds_read_b128 v[176:179], v154
	ds_read_b128 v[180:183], v155
	ds_read_b128 v[184:187], v156
	ds_read_b128 v[188:191], v157
	ds_read_b128 v[192:195], v158
	s_add_u32 s0, s28, 0xfffc0080
	s_addc_u32 s1, s29, -1
	s_cmp_eq_u32 s59, 12
	s_cselect_b32 s31, s21, s1
	s_cselect_b32 s30, s27, s0
	s_cselect_b32 s1, s19, s58
	s_cselect_b32 s0, s56, s57
	s_mov_b32 m0, s53
	ds_read_b128 v[196:199], v150
	ds_read_b128 v[200:203], v150 offset:1024
	ds_read_b128 v[204:207], v150 offset:2048
	ds_read_b128 v[208:211], v150 offset:3072
	ds_read_b128 v[212:215], v150 offset:4096
	ds_read_b128 v[216:219], v150 offset:5120
	ds_read_b128 v[220:223], v150 offset:6144
	ds_read_b128 v[224:227], v150 offset:7168
	global_load_lds_dwordx4 v138, s[28:29]
	s_mov_b32 m0, s54
	s_nop 0
	global_load_lds_dwordx4 v136, s[28:29]
	s_waitcnt vmcnt(8)
	s_waitcnt lgkmcnt(0)
	s_setprio 1
	s_barrier
	v_mfma_f32_16x16x32_bf16 v[124:127], v[144:147], v[196:199], v[124:127]
	v_mfma_f32_16x16x32_bf16 v[120:123], v[172:175], v[196:199], v[120:123]
	v_mfma_f32_16x16x32_bf16 v[108:111], v[144:147], v[204:207], v[108:111]
	v_mfma_f32_16x16x32_bf16 v[104:107], v[172:175], v[204:207], v[104:107]
	v_mfma_f32_16x16x32_bf16 v[92:95], v[144:147], v[212:215], v[92:95]
	v_mfma_f32_16x16x32_bf16 v[88:91], v[172:175], v[212:215], v[88:91]
	v_mfma_f32_16x16x32_bf16 v[76:79], v[144:147], v[220:223], v[76:79]
	v_mfma_f32_16x16x32_bf16 v[72:75], v[172:175], v[220:223], v[72:75]
	v_mfma_f32_16x16x32_bf16 v[124:127], v[168:171], v[200:203], v[124:127]
	v_mfma_f32_16x16x32_bf16 v[120:123], v[176:179], v[200:203], v[120:123]
	v_mfma_f32_16x16x32_bf16 v[108:111], v[168:171], v[208:211], v[108:111]
	v_mfma_f32_16x16x32_bf16 v[104:107], v[176:179], v[208:211], v[104:107]
	v_mfma_f32_16x16x32_bf16 v[92:95], v[168:171], v[216:219], v[92:95]
	v_mfma_f32_16x16x32_bf16 v[88:91], v[176:179], v[216:219], v[88:91]
	v_mfma_f32_16x16x32_bf16 v[76:79], v[168:171], v[224:227], v[76:79]
	v_mfma_f32_16x16x32_bf16 v[72:75], v[176:179], v[224:227], v[72:75]
	s_setprio 0
	s_setprio 1
	v_mfma_f32_16x16x32_bf16 v[116:119], v[180:183], v[196:199], v[116:119]
	v_mfma_f32_16x16x32_bf16 v[112:115], v[188:191], v[196:199], v[112:115]
	v_mfma_f32_16x16x32_bf16 v[100:103], v[180:183], v[204:207], v[100:103]
	v_mfma_f32_16x16x32_bf16 v[96:99], v[188:191], v[204:207], v[96:99]
	v_mfma_f32_16x16x32_bf16 v[84:87], v[180:183], v[212:215], v[84:87]
	v_mfma_f32_16x16x32_bf16 v[80:83], v[188:191], v[212:215], v[80:83]
	v_mfma_f32_16x16x32_bf16 v[68:71], v[180:183], v[220:223], v[68:71]
	v_mfma_f32_16x16x32_bf16 v[64:67], v[188:191], v[220:223], v[64:67]
	v_mfma_f32_16x16x32_bf16 v[116:119], v[184:187], v[200:203], v[116:119]
	v_mfma_f32_16x16x32_bf16 v[112:115], v[192:195], v[200:203], v[112:115]
	v_mfma_f32_16x16x32_bf16 v[100:103], v[184:187], v[208:211], v[100:103]
	v_mfma_f32_16x16x32_bf16 v[96:99], v[192:195], v[208:211], v[96:99]
	v_mfma_f32_16x16x32_bf16 v[84:87], v[184:187], v[216:219], v[84:87]
	v_mfma_f32_16x16x32_bf16 v[80:83], v[192:195], v[216:219], v[80:83]
	v_mfma_f32_16x16x32_bf16 v[68:71], v[184:187], v[224:227], v[68:71]
	v_mfma_f32_16x16x32_bf16 v[64:67], v[192:195], v[224:227], v[64:67]
	s_barrier
	s_setprio 0
	s_mov_b32 m0, s5
	s_add_u32 s98, s0, s14
	s_addc_u32 s99, s1, s15
	s_add_u32 s60, s0, 0x40000
	ds_read_b128 v[196:199], v150 offset:16384
	ds_read_b128 v[200:203], v150 offset:17408
	ds_read_b128 v[204:207], v150 offset:18432
	ds_read_b128 v[208:211], v150 offset:19456
	ds_read_b128 v[212:215], v150 offset:20480
	ds_read_b128 v[216:219], v150 offset:21504
	ds_read_b128 v[220:223], v150 offset:22528
	ds_read_b128 v[224:227], v150 offset:23552
	global_load_lds_dwordx4 v130, s[0:1]
	s_mov_b32 m0, s36
	s_addc_u32 s61, s1, 0
	global_load_lds_dwordx4 v134, s[0:1]
	s_mov_b32 m0, s37
	s_nop 0
	global_load_lds_dwordx4 v130, s[60:61]
	s_mov_b32 m0, s38
	s_nop 0
	global_load_lds_dwordx4 v134, s[60:61]
	s_add_u32 s100, s30, s14
	s_addc_u32 s101, s31, s15
	s_mov_b32 m0, s35
	s_nop 0
	global_load_lds_dwordx4 v128, s[30:31]
	s_mov_b32 m0, s39
	s_nop 0
	global_load_lds_dwordx4 v132, s[30:31]
	s_waitcnt vmcnt(8)
	s_waitcnt lgkmcnt(0)
	s_setprio 1
	s_barrier
	v_mfma_f32_16x16x32_bf16 v[60:63], v[144:147], v[196:199], v[60:63]
	v_mfma_f32_16x16x32_bf16 v[56:59], v[172:175], v[196:199], v[56:59]
	v_mfma_f32_16x16x32_bf16 v[44:47], v[144:147], v[204:207], v[44:47]
	v_mfma_f32_16x16x32_bf16 v[40:43], v[172:175], v[204:207], v[40:43]
	v_mfma_f32_16x16x32_bf16 v[28:31], v[144:147], v[212:215], v[28:31]
	v_mfma_f32_16x16x32_bf16 v[24:27], v[172:175], v[212:215], v[24:27]
	v_mfma_f32_16x16x32_bf16 v[12:15], v[144:147], v[220:223], v[12:15]
	v_mfma_f32_16x16x32_bf16 v[8:11], v[172:175], v[220:223], v[8:11]
	v_mfma_f32_16x16x32_bf16 v[60:63], v[168:171], v[200:203], v[60:63]
	v_mfma_f32_16x16x32_bf16 v[56:59], v[176:179], v[200:203], v[56:59]
	v_mfma_f32_16x16x32_bf16 v[44:47], v[168:171], v[208:211], v[44:47]
	v_mfma_f32_16x16x32_bf16 v[40:43], v[176:179], v[208:211], v[40:43]
	v_mfma_f32_16x16x32_bf16 v[28:31], v[168:171], v[216:219], v[28:31]
	v_mfma_f32_16x16x32_bf16 v[24:27], v[176:179], v[216:219], v[24:27]
	v_mfma_f32_16x16x32_bf16 v[12:15], v[168:171], v[224:227], v[12:15]
	v_mfma_f32_16x16x32_bf16 v[8:11], v[176:179], v[224:227], v[8:11]
	s_setprio 0
	s_setprio 1
	v_mfma_f32_16x16x32_bf16 v[52:55], v[180:183], v[196:199], v[52:55]
	v_mfma_f32_16x16x32_bf16 v[48:51], v[188:191], v[196:199], v[48:51]
	v_mfma_f32_16x16x32_bf16 v[36:39], v[180:183], v[204:207], v[36:39]
	v_mfma_f32_16x16x32_bf16 v[32:35], v[188:191], v[204:207], v[32:35]
	v_mfma_f32_16x16x32_bf16 v[20:23], v[180:183], v[212:215], v[20:23]
	v_mfma_f32_16x16x32_bf16 v[16:19], v[188:191], v[212:215], v[16:19]
	v_mfma_f32_16x16x32_bf16 v[4:7], v[180:183], v[220:223], v[4:7]
	v_mfma_f32_16x16x32_bf16 v[0:3], v[188:191], v[220:223], v[0:3]
	v_mfma_f32_16x16x32_bf16 v[52:55], v[184:187], v[200:203], v[52:55]
	v_mfma_f32_16x16x32_bf16 v[48:51], v[192:195], v[200:203], v[48:51]
	v_mfma_f32_16x16x32_bf16 v[36:39], v[184:187], v[208:211], v[36:39]
	v_mfma_f32_16x16x32_bf16 v[32:35], v[192:195], v[208:211], v[32:35]
	v_mfma_f32_16x16x32_bf16 v[20:23], v[184:187], v[216:219], v[20:23]
	v_mfma_f32_16x16x32_bf16 v[16:19], v[192:195], v[216:219], v[16:19]
	v_mfma_f32_16x16x32_bf16 v[4:7], v[184:187], v[224:227], v[4:7]
	v_mfma_f32_16x16x32_bf16 v[0:3], v[192:195], v[224:227], v[0:3]
	s_barrier
; #define PG8_STAGE(bufoff, gbase, voff) do { _Pragma("unroll") for (int _i = 0; _i < 2; ++_i) \
;         __builtin_amdgcn_global_load_lds((const unsigned*)((const char*)(gbase) + (voff)[_i]), (PG8_LAS unsigned*)(lds + (bufoff) + ldsw + _i * 8192), 16, 0, 0); } while (0)
; #define PG8_LDA(dst, b, h) do { _Pragma("unroll") for (int m = 0; m < 4; ++m) _Pragma("unroll") for (int k = 0; k < 2; ++k) dst[m][k] = *(const PG8_LAS bf16x8*)(lds + PG8_SA(b, h) + aoff + m * 2048 + k * 1024); } while (0)
; #define PG8_LDB(dst, b, h) do { _Pragma("unroll") for (int n = 0; n < 2; ++n) _Pragma("unroll") for (int k = 0; k < 2; ++k) dst[n][k] = *(const PG8_LAS bf16x8*)(lds + PG8_SB(b, h) + boff + n * 2048 + k * 1024); } while (0)
; #define PG8_MMA(ai, bj, At, Bt) do { __builtin_amdgcn_s_setprio(1); _Pragma("unroll") for (int m = 0; m < 4; ++m) _Pragma("unroll") for (int n = 0; n < 2; ++n) _Pragma("unroll") for (int k = 0; k < 2; ++k) \
;         acc[ai][bj][m][n] = __builtin_amdgcn_mfma_f32_16x16x32_bf16(Bt[n][k], At[m][k], acc[ai][bj][m][n], 0, 0, 0); __builtin_amdgcn_s_setprio(0); } while (0)
; #define PG8_WAIT_V(n) asm volatile("s_waitcnt vmcnt(" #n ")" ::: "memory")
; #define PG8_WAIT_L(n) asm volatile("s_waitcnt lgkmcnt(" #n ")" ::: "memory")
; #define PG8_BAR __builtin_amdgcn_s_barrier()
; #define PG8_SCHED __builtin_amdgcn_sched_barrier(0)
; template <class Epi, class Sched, bool ALIGN_EPI = false, bool SP2 = false>
; __device__ __forceinline__ void gemm_phase(PG8_LAS unsigned char* lds, const Gemm g, const Sched& S, const Epi& E, const int tid_arg) {
;     ...
;             PG8_LDB(B0, 1, 0); PG8_LDB(B1, 1, 1); PG8_SCHED; PG8_LDA(At, 1, 0); PG8_STAGE(PG8_SA(0, 1), a2 + hstep, voffA);
;             PG8_WAIT_V(8); PG8_WAIT_L(0); PG8_BAR; PG8_MMA(0, 0, At, B0); PG8_MMA(0, 1, At, B1); PG8_BAR; PG8_SCHED;
;             PG8_LDA(At, 1, 1); PG8_STAGE(PG8_SB(1, 0), b3, voffB); PG8_STAGE(PG8_SB(1, 1), b3 + hstep, voffB); PG8_STAGE(PG8_SA(1, 0), a3, voffA);
;             PG8_WAIT_V(8); PG8_WAIT_L(0); PG8_BAR; PG8_MMA(1, 0, At, B0); PG8_MMA(1, 1, At, B1); PG8_BAR; PG8_SCHED;
	s_setprio 0
	ds_read_b128 v[144:147], v159
	ds_read_b128 v[168:171], v160
	ds_read_b128 v[172:175], v161
	ds_read_b128 v[176:179], v162
	ds_read_b128 v[180:183], v163
	ds_read_b128 v[184:187], v164
	ds_read_b128 v[188:191], v165
	ds_read_b128 v[192:195], v166
	s_add_u32 s30, s30, 0x40000
	s_addc_u32 s31, s31, 0
	s_mov_b32 m0, s40
	ds_read_b128 v[196:199], v150 offset:32768
	ds_read_b128 v[200:203], v150 offset:33792
	ds_read_b128 v[204:207], v150 offset:34816
	ds_read_b128 v[208:211], v150 offset:35840
	ds_read_b128 v[212:215], v150 offset:36864
	ds_read_b128 v[216:219], v150 offset:37888
	ds_read_b128 v[220:223], v150 offset:38912
	ds_read_b128 v[224:227], v150 offset:39936
	global_load_lds_dwordx4 v128, s[30:31]
	s_mov_b32 m0, s41
	s_nop 0
	global_load_lds_dwordx4 v132, s[30:31]
	s_waitcnt vmcnt(8)
	s_waitcnt lgkmcnt(0)
	s_setprio 1
	s_barrier
	v_mfma_f32_16x16x32_bf16 v[124:127], v[144:147], v[196:199], v[124:127]
	v_mfma_f32_16x16x32_bf16 v[120:123], v[172:175], v[196:199], v[120:123]
	v_mfma_f32_16x16x32_bf16 v[108:111], v[144:147], v[204:207], v[108:111]
	v_mfma_f32_16x16x32_bf16 v[104:107], v[172:175], v[204:207], v[104:107]
	v_mfma_f32_16x16x32_bf16 v[92:95], v[144:147], v[212:215], v[92:95]
	v_mfma_f32_16x16x32_bf16 v[88:91], v[172:175], v[212:215], v[88:91]
	v_mfma_f32_16x16x32_bf16 v[76:79], v[144:147], v[220:223], v[76:79]
	v_mfma_f32_16x16x32_bf16 v[72:75], v[172:175], v[220:223], v[72:75]
	v_mfma_f32_16x16x32_bf16 v[124:127], v[168:171], v[200:203], v[124:127]
	v_mfma_f32_16x16x32_bf16 v[120:123], v[176:179], v[200:203], v[120:123]
	v_mfma_f32_16x16x32_bf16 v[108:111], v[168:171], v[208:211], v[108:111]
	v_mfma_f32_16x16x32_bf16 v[104:107], v[176:179], v[208:211], v[104:107]
	v_mfma_f32_16x16x32_bf16 v[92:95], v[168:171], v[216:219], v[92:95]
	v_mfma_f32_16x16x32_bf16 v[88:91], v[176:179], v[216:219], v[88:91]
	v_mfma_f32_16x16x32_bf16 v[76:79], v[168:171], v[224:227], v[76:79]
	v_mfma_f32_16x16x32_bf16 v[72:75], v[176:179], v[224:227], v[72:75]
	s_setprio 0
	s_setprio 1
	v_mfma_f32_16x16x32_bf16 v[116:119], v[180:183], v[196:199], v[116:119]
	v_mfma_f32_16x16x32_bf16 v[112:115], v[188:191], v[196:199], v[112:115]
	v_mfma_f32_16x16x32_bf16 v[100:103], v[180:183], v[204:207], v[100:103]
	v_mfma_f32_16x16x32_bf16 v[96:99], v[188:191], v[204:207], v[96:99]
	v_mfma_f32_16x16x32_bf16 v[84:87], v[180:183], v[212:215], v[84:87]
	v_mfma_f32_16x16x32_bf16 v[80:83], v[188:191], v[212:215], v[80:83]
	v_mfma_f32_16x16x32_bf16 v[68:71], v[180:183], v[220:223], v[68:71]
	v_mfma_f32_16x16x32_bf16 v[64:67], v[188:191], v[220:223], v[64:67]
	v_mfma_f32_16x16x32_bf16 v[116:119], v[184:187], v[200:203], v[116:119]
	v_mfma_f32_16x16x32_bf16 v[112:115], v[192:195], v[200:203], v[112:115]
	v_mfma_f32_16x16x32_bf16 v[100:103], v[184:187], v[208:211], v[100:103]
	v_mfma_f32_16x16x32_bf16 v[96:99], v[192:195], v[208:211], v[96:99]
	v_mfma_f32_16x16x32_bf16 v[84:87], v[184:187], v[216:219], v[84:87]
	v_mfma_f32_16x16x32_bf16 v[80:83], v[192:195], v[216:219], v[80:83]
	v_mfma_f32_16x16x32_bf16 v[68:71], v[184:187], v[224:227], v[68:71]
	v_mfma_f32_16x16x32_bf16 v[64:67], v[192:195], v[224:227], v[64:67]
	s_barrier
	s_setprio 0
	s_mov_b32 m0, s45
	s_add_u32 s0, s0, 0x40080
	ds_read_b128 v[196:199], v150 offset:49152
	ds_read_b128 v[200:203], v150 offset:50176
	ds_read_b128 v[204:207], v150 offset:51200
	ds_read_b128 v[208:211], v150 offset:52224
	ds_read_b128 v[212:215], v150 offset:53248
	ds_read_b128 v[216:219], v150 offset:54272
	ds_read_b128 v[220:223], v150 offset:55296
	ds_read_b128 v[224:227], v150 offset:56320
	global_load_lds_dwordx4 v130, s[98:99]
	s_mov_b32 m0, s46
	s_addc_u32 s1, s1, 0
	global_load_lds_dwordx4 v134, s[98:99]
	s_mov_b32 m0, s49
	s_nop 0
	global_load_lds_dwordx4 v130, s[0:1]
	s_mov_b32 m0, s50
	s_nop 0
	global_load_lds_dwordx4 v134, s[0:1]
	s_mov_b32 m0, s47
	s_nop 0
	global_load_lds_dwordx4 v128, s[100:101]
	s_mov_b32 m0, s48
	s_nop 0
	global_load_lds_dwordx4 v132, s[100:101]
	s_waitcnt vmcnt(8)
	s_waitcnt lgkmcnt(0)
	s_setprio 1
	s_barrier
	v_mfma_f32_16x16x32_bf16 v[60:63], v[144:147], v[196:199], v[60:63]
	v_mfma_f32_16x16x32_bf16 v[56:59], v[172:175], v[196:199], v[56:59]
	v_mfma_f32_16x16x32_bf16 v[44:47], v[144:147], v[204:207], v[44:47]
	v_mfma_f32_16x16x32_bf16 v[40:43], v[172:175], v[204:207], v[40:43]
	v_mfma_f32_16x16x32_bf16 v[28:31], v[144:147], v[212:215], v[28:31]
	v_mfma_f32_16x16x32_bf16 v[24:27], v[172:175], v[212:215], v[24:27]
	v_mfma_f32_16x16x32_bf16 v[12:15], v[144:147], v[220:223], v[12:15]
	v_mfma_f32_16x16x32_bf16 v[8:11], v[172:175], v[220:223], v[8:11]
	v_mfma_f32_16x16x32_bf16 v[60:63], v[168:171], v[200:203], v[60:63]
	v_mfma_f32_16x16x32_bf16 v[56:59], v[176:179], v[200:203], v[56:59]
	v_mfma_f32_16x16x32_bf16 v[44:47], v[168:171], v[208:211], v[44:47]
	v_mfma_f32_16x16x32_bf16 v[40:43], v[176:179], v[208:211], v[40:43]
	v_mfma_f32_16x16x32_bf16 v[28:31], v[168:171], v[216:219], v[28:31]
	v_mfma_f32_16x16x32_bf16 v[24:27], v[176:179], v[216:219], v[24:27]
	v_mfma_f32_16x16x32_bf16 v[12:15], v[168:171], v[224:227], v[12:15]
	v_mfma_f32_16x16x32_bf16 v[8:11], v[176:179], v[224:227], v[8:11]
	s_setprio 0
	s_setprio 1
	v_mfma_f32_16x16x32_bf16 v[52:55], v[180:183], v[196:199], v[52:55]
	v_mfma_f32_16x16x32_bf16 v[48:51], v[188:191], v[196:199], v[48:51]
	v_mfma_f32_16x16x32_bf16 v[36:39], v[180:183], v[204:207], v[36:39]
	v_mfma_f32_16x16x32_bf16 v[32:35], v[188:191], v[204:207], v[32:35]
	v_mfma_f32_16x16x32_bf16 v[20:23], v[180:183], v[212:215], v[20:23]
	v_mfma_f32_16x16x32_bf16 v[16:19], v[188:191], v[212:215], v[16:19]
	v_mfma_f32_16x16x32_bf16 v[4:7], v[180:183], v[220:223], v[4:7]
	v_mfma_f32_16x16x32_bf16 v[0:3], v[188:191], v[220:223], v[0:3]
	v_mfma_f32_16x16x32_bf16 v[52:55], v[184:187], v[200:203], v[52:55]
	v_mfma_f32_16x16x32_bf16 v[48:51], v[192:195], v[200:203], v[48:51]
	v_mfma_f32_16x16x32_bf16 v[36:39], v[184:187], v[208:211], v[36:39]
	v_mfma_f32_16x16x32_bf16 v[32:35], v[192:195], v[208:211], v[32:35]
	v_mfma_f32_16x16x32_bf16 v[20:23], v[184:187], v[216:219], v[20:23]
	v_mfma_f32_16x16x32_bf16 v[16:19], v[192:195], v[216:219], v[16:19]
	v_mfma_f32_16x16x32_bf16 v[4:7], v[184:187], v[224:227], v[4:7]
	v_mfma_f32_16x16x32_bf16 v[0:3], v[192:195], v[224:227], v[0:3]
	s_barrier
	s_setprio 0
	s_add_i32 s59, s59, 2
	s_add_u32 s57, s57, 0x100
	s_addc_u32 s58, s58, 0
	s_add_u32 s28, s28, 0x100
	s_addc_u32 s29, s29, 0
	s_cmp_gt_u32 s59, 13
	s_cbranch_scc0 .LBB0_1459
	s_and_b64 vcc, exec, s[16:17]
	s_cbranch_vccz .LBB0_1462
	s_barrier

; #define PG8_STAGE(bufoff, gbase, voff) do { _Pragma("unroll") for (int _i = 0; _i < 2; ++_i) \
;         __builtin_amdgcn_global_load_lds((const unsigned*)((const char*)(gbase) + (voff)[_i]), (PG8_LAS unsigned*)(lds + (bufoff) + ldsw + _i * 8192), 16, 0, 0); } while (0)
; #define PG8_LDA(dst, b, h) do { _Pragma("unroll") for (int m = 0; m < 4; ++m) _Pragma("unroll") for (int k = 0; k < 2; ++k) dst[m][k] = *(const PG8_LAS bf16x8*)(lds + PG8_SA(b, h) + aoff + m * 2048 + k * 1024); } while (0)
; #define PG8_LDB(dst, b, h) do { _Pragma("unroll") for (int n = 0; n < 2; ++n) _Pragma("unroll") for (int k = 0; k < 2; ++k) dst[n][k] = *(const PG8_LAS bf16x8*)(lds + PG8_SB(b, h) + boff + n * 2048 + k * 1024); } while (0)
; #define PG8_MMA(ai, bj, At, Bt) do { __builtin_amdgcn_s_setprio(1); _Pragma("unroll") for (int m = 0; m < 4; ++m) _Pragma("unroll") for (int n = 0; n < 2; ++n) _Pragma("unroll") for (int k = 0; k < 2; ++k) \
;         acc[ai][bj][m][n] = __builtin_amdgcn_mfma_f32_16x16x32_bf16(Bt[n][k], At[m][k], acc[ai][bj][m][n], 0, 0, 0); __builtin_amdgcn_s_setprio(0); } while (0)
; #define PG8_WAIT_V(n) asm volatile("s_waitcnt vmcnt(" #n ")" ::: "memory")
; #define PG8_BAR __builtin_amdgcn_s_barrier()
; template <class Epi, class Sched, bool ALIGN_EPI = false, bool SP2 = false>
; __device__ __forceinline__ void gemm_phase(PG8_LAS unsigned char* lds, const Gemm g, const Sched& S, const Epi& E, const int tid_arg) {
;     ...
;         for (int t = 0; t < nt; t += 2) {
;             const bool last = (t == nt - 2);
;             const char* a1 = cA + (size_t)(t + 1) * kstep;
;             const char* a2 = last ? nA : cA + (size_t)(t + 2) * kstep; const char* b2 = last ? nB : cB + (size_t)(t + 2) * kstep;
;             const char* a3 = a2 + kstep; const char* b3 = b2 + kstep;
;             if (last && has_next) S.a_ready(nxt);
;             if constexpr (SP2) {
;             PG8_LDB(B0, 0, 0); PG8_LDB(B1, 0, 1); PG8_SCHED; PG8_LDA(At, 0, 0); PG8_STAGE(PG8_SA(1, 1), a1 + hstep, voffA);
;             PG8_WAIT_V(8); PG8_WAIT_L(0); PG8_BAR; PG8_MMA(0, 0, At, B0); PG8_MMA(0, 1, At, B1); PG8_BAR; PG8_SCHED;
;             PG8_LDA(At, 0, 1); PG8_STAGE(PG8_SB(0, 0), b2, voffB); PG8_STAGE(PG8_SB(0, 1), b2 + hstep, voffB); PG8_STAGE(PG8_SA(0, 0), a2, voffA);
;             PG8_WAIT_V(8); PG8_WAIT_L(0); PG8_BAR; PG8_MMA(1, 0, At, B0); PG8_MMA(1, 1, At, B1); PG8_BAR; PG8_SCHED;
.LBB0_1547:
	ds_read_b128 v[72:75], v207
	ds_read_b128 v[100:103], v208
	ds_read_b128 v[136:139], v209
	ds_read_b128 v[140:143], v210
	ds_read_b128 v[144:147], v211
	ds_read_b128 v[148:151], v212
	ds_read_b128 v[152:155], v213
	ds_read_b128 v[156:159], v214
	s_add_u32 s6, s4, 0x100
	s_addc_u32 s7, s5, 0
	s_cmp_eq_u32 s78, 12
	s_cselect_b32 s11, s13, s7
	s_cselect_b32 s10, s31, s6
	s_cselect_b32 s1, s29, s75
	s_cselect_b32 s0, s42, s43
	s_mov_b32 m0, s71
	ds_read_b128 v[160:163], v206
	ds_read_b128 v[164:167], v206 offset:1024
	ds_read_b128 v[168:171], v206 offset:2048
	ds_read_b128 v[172:175], v206 offset:3072
	ds_read_b128 v[176:179], v206 offset:4096
	ds_read_b128 v[180:183], v206 offset:5120
	ds_read_b128 v[226:229], v206 offset:6144
	ds_read_b128 v[230:233], v206 offset:7168
	global_load_lds_dwordx4 v196, s[4:5]
	s_mov_b32 m0, s72
	s_nop 0
	global_load_lds_dwordx4 v194, s[4:5]
	s_waitcnt vmcnt(8)
	s_waitcnt lgkmcnt(0)
	s_setprio 1
	s_barrier
	v_mfma_f32_16x16x32_bf16 v[132:135], v[72:75], v[160:163], v[132:135]
	v_mfma_f32_16x16x32_bf16 v[60:63], v[136:139], v[160:163], v[60:63]
	v_mfma_f32_16x16x32_bf16 v[124:127], v[72:75], v[168:171], v[124:127]
	v_mfma_f32_16x16x32_bf16 v[52:55], v[136:139], v[168:171], v[52:55]
	v_mfma_f32_16x16x32_bf16 v[116:119], v[72:75], v[176:179], v[116:119]
	v_mfma_f32_16x16x32_bf16 v[44:47], v[136:139], v[176:179], v[44:47]
	v_mfma_f32_16x16x32_bf16 v[108:111], v[72:75], v[226:229], v[108:111]
	v_mfma_f32_16x16x32_bf16 v[36:39], v[136:139], v[226:229], v[36:39]
	v_mfma_f32_16x16x32_bf16 v[132:135], v[100:103], v[164:167], v[132:135]
	v_mfma_f32_16x16x32_bf16 v[60:63], v[140:143], v[164:167], v[60:63]
	v_mfma_f32_16x16x32_bf16 v[124:127], v[100:103], v[172:175], v[124:127]
	v_mfma_f32_16x16x32_bf16 v[52:55], v[140:143], v[172:175], v[52:55]
	v_mfma_f32_16x16x32_bf16 v[116:119], v[100:103], v[180:183], v[116:119]
	v_mfma_f32_16x16x32_bf16 v[44:47], v[140:143], v[180:183], v[44:47]
	v_mfma_f32_16x16x32_bf16 v[108:111], v[100:103], v[230:233], v[108:111]
	v_mfma_f32_16x16x32_bf16 v[36:39], v[140:143], v[230:233], v[36:39]
	s_setprio 0
	s_setprio 1
	v_mfma_f32_16x16x32_bf16 v[128:131], v[144:147], v[160:163], v[128:131]
	v_mfma_f32_16x16x32_bf16 v[56:59], v[152:155], v[160:163], v[56:59]
	v_mfma_f32_16x16x32_bf16 v[120:123], v[144:147], v[168:171], v[120:123]
	v_mfma_f32_16x16x32_bf16 v[48:51], v[152:155], v[168:171], v[48:51]
	v_mfma_f32_16x16x32_bf16 v[112:115], v[144:147], v[176:179], v[112:115]
	v_mfma_f32_16x16x32_bf16 v[40:43], v[152:155], v[176:179], v[40:43]
	v_mfma_f32_16x16x32_bf16 v[104:107], v[144:147], v[226:229], v[104:107]
	v_mfma_f32_16x16x32_bf16 v[32:35], v[152:155], v[226:229], v[32:35]
	v_mfma_f32_16x16x32_bf16 v[128:131], v[148:151], v[164:167], v[128:131]
	v_mfma_f32_16x16x32_bf16 v[56:59], v[156:159], v[164:167], v[56:59]
	v_mfma_f32_16x16x32_bf16 v[120:123], v[148:151], v[172:175], v[120:123]
	v_mfma_f32_16x16x32_bf16 v[48:51], v[156:159], v[172:175], v[48:51]
	v_mfma_f32_16x16x32_bf16 v[112:115], v[148:151], v[180:183], v[112:115]
	v_mfma_f32_16x16x32_bf16 v[40:43], v[156:159], v[180:183], v[40:43]
	v_mfma_f32_16x16x32_bf16 v[104:107], v[148:151], v[230:233], v[104:107]
	v_mfma_f32_16x16x32_bf16 v[32:35], v[156:159], v[230:233], v[32:35]
	s_barrier
	s_setprio 0
	s_mov_b32 m0, s39
	s_add_u32 s98, s0, s20
	s_addc_u32 s99, s1, s21
	s_add_u32 s4, s0, 0x40000
	ds_read_b128 v[160:163], v206 offset:16384
	ds_read_b128 v[164:167], v206 offset:17408
	ds_read_b128 v[168:171], v206 offset:18432
	ds_read_b128 v[172:175], v206 offset:19456
	ds_read_b128 v[176:179], v206 offset:20480
	ds_read_b128 v[180:183], v206 offset:21504
	ds_read_b128 v[226:229], v206 offset:22528
	ds_read_b128 v[230:233], v206 offset:23552
	global_load_lds_dwordx4 v188, s[0:1]
	s_mov_b32 m0, s41
	s_addc_u32 s5, s1, 0
	global_load_lds_dwordx4 v192, s[0:1]
	s_mov_b32 m0, s47
	s_nop 0
	global_load_lds_dwordx4 v188, s[4:5]
	s_mov_b32 m0, s48
	s_nop 0
	global_load_lds_dwordx4 v192, s[4:5]
	s_add_u32 s100, s10, s20
	s_addc_u32 s101, s11, s21
	s_mov_b32 m0, s46
	s_nop 0
	global_load_lds_dwordx4 v186, s[10:11]
	s_mov_b32 m0, s49
	s_nop 0
	global_load_lds_dwordx4 v190, s[10:11]
	s_waitcnt vmcnt(8)
	s_waitcnt lgkmcnt(0)
	s_setprio 1
	s_barrier
	v_mfma_f32_16x16x32_bf16 v[96:99], v[72:75], v[160:163], v[96:99]
	v_mfma_f32_16x16x32_bf16 v[28:31], v[136:139], v[160:163], v[28:31]
	v_mfma_f32_16x16x32_bf16 v[88:91], v[72:75], v[168:171], v[88:91]
	v_mfma_f32_16x16x32_bf16 v[20:23], v[136:139], v[168:171], v[20:23]
	v_mfma_f32_16x16x32_bf16 v[80:83], v[72:75], v[176:179], v[80:83]
	v_mfma_f32_16x16x32_bf16 v[12:15], v[136:139], v[176:179], v[12:15]
	v_mfma_f32_16x16x32_bf16 v[68:71], v[72:75], v[226:229], v[68:71]
	v_mfma_f32_16x16x32_bf16 v[4:7], v[136:139], v[226:229], v[4:7]
	v_mfma_f32_16x16x32_bf16 v[96:99], v[100:103], v[164:167], v[96:99]
	v_mfma_f32_16x16x32_bf16 v[28:31], v[140:143], v[164:167], v[28:31]
	v_mfma_f32_16x16x32_bf16 v[88:91], v[100:103], v[172:175], v[88:91]
	v_mfma_f32_16x16x32_bf16 v[20:23], v[140:143], v[172:175], v[20:23]
	v_mfma_f32_16x16x32_bf16 v[80:83], v[100:103], v[180:183], v[80:83]
	v_mfma_f32_16x16x32_bf16 v[12:15], v[140:143], v[180:183], v[12:15]
	v_mfma_f32_16x16x32_bf16 v[68:71], v[100:103], v[230:233], v[68:71]
	v_mfma_f32_16x16x32_bf16 v[4:7], v[140:143], v[230:233], v[4:7]
	s_setprio 0
	s_setprio 1
	v_mfma_f32_16x16x32_bf16 v[24:27], v[152:155], v[160:163], v[24:27]
	v_mfma_f32_16x16x32_bf16 v[84:87], v[144:147], v[168:171], v[84:87]
	v_mfma_f32_16x16x32_bf16 v[16:19], v[152:155], v[168:171], v[16:19]
	v_mfma_f32_16x16x32_bf16 v[76:79], v[144:147], v[176:179], v[76:79]
	v_mfma_f32_16x16x32_bf16 v[8:11], v[152:155], v[176:179], v[8:11]
	v_mfma_f32_16x16x32_bf16 v[64:67], v[144:147], v[226:229], v[64:67]
	v_mfma_f32_16x16x32_bf16 v[0:3], v[152:155], v[226:229], v[0:3]
	v_mfma_f32_16x16x32_bf16 v[72:75], v[144:147], v[160:163], v[92:95]
	v_mfma_f32_16x16x32_bf16 v[24:27], v[156:159], v[164:167], v[24:27]
	v_mfma_f32_16x16x32_bf16 v[84:87], v[148:151], v[172:175], v[84:87]
	v_mfma_f32_16x16x32_bf16 v[16:19], v[156:159], v[172:175], v[16:19]
	v_mfma_f32_16x16x32_bf16 v[76:79], v[148:151], v[180:183], v[76:79]
	v_mfma_f32_16x16x32_bf16 v[8:11], v[156:159], v[180:183], v[8:11]
	v_mfma_f32_16x16x32_bf16 v[64:67], v[148:151], v[230:233], v[64:67]
	v_mfma_f32_16x16x32_bf16 v[0:3], v[156:159], v[230:233], v[0:3]
	v_mfma_f32_16x16x32_bf16 v[72:75], v[148:151], v[164:167], v[72:75]
	s_barrier
; #define PG8_STAGE(bufoff, gbase, voff) do { _Pragma("unroll") for (int _i = 0; _i < 2; ++_i) \
;         __builtin_amdgcn_global_load_lds((const unsigned*)((const char*)(gbase) + (voff)[_i]), (PG8_LAS unsigned*)(lds + (bufoff) + ldsw + _i * 8192), 16, 0, 0); } while (0)
; #define PG8_LDA(dst, b, h) do { _Pragma("unroll") for (int m = 0; m < 4; ++m) _Pragma("unroll") for (int k = 0; k < 2; ++k) dst[m][k] = *(const PG8_LAS bf16x8*)(lds + PG8_SA(b, h) + aoff + m * 2048 + k * 1024); } while (0)
; #define PG8_LDB(dst, b, h) do { _Pragma("unroll") for (int n = 0; n < 2; ++n) _Pragma("unroll") for (int k = 0; k < 2; ++k) dst[n][k] = *(const PG8_LAS bf16x8*)(lds + PG8_SB(b, h) + boff + n * 2048 + k * 1024); } while (0)
; #define PG8_MMA(ai, bj, At, Bt) do { __builtin_amdgcn_s_setprio(1); _Pragma("unroll") for (int m = 0; m < 4; ++m) _Pragma("unroll") for (int n = 0; n < 2; ++n) _Pragma("unroll") for (int k = 0; k < 2; ++k) \
;         acc[ai][bj][m][n] = __builtin_amdgcn_mfma_f32_16x16x32_bf16(Bt[n][k], At[m][k], acc[ai][bj][m][n], 0, 0, 0); __builtin_amdgcn_s_setprio(0); } while (0)
; #define PG8_WAIT_V(n) asm volatile("s_waitcnt vmcnt(" #n ")" ::: "memory")
; #define PG8_WAIT_L(n) asm volatile("s_waitcnt lgkmcnt(" #n ")" ::: "memory")
; #define PG8_BAR __builtin_amdgcn_s_barrier()
; #define PG8_SCHED __builtin_amdgcn_sched_barrier(0)
; template <class Epi, class Sched, bool ALIGN_EPI = false, bool SP2 = false>
; __device__ __forceinline__ void gemm_phase(PG8_LAS unsigned char* lds, const Gemm g, const Sched& S, const Epi& E, const int tid_arg) {
;     ...
;             PG8_LDB(B0, 1, 0); PG8_LDB(B1, 1, 1); PG8_SCHED; PG8_LDA(At, 1, 0); PG8_STAGE(PG8_SA(0, 1), a2 + hstep, voffA);
;             PG8_WAIT_V(8); PG8_WAIT_L(0); PG8_BAR; PG8_MMA(0, 0, At, B0); PG8_MMA(0, 1, At, B1); PG8_BAR; PG8_SCHED;
;             PG8_LDA(At, 1, 1); PG8_STAGE(PG8_SB(1, 0), b3, voffB); PG8_STAGE(PG8_SB(1, 1), b3 + hstep, voffB); PG8_STAGE(PG8_SA(1, 0), a3, voffA);
;             PG8_WAIT_V(8); PG8_WAIT_L(0); PG8_BAR; PG8_MMA(1, 0, At, B0); PG8_MMA(1, 1, At, B1); PG8_BAR; PG8_SCHED;
	s_setprio 0
	ds_read_b128 v[92:95], v215
	ds_read_b128 v[100:103], v216
	ds_read_b128 v[136:139], v217
	ds_read_b128 v[140:143], v218
	ds_read_b128 v[144:147], v219
	ds_read_b128 v[148:151], v220
	ds_read_b128 v[152:155], v221
	ds_read_b128 v[156:159], v222
	s_add_u32 s4, s10, 0x40000
	s_addc_u32 s5, s11, 0
	s_mov_b32 m0, s50
	ds_read_b128 v[160:163], v206 offset:32768
	ds_read_b128 v[164:167], v206 offset:33792
	ds_read_b128 v[168:171], v206 offset:34816
	ds_read_b128 v[172:175], v206 offset:35840
	ds_read_b128 v[176:179], v206 offset:36864
	ds_read_b128 v[180:183], v206 offset:37888
	ds_read_b128 v[226:229], v206 offset:38912
	ds_read_b128 v[230:233], v206 offset:39936
	global_load_lds_dwordx4 v186, s[4:5]
	s_mov_b32 m0, s51
	s_nop 0
	global_load_lds_dwordx4 v190, s[4:5]
	s_waitcnt vmcnt(8)
	s_waitcnt lgkmcnt(0)
	s_setprio 1
	s_barrier
	v_mfma_f32_16x16x32_bf16 v[132:135], v[92:95], v[160:163], v[132:135]
	v_mfma_f32_16x16x32_bf16 v[60:63], v[136:139], v[160:163], v[60:63]
	v_mfma_f32_16x16x32_bf16 v[124:127], v[92:95], v[168:171], v[124:127]
	v_mfma_f32_16x16x32_bf16 v[52:55], v[136:139], v[168:171], v[52:55]
	v_mfma_f32_16x16x32_bf16 v[116:119], v[92:95], v[176:179], v[116:119]
	v_mfma_f32_16x16x32_bf16 v[44:47], v[136:139], v[176:179], v[44:47]
	v_mfma_f32_16x16x32_bf16 v[108:111], v[92:95], v[226:229], v[108:111]
	v_mfma_f32_16x16x32_bf16 v[36:39], v[136:139], v[226:229], v[36:39]
	v_mfma_f32_16x16x32_bf16 v[132:135], v[100:103], v[164:167], v[132:135]
	v_mfma_f32_16x16x32_bf16 v[60:63], v[140:143], v[164:167], v[60:63]
	v_mfma_f32_16x16x32_bf16 v[124:127], v[100:103], v[172:175], v[124:127]
	v_mfma_f32_16x16x32_bf16 v[52:55], v[140:143], v[172:175], v[52:55]
	v_mfma_f32_16x16x32_bf16 v[116:119], v[100:103], v[180:183], v[116:119]
	v_mfma_f32_16x16x32_bf16 v[44:47], v[140:143], v[180:183], v[44:47]
	v_mfma_f32_16x16x32_bf16 v[108:111], v[100:103], v[230:233], v[108:111]
	v_mfma_f32_16x16x32_bf16 v[36:39], v[140:143], v[230:233], v[36:39]
	s_setprio 0
	s_setprio 1
	v_mfma_f32_16x16x32_bf16 v[128:131], v[144:147], v[160:163], v[128:131]
	v_mfma_f32_16x16x32_bf16 v[56:59], v[152:155], v[160:163], v[56:59]
	v_mfma_f32_16x16x32_bf16 v[120:123], v[144:147], v[168:171], v[120:123]
	v_mfma_f32_16x16x32_bf16 v[48:51], v[152:155], v[168:171], v[48:51]
	v_mfma_f32_16x16x32_bf16 v[112:115], v[144:147], v[176:179], v[112:115]
	v_mfma_f32_16x16x32_bf16 v[40:43], v[152:155], v[176:179], v[40:43]
	v_mfma_f32_16x16x32_bf16 v[104:107], v[144:147], v[226:229], v[104:107]
	v_mfma_f32_16x16x32_bf16 v[32:35], v[152:155], v[226:229], v[32:35]
	v_mfma_f32_16x16x32_bf16 v[128:131], v[148:151], v[164:167], v[128:131]
	v_mfma_f32_16x16x32_bf16 v[56:59], v[156:159], v[164:167], v[56:59]
	v_mfma_f32_16x16x32_bf16 v[120:123], v[148:151], v[172:175], v[120:123]
	v_mfma_f32_16x16x32_bf16 v[48:51], v[156:159], v[172:175], v[48:51]
	v_mfma_f32_16x16x32_bf16 v[112:115], v[148:151], v[180:183], v[112:115]
	v_mfma_f32_16x16x32_bf16 v[40:43], v[156:159], v[180:183], v[40:43]
	v_mfma_f32_16x16x32_bf16 v[104:107], v[148:151], v[230:233], v[104:107]
	v_mfma_f32_16x16x32_bf16 v[32:35], v[156:159], v[230:233], v[32:35]
	s_barrier
	s_setprio 0
	s_mov_b32 m0, s60
	s_add_u32 s0, s0, 0x40080
	ds_read_b128 v[160:163], v206 offset:49152
	ds_read_b128 v[164:167], v206 offset:50176
	ds_read_b128 v[168:171], v206 offset:51200
	ds_read_b128 v[172:175], v206 offset:52224
	ds_read_b128 v[176:179], v206 offset:53248
	ds_read_b128 v[180:183], v206 offset:54272
	ds_read_b128 v[226:229], v206 offset:55296
	ds_read_b128 v[230:233], v206 offset:56320
	global_load_lds_dwordx4 v188, s[98:99]
	s_mov_b32 m0, s61
	s_addc_u32 s1, s1, 0
	global_load_lds_dwordx4 v192, s[98:99]
	s_mov_b32 m0, s64
	s_nop 0
	global_load_lds_dwordx4 v188, s[0:1]
	s_mov_b32 m0, s65
	s_nop 0
	global_load_lds_dwordx4 v192, s[0:1]
	s_mov_b32 m0, s62
	s_nop 0
	global_load_lds_dwordx4 v186, s[100:101]
	s_mov_b32 m0, s63
	s_nop 0
	global_load_lds_dwordx4 v190, s[100:101]
	s_waitcnt vmcnt(8)
	s_waitcnt lgkmcnt(0)
	s_setprio 1
	s_barrier
	v_mfma_f32_16x16x32_bf16 v[96:99], v[92:95], v[160:163], v[96:99]
	v_mfma_f32_16x16x32_bf16 v[28:31], v[136:139], v[160:163], v[28:31]
	v_mfma_f32_16x16x32_bf16 v[88:91], v[92:95], v[168:171], v[88:91]
	v_mfma_f32_16x16x32_bf16 v[20:23], v[136:139], v[168:171], v[20:23]
	v_mfma_f32_16x16x32_bf16 v[80:83], v[92:95], v[176:179], v[80:83]
	v_mfma_f32_16x16x32_bf16 v[12:15], v[136:139], v[176:179], v[12:15]
	v_mfma_f32_16x16x32_bf16 v[68:71], v[92:95], v[226:229], v[68:71]
	v_mfma_f32_16x16x32_bf16 v[4:7], v[136:139], v[226:229], v[4:7]
	v_mfma_f32_16x16x32_bf16 v[96:99], v[100:103], v[164:167], v[96:99]
	v_mfma_f32_16x16x32_bf16 v[28:31], v[140:143], v[164:167], v[28:31]
	v_mfma_f32_16x16x32_bf16 v[88:91], v[100:103], v[172:175], v[88:91]
	v_mfma_f32_16x16x32_bf16 v[20:23], v[140:143], v[172:175], v[20:23]
	v_mfma_f32_16x16x32_bf16 v[80:83], v[100:103], v[180:183], v[80:83]
	v_mfma_f32_16x16x32_bf16 v[12:15], v[140:143], v[180:183], v[12:15]
	v_mfma_f32_16x16x32_bf16 v[68:71], v[100:103], v[230:233], v[68:71]
	v_mfma_f32_16x16x32_bf16 v[4:7], v[140:143], v[230:233], v[4:7]
	s_setprio 0
	s_setprio 1
	v_mfma_f32_16x16x32_bf16 v[72:75], v[144:147], v[160:163], v[72:75]
	v_mfma_f32_16x16x32_bf16 v[92:95], v[148:151], v[164:167], v[72:75]
	v_mfma_f32_16x16x32_bf16 v[72:75], v[144:147], v[168:171], v[84:87]
	v_mfma_f32_16x16x32_bf16 v[24:27], v[152:155], v[160:163], v[24:27]
	v_mfma_f32_16x16x32_bf16 v[84:87], v[148:151], v[172:175], v[72:75]
	v_mfma_f32_16x16x32_bf16 v[16:19], v[152:155], v[168:171], v[16:19]
	v_mfma_f32_16x16x32_bf16 v[72:75], v[144:147], v[176:179], v[76:79]
	v_mfma_f32_16x16x32_bf16 v[8:11], v[152:155], v[176:179], v[8:11]
	v_mfma_f32_16x16x32_bf16 v[64:67], v[144:147], v[226:229], v[64:67]
	v_mfma_f32_16x16x32_bf16 v[0:3], v[152:155], v[226:229], v[0:3]
	v_mfma_f32_16x16x32_bf16 v[24:27], v[156:159], v[164:167], v[24:27]
	v_mfma_f32_16x16x32_bf16 v[16:19], v[156:159], v[172:175], v[16:19]
	v_mfma_f32_16x16x32_bf16 v[76:79], v[148:151], v[180:183], v[72:75]
	v_mfma_f32_16x16x32_bf16 v[8:11], v[156:159], v[180:183], v[8:11]
	v_mfma_f32_16x16x32_bf16 v[64:67], v[148:151], v[230:233], v[64:67]
	v_mfma_f32_16x16x32_bf16 v[0:3], v[156:159], v[230:233], v[0:3]
	s_barrier
	s_setprio 0
	s_add_i32 s78, s78, 2
	s_add_u32 s43, s43, 0x100
	s_addc_u32 s75, s75, 0
	s_cmp_gt_u32 s78, 13
	s_mov_b64 s[4:5], s[6:7]
	s_cbranch_scc0 .LBB0_1547
	s_and_b64 vcc, exec, s[22:23]
	s_cbranch_vccz .LBB0_1550
	s_barrier

; #define PG8_STAGE(bufoff, gbase, voff) do { _Pragma("unroll") for (int _i = 0; _i < 2; ++_i) \
;         __builtin_amdgcn_global_load_lds((const unsigned*)((const char*)(gbase) + (voff)[_i]), (PG8_LAS unsigned*)(lds + (bufoff) + ldsw + _i * 8192), 16, 0, 0); } while (0)
; #define PG8_LDA(dst, b, h) do { _Pragma("unroll") for (int m = 0; m < 4; ++m) _Pragma("unroll") for (int k = 0; k < 2; ++k) dst[m][k] = *(const PG8_LAS bf16x8*)(lds + PG8_SA(b, h) + aoff + m * 2048 + k * 1024); } while (0)
; #define PG8_LDB(dst, b, h) do { _Pragma("unroll") for (int n = 0; n < 2; ++n) _Pragma("unroll") for (int k = 0; k < 2; ++k) dst[n][k] = *(const PG8_LAS bf16x8*)(lds + PG8_SB(b, h) + boff + n * 2048 + k * 1024); } while (0)
; #define PG8_MMA(ai, bj, At, Bt) do { __builtin_amdgcn_s_setprio(1); _Pragma("unroll") for (int m = 0; m < 4; ++m) _Pragma("unroll") for (int n = 0; n < 2; ++n) _Pragma("unroll") for (int k = 0; k < 2; ++k) \
;         acc[ai][bj][m][n] = __builtin_amdgcn_mfma_f32_16x16x32_bf16(Bt[n][k], At[m][k], acc[ai][bj][m][n], 0, 0, 0); __builtin_amdgcn_s_setprio(0); } while (0)
; #define PG8_WAIT_V(n) asm volatile("s_waitcnt vmcnt(" #n ")" ::: "memory")
; #define PG8_BAR __builtin_amdgcn_s_barrier()
; template <class Epi, class Sched, bool ALIGN_EPI = false, bool SP2 = false>
; __device__ __forceinline__ void gemm_phase(PG8_LAS unsigned char* lds, const Gemm g, const Sched& S, const Epi& E, const int tid_arg) {
;     ...
;         for (int t = 0; t < nt; t += 2) {
;             const bool last = (t == nt - 2);
;             const char* a1 = cA + (size_t)(t + 1) * kstep;
;             const char* a2 = last ? nA : cA + (size_t)(t + 2) * kstep; const char* b2 = last ? nB : cB + (size_t)(t + 2) * kstep;
;             const char* a3 = a2 + kstep; const char* b3 = b2 + kstep;
;             if (last && has_next) S.a_ready(nxt);
;             if constexpr (SP2) {
;             PG8_LDB(B0, 0, 0); PG8_LDB(B1, 0, 1); PG8_SCHED; PG8_LDA(At, 0, 0); PG8_STAGE(PG8_SA(1, 1), a1 + hstep, voffA);
;             PG8_WAIT_V(8); PG8_WAIT_L(0); PG8_BAR; PG8_MMA(0, 0, At, B0); PG8_MMA(0, 1, At, B1); PG8_BAR; PG8_SCHED;
;             PG8_LDA(At, 0, 1); PG8_STAGE(PG8_SB(0, 0), b2, voffB); PG8_STAGE(PG8_SB(0, 1), b2 + hstep, voffB); PG8_STAGE(PG8_SA(0, 0), a2, voffA);
;             PG8_WAIT_V(8); PG8_WAIT_L(0); PG8_BAR; PG8_MMA(1, 0, At, B0); PG8_MMA(1, 1, At, B1); PG8_BAR; PG8_SCHED;
.LBB0_1733:
	ds_read_b128 v[144:147], v151
	ds_read_b128 v[168:171], v152
	ds_read_b128 v[172:175], v153
	ds_read_b128 v[176:179], v154
	ds_read_b128 v[180:183], v155
	ds_read_b128 v[184:187], v156
	ds_read_b128 v[188:191], v157
	ds_read_b128 v[192:195], v158
	s_add_u32 s22, s4, 0x100
	s_addc_u32 s23, s5, 0
	s_cmp_eq_u32 s57, 40
	s_cselect_b32 s25, s9, s23
	s_cselect_b32 s24, s8, s22
	s_cselect_b32 s1, s21, s56
	s_cselect_b32 s0, s20, s55
	s_mov_b32 m0, s48
	ds_read_b128 v[196:199], v150
	ds_read_b128 v[200:203], v150 offset:1024
	ds_read_b128 v[204:207], v150 offset:2048
	ds_read_b128 v[208:211], v150 offset:3072
	ds_read_b128 v[212:215], v150 offset:4096
	ds_read_b128 v[216:219], v150 offset:5120
	ds_read_b128 v[220:223], v150 offset:6144
	ds_read_b128 v[224:227], v150 offset:7168
	global_load_lds_dwordx4 v138, s[4:5]
	s_mov_b32 m0, s49
	s_nop 0
	global_load_lds_dwordx4 v136, s[4:5]
	s_waitcnt vmcnt(8)
	s_waitcnt lgkmcnt(0)
	s_setprio 1
	s_barrier
	v_mfma_f32_16x16x32_bf16 v[124:127], v[144:147], v[196:199], v[124:127]
	v_mfma_f32_16x16x32_bf16 v[120:123], v[172:175], v[196:199], v[120:123]
	v_mfma_f32_16x16x32_bf16 v[108:111], v[144:147], v[204:207], v[108:111]
	v_mfma_f32_16x16x32_bf16 v[104:107], v[172:175], v[204:207], v[104:107]
	v_mfma_f32_16x16x32_bf16 v[92:95], v[144:147], v[212:215], v[92:95]
	v_mfma_f32_16x16x32_bf16 v[88:91], v[172:175], v[212:215], v[88:91]
	v_mfma_f32_16x16x32_bf16 v[76:79], v[144:147], v[220:223], v[76:79]
	v_mfma_f32_16x16x32_bf16 v[72:75], v[172:175], v[220:223], v[72:75]
	v_mfma_f32_16x16x32_bf16 v[124:127], v[168:171], v[200:203], v[124:127]
	v_mfma_f32_16x16x32_bf16 v[120:123], v[176:179], v[200:203], v[120:123]
	v_mfma_f32_16x16x32_bf16 v[108:111], v[168:171], v[208:211], v[108:111]
	v_mfma_f32_16x16x32_bf16 v[104:107], v[176:179], v[208:211], v[104:107]
	v_mfma_f32_16x16x32_bf16 v[92:95], v[168:171], v[216:219], v[92:95]
	v_mfma_f32_16x16x32_bf16 v[88:91], v[176:179], v[216:219], v[88:91]
	v_mfma_f32_16x16x32_bf16 v[76:79], v[168:171], v[224:227], v[76:79]
	v_mfma_f32_16x16x32_bf16 v[72:75], v[176:179], v[224:227], v[72:75]
	s_setprio 0
	s_setprio 1
	v_mfma_f32_16x16x32_bf16 v[116:119], v[180:183], v[196:199], v[116:119]
	v_mfma_f32_16x16x32_bf16 v[112:115], v[188:191], v[196:199], v[112:115]
	v_mfma_f32_16x16x32_bf16 v[100:103], v[180:183], v[204:207], v[100:103]
	v_mfma_f32_16x16x32_bf16 v[96:99], v[188:191], v[204:207], v[96:99]
	v_mfma_f32_16x16x32_bf16 v[84:87], v[180:183], v[212:215], v[84:87]
	v_mfma_f32_16x16x32_bf16 v[80:83], v[188:191], v[212:215], v[80:83]
	v_mfma_f32_16x16x32_bf16 v[68:71], v[180:183], v[220:223], v[68:71]
	v_mfma_f32_16x16x32_bf16 v[64:67], v[188:191], v[220:223], v[64:67]
	v_mfma_f32_16x16x32_bf16 v[116:119], v[184:187], v[200:203], v[116:119]
	v_mfma_f32_16x16x32_bf16 v[112:115], v[192:195], v[200:203], v[112:115]
	v_mfma_f32_16x16x32_bf16 v[100:103], v[184:187], v[208:211], v[100:103]
	v_mfma_f32_16x16x32_bf16 v[96:99], v[192:195], v[208:211], v[96:99]
	v_mfma_f32_16x16x32_bf16 v[84:87], v[184:187], v[216:219], v[84:87]
	v_mfma_f32_16x16x32_bf16 v[80:83], v[192:195], v[216:219], v[80:83]
	v_mfma_f32_16x16x32_bf16 v[68:71], v[184:187], v[224:227], v[68:71]
	v_mfma_f32_16x16x32_bf16 v[64:67], v[192:195], v[224:227], v[64:67]
	s_barrier
	s_setprio 0
	s_mov_b32 m0, s29
	s_add_u32 s98, s0, s16
	s_addc_u32 s99, s1, s17
	s_add_u32 s4, s0, 0xb0000
	ds_read_b128 v[196:199], v150 offset:16384
	ds_read_b128 v[200:203], v150 offset:17408
	ds_read_b128 v[204:207], v150 offset:18432
	ds_read_b128 v[208:211], v150 offset:19456
	ds_read_b128 v[212:215], v150 offset:20480
	ds_read_b128 v[216:219], v150 offset:21504
	ds_read_b128 v[220:223], v150 offset:22528
	ds_read_b128 v[224:227], v150 offset:23552
	global_load_lds_dwordx4 v130, s[0:1]
	s_mov_b32 m0, s30
	s_addc_u32 s5, s1, 0
	global_load_lds_dwordx4 v134, s[0:1]
	s_mov_b32 m0, s31
	s_nop 0
	global_load_lds_dwordx4 v130, s[4:5]
	s_mov_b32 m0, s33
	s_nop 0
	global_load_lds_dwordx4 v134, s[4:5]
	s_add_u32 s100, s24, s16
	s_addc_u32 s101, s25, s17
	s_mov_b32 m0, s28
	s_nop 0
	global_load_lds_dwordx4 v128, s[24:25]
	s_mov_b32 m0, s34
	s_nop 0
	global_load_lds_dwordx4 v132, s[24:25]
	s_waitcnt vmcnt(8)
	s_waitcnt lgkmcnt(0)
	s_setprio 1
	s_barrier
	v_mfma_f32_16x16x32_bf16 v[60:63], v[144:147], v[196:199], v[60:63]
	v_mfma_f32_16x16x32_bf16 v[56:59], v[172:175], v[196:199], v[56:59]
	v_mfma_f32_16x16x32_bf16 v[44:47], v[144:147], v[204:207], v[44:47]
	v_mfma_f32_16x16x32_bf16 v[40:43], v[172:175], v[204:207], v[40:43]
	v_mfma_f32_16x16x32_bf16 v[28:31], v[144:147], v[212:215], v[28:31]
	v_mfma_f32_16x16x32_bf16 v[24:27], v[172:175], v[212:215], v[24:27]
	v_mfma_f32_16x16x32_bf16 v[12:15], v[144:147], v[220:223], v[12:15]
	v_mfma_f32_16x16x32_bf16 v[8:11], v[172:175], v[220:223], v[8:11]
	v_mfma_f32_16x16x32_bf16 v[60:63], v[168:171], v[200:203], v[60:63]
	v_mfma_f32_16x16x32_bf16 v[56:59], v[176:179], v[200:203], v[56:59]
	v_mfma_f32_16x16x32_bf16 v[44:47], v[168:171], v[208:211], v[44:47]
	v_mfma_f32_16x16x32_bf16 v[40:43], v[176:179], v[208:211], v[40:43]
	v_mfma_f32_16x16x32_bf16 v[28:31], v[168:171], v[216:219], v[28:31]
	v_mfma_f32_16x16x32_bf16 v[24:27], v[176:179], v[216:219], v[24:27]
	v_mfma_f32_16x16x32_bf16 v[12:15], v[168:171], v[224:227], v[12:15]
	v_mfma_f32_16x16x32_bf16 v[8:11], v[176:179], v[224:227], v[8:11]
	s_setprio 0
	s_setprio 1
	v_mfma_f32_16x16x32_bf16 v[52:55], v[180:183], v[196:199], v[52:55]
	v_mfma_f32_16x16x32_bf16 v[48:51], v[188:191], v[196:199], v[48:51]
	v_mfma_f32_16x16x32_bf16 v[36:39], v[180:183], v[204:207], v[36:39]
	v_mfma_f32_16x16x32_bf16 v[32:35], v[188:191], v[204:207], v[32:35]
	v_mfma_f32_16x16x32_bf16 v[20:23], v[180:183], v[212:215], v[20:23]
	v_mfma_f32_16x16x32_bf16 v[16:19], v[188:191], v[212:215], v[16:19]
	v_mfma_f32_16x16x32_bf16 v[4:7], v[180:183], v[220:223], v[4:7]
	v_mfma_f32_16x16x32_bf16 v[0:3], v[188:191], v[220:223], v[0:3]
	v_mfma_f32_16x16x32_bf16 v[52:55], v[184:187], v[200:203], v[52:55]
	v_mfma_f32_16x16x32_bf16 v[48:51], v[192:195], v[200:203], v[48:51]
	v_mfma_f32_16x16x32_bf16 v[36:39], v[184:187], v[208:211], v[36:39]
	v_mfma_f32_16x16x32_bf16 v[32:35], v[192:195], v[208:211], v[32:35]
	v_mfma_f32_16x16x32_bf16 v[20:23], v[184:187], v[216:219], v[20:23]
	v_mfma_f32_16x16x32_bf16 v[16:19], v[192:195], v[216:219], v[16:19]
	v_mfma_f32_16x16x32_bf16 v[4:7], v[184:187], v[224:227], v[4:7]
	v_mfma_f32_16x16x32_bf16 v[0:3], v[192:195], v[224:227], v[0:3]
	s_barrier
; #define PG8_STAGE(bufoff, gbase, voff) do { _Pragma("unroll") for (int _i = 0; _i < 2; ++_i) \
;         __builtin_amdgcn_global_load_lds((const unsigned*)((const char*)(gbase) + (voff)[_i]), (PG8_LAS unsigned*)(lds + (bufoff) + ldsw + _i * 8192), 16, 0, 0); } while (0)
; #define PG8_LDA(dst, b, h) do { _Pragma("unroll") for (int m = 0; m < 4; ++m) _Pragma("unroll") for (int k = 0; k < 2; ++k) dst[m][k] = *(const PG8_LAS bf16x8*)(lds + PG8_SA(b, h) + aoff + m * 2048 + k * 1024); } while (0)
; #define PG8_LDB(dst, b, h) do { _Pragma("unroll") for (int n = 0; n < 2; ++n) _Pragma("unroll") for (int k = 0; k < 2; ++k) dst[n][k] = *(const PG8_LAS bf16x8*)(lds + PG8_SB(b, h) + boff + n * 2048 + k * 1024); } while (0)
; #define PG8_MMA(ai, bj, At, Bt) do { __builtin_amdgcn_s_setprio(1); _Pragma("unroll") for (int m = 0; m < 4; ++m) _Pragma("unroll") for (int n = 0; n < 2; ++n) _Pragma("unroll") for (int k = 0; k < 2; ++k) \
;         acc[ai][bj][m][n] = __builtin_amdgcn_mfma_f32_16x16x32_bf16(Bt[n][k], At[m][k], acc[ai][bj][m][n], 0, 0, 0); __builtin_amdgcn_s_setprio(0); } while (0)
; #define PG8_WAIT_V(n) asm volatile("s_waitcnt vmcnt(" #n ")" ::: "memory")
; #define PG8_WAIT_L(n) asm volatile("s_waitcnt lgkmcnt(" #n ")" ::: "memory")
; #define PG8_BAR __builtin_amdgcn_s_barrier()
; #define PG8_SCHED __builtin_amdgcn_sched_barrier(0)
; template <class Epi, class Sched, bool ALIGN_EPI = false, bool SP2 = false>
; __device__ __forceinline__ void gemm_phase(PG8_LAS unsigned char* lds, const Gemm g, const Sched& S, const Epi& E, const int tid_arg) {
;     ...
;             PG8_LDB(B0, 1, 0); PG8_LDB(B1, 1, 1); PG8_SCHED; PG8_LDA(At, 1, 0); PG8_STAGE(PG8_SA(0, 1), a2 + hstep, voffA);
;             PG8_WAIT_V(8); PG8_WAIT_L(0); PG8_BAR; PG8_MMA(0, 0, At, B0); PG8_MMA(0, 1, At, B1); PG8_BAR; PG8_SCHED;
;             PG8_LDA(At, 1, 1); PG8_STAGE(PG8_SB(1, 0), b3, voffB); PG8_STAGE(PG8_SB(1, 1), b3 + hstep, voffB); PG8_STAGE(PG8_SA(1, 0), a3, voffA);
;             PG8_WAIT_V(8); PG8_WAIT_L(0); PG8_BAR; PG8_MMA(1, 0, At, B0); PG8_MMA(1, 1, At, B1); PG8_BAR; PG8_SCHED;
	s_setprio 0
	ds_read_b128 v[144:147], v159
	ds_read_b128 v[168:171], v160
	ds_read_b128 v[172:175], v161
	ds_read_b128 v[176:179], v162
	ds_read_b128 v[180:183], v163
	ds_read_b128 v[184:187], v164
	ds_read_b128 v[188:191], v165
	ds_read_b128 v[192:195], v166
	s_add_u32 s4, s24, 0xb0000
	s_addc_u32 s5, s25, 0
	s_mov_b32 m0, s35
	ds_read_b128 v[196:199], v150 offset:32768
	ds_read_b128 v[200:203], v150 offset:33792
	ds_read_b128 v[204:207], v150 offset:34816
	ds_read_b128 v[208:211], v150 offset:35840
	ds_read_b128 v[212:215], v150 offset:36864
	ds_read_b128 v[216:219], v150 offset:37888
	ds_read_b128 v[220:223], v150 offset:38912
	ds_read_b128 v[224:227], v150 offset:39936
	global_load_lds_dwordx4 v128, s[4:5]
	s_mov_b32 m0, s36
	s_nop 0
	global_load_lds_dwordx4 v132, s[4:5]
	s_waitcnt vmcnt(8)
	s_waitcnt lgkmcnt(0)
	s_setprio 1
	s_barrier
	v_mfma_f32_16x16x32_bf16 v[124:127], v[144:147], v[196:199], v[124:127]
	v_mfma_f32_16x16x32_bf16 v[120:123], v[172:175], v[196:199], v[120:123]
	v_mfma_f32_16x16x32_bf16 v[108:111], v[144:147], v[204:207], v[108:111]
	v_mfma_f32_16x16x32_bf16 v[104:107], v[172:175], v[204:207], v[104:107]
	v_mfma_f32_16x16x32_bf16 v[92:95], v[144:147], v[212:215], v[92:95]
	v_mfma_f32_16x16x32_bf16 v[88:91], v[172:175], v[212:215], v[88:91]
	v_mfma_f32_16x16x32_bf16 v[76:79], v[144:147], v[220:223], v[76:79]
	v_mfma_f32_16x16x32_bf16 v[72:75], v[172:175], v[220:223], v[72:75]
	v_mfma_f32_16x16x32_bf16 v[124:127], v[168:171], v[200:203], v[124:127]
	v_mfma_f32_16x16x32_bf16 v[120:123], v[176:179], v[200:203], v[120:123]
	v_mfma_f32_16x16x32_bf16 v[108:111], v[168:171], v[208:211], v[108:111]
	v_mfma_f32_16x16x32_bf16 v[104:107], v[176:179], v[208:211], v[104:107]
	v_mfma_f32_16x16x32_bf16 v[92:95], v[168:171], v[216:219], v[92:95]
	v_mfma_f32_16x16x32_bf16 v[88:91], v[176:179], v[216:219], v[88:91]
	v_mfma_f32_16x16x32_bf16 v[76:79], v[168:171], v[224:227], v[76:79]
	v_mfma_f32_16x16x32_bf16 v[72:75], v[176:179], v[224:227], v[72:75]
	s_setprio 0
	s_setprio 1
	v_mfma_f32_16x16x32_bf16 v[116:119], v[180:183], v[196:199], v[116:119]
	v_mfma_f32_16x16x32_bf16 v[112:115], v[188:191], v[196:199], v[112:115]
	v_mfma_f32_16x16x32_bf16 v[100:103], v[180:183], v[204:207], v[100:103]
	v_mfma_f32_16x16x32_bf16 v[96:99], v[188:191], v[204:207], v[96:99]
	v_mfma_f32_16x16x32_bf16 v[84:87], v[180:183], v[212:215], v[84:87]
	v_mfma_f32_16x16x32_bf16 v[80:83], v[188:191], v[212:215], v[80:83]
	v_mfma_f32_16x16x32_bf16 v[68:71], v[180:183], v[220:223], v[68:71]
	v_mfma_f32_16x16x32_bf16 v[64:67], v[188:191], v[220:223], v[64:67]
	v_mfma_f32_16x16x32_bf16 v[116:119], v[184:187], v[200:203], v[116:119]
	v_mfma_f32_16x16x32_bf16 v[112:115], v[192:195], v[200:203], v[112:115]
	v_mfma_f32_16x16x32_bf16 v[100:103], v[184:187], v[208:211], v[100:103]
	v_mfma_f32_16x16x32_bf16 v[96:99], v[192:195], v[208:211], v[96:99]
	v_mfma_f32_16x16x32_bf16 v[84:87], v[184:187], v[216:219], v[84:87]
	v_mfma_f32_16x16x32_bf16 v[80:83], v[192:195], v[216:219], v[80:83]
	v_mfma_f32_16x16x32_bf16 v[68:71], v[184:187], v[224:227], v[68:71]
	v_mfma_f32_16x16x32_bf16 v[64:67], v[192:195], v[224:227], v[64:67]
	s_barrier
	s_setprio 0
	s_mov_b32 m0, s40
	s_add_u32 s0, s0, 0xb0080
	ds_read_b128 v[196:199], v150 offset:49152
	ds_read_b128 v[200:203], v150 offset:50176
	ds_read_b128 v[204:207], v150 offset:51200
	ds_read_b128 v[208:211], v150 offset:52224
	ds_read_b128 v[212:215], v150 offset:53248
	ds_read_b128 v[216:219], v150 offset:54272
	ds_read_b128 v[220:223], v150 offset:55296
	ds_read_b128 v[224:227], v150 offset:56320
	global_load_lds_dwordx4 v130, s[98:99]
	s_mov_b32 m0, s41
	s_addc_u32 s1, s1, 0
	global_load_lds_dwordx4 v134, s[98:99]
	s_mov_b32 m0, s44
	s_nop 0
	global_load_lds_dwordx4 v130, s[0:1]
	s_mov_b32 m0, s45
	s_nop 0
	global_load_lds_dwordx4 v134, s[0:1]
	s_mov_b32 m0, s42
	s_nop 0
	global_load_lds_dwordx4 v128, s[100:101]
	s_mov_b32 m0, s43
	s_nop 0
	global_load_lds_dwordx4 v132, s[100:101]
	s_waitcnt vmcnt(8)
	s_waitcnt lgkmcnt(0)
	s_setprio 1
	s_barrier
	v_mfma_f32_16x16x32_bf16 v[60:63], v[144:147], v[196:199], v[60:63]
	v_mfma_f32_16x16x32_bf16 v[56:59], v[172:175], v[196:199], v[56:59]
	v_mfma_f32_16x16x32_bf16 v[44:47], v[144:147], v[204:207], v[44:47]
	v_mfma_f32_16x16x32_bf16 v[40:43], v[172:175], v[204:207], v[40:43]
	v_mfma_f32_16x16x32_bf16 v[28:31], v[144:147], v[212:215], v[28:31]
	v_mfma_f32_16x16x32_bf16 v[24:27], v[172:175], v[212:215], v[24:27]
	v_mfma_f32_16x16x32_bf16 v[12:15], v[144:147], v[220:223], v[12:15]
	v_mfma_f32_16x16x32_bf16 v[8:11], v[172:175], v[220:223], v[8:11]
	v_mfma_f32_16x16x32_bf16 v[60:63], v[168:171], v[200:203], v[60:63]
	v_mfma_f32_16x16x32_bf16 v[56:59], v[176:179], v[200:203], v[56:59]
	v_mfma_f32_16x16x32_bf16 v[44:47], v[168:171], v[208:211], v[44:47]
	v_mfma_f32_16x16x32_bf16 v[40:43], v[176:179], v[208:211], v[40:43]
	v_mfma_f32_16x16x32_bf16 v[28:31], v[168:171], v[216:219], v[28:31]
	v_mfma_f32_16x16x32_bf16 v[24:27], v[176:179], v[216:219], v[24:27]
	v_mfma_f32_16x16x32_bf16 v[12:15], v[168:171], v[224:227], v[12:15]
	v_mfma_f32_16x16x32_bf16 v[8:11], v[176:179], v[224:227], v[8:11]
	s_setprio 0
	s_setprio 1
	v_mfma_f32_16x16x32_bf16 v[52:55], v[180:183], v[196:199], v[52:55]
	v_mfma_f32_16x16x32_bf16 v[48:51], v[188:191], v[196:199], v[48:51]
	v_mfma_f32_16x16x32_bf16 v[36:39], v[180:183], v[204:207], v[36:39]
	v_mfma_f32_16x16x32_bf16 v[32:35], v[188:191], v[204:207], v[32:35]
	v_mfma_f32_16x16x32_bf16 v[20:23], v[180:183], v[212:215], v[20:23]
	v_mfma_f32_16x16x32_bf16 v[16:19], v[188:191], v[212:215], v[16:19]
	v_mfma_f32_16x16x32_bf16 v[4:7], v[180:183], v[220:223], v[4:7]
	v_mfma_f32_16x16x32_bf16 v[0:3], v[188:191], v[220:223], v[0:3]
	v_mfma_f32_16x16x32_bf16 v[52:55], v[184:187], v[200:203], v[52:55]
	v_mfma_f32_16x16x32_bf16 v[48:51], v[192:195], v[200:203], v[48:51]
	v_mfma_f32_16x16x32_bf16 v[36:39], v[184:187], v[208:211], v[36:39]
	v_mfma_f32_16x16x32_bf16 v[32:35], v[192:195], v[208:211], v[32:35]
	v_mfma_f32_16x16x32_bf16 v[20:23], v[184:187], v[216:219], v[20:23]
	v_mfma_f32_16x16x32_bf16 v[16:19], v[192:195], v[216:219], v[16:19]
	v_mfma_f32_16x16x32_bf16 v[4:7], v[184:187], v[224:227], v[4:7]
	v_mfma_f32_16x16x32_bf16 v[0:3], v[192:195], v[224:227], v[0:3]
	s_barrier
	s_setprio 0
	s_add_i32 s57, s57, 2
	s_add_u32 s55, s55, 0x100
	s_addc_u32 s56, s56, 0
	s_cmp_gt_u32 s57, 41
	s_mov_b64 s[4:5], s[22:23]
	s_cbranch_scc0 .LBB0_1733
	s_and_b64 vcc, exec, s[18:19]
	s_cbranch_vccz .LBB0_1736
	s_barrier

; #define PG8_STAGE(bufoff, gbase, voff) do { _Pragma("unroll") for (int _i = 0; _i < 2; ++_i) \
;         __builtin_amdgcn_global_load_lds((const unsigned*)((const char*)(gbase) + (voff)[_i]), (PG8_LAS unsigned*)(lds + (bufoff) + ldsw + _i * 8192), 16, 0, 0); } while (0)
; #define PG8_LDA(dst, b, h) do { _Pragma("unroll") for (int m = 0; m < 4; ++m) _Pragma("unroll") for (int k = 0; k < 2; ++k) dst[m][k] = *(const PG8_LAS bf16x8*)(lds + PG8_SA(b, h) + aoff + m * 2048 + k * 1024); } while (0)
; #define PG8_LDB(dst, b, h) do { _Pragma("unroll") for (int n = 0; n < 2; ++n) _Pragma("unroll") for (int k = 0; k < 2; ++k) dst[n][k] = *(const PG8_LAS bf16x8*)(lds + PG8_SB(b, h) + boff + n * 2048 + k * 1024); } while (0)
; #define PG8_MMA(ai, bj, At, Bt) do { __builtin_amdgcn_s_setprio(1); _Pragma("unroll") for (int m = 0; m < 4; ++m) _Pragma("unroll") for (int n = 0; n < 2; ++n) _Pragma("unroll") for (int k = 0; k < 2; ++k) \
;         acc[ai][bj][m][n] = __builtin_amdgcn_mfma_f32_16x16x32_bf16(Bt[n][k], At[m][k], acc[ai][bj][m][n], 0, 0, 0); __builtin_amdgcn_s_setprio(0); } while (0)
; #define PG8_WAIT_V(n) asm volatile("s_waitcnt vmcnt(" #n ")" ::: "memory")
; #define PG8_BAR __builtin_amdgcn_s_barrier()
; template <class Epi, class Sched, bool ALIGN_EPI = false, bool SP2 = false>
; __device__ __forceinline__ void gemm_phase(PG8_LAS unsigned char* lds, const Gemm g, const Sched& S, const Epi& E, const int tid_arg) {
;     ...
;         for (int t = 0; t < nt; t += 2) {
;             const bool last = (t == nt - 2);
;             const char* a1 = cA + (size_t)(t + 1) * kstep;
;             const char* a2 = last ? nA : cA + (size_t)(t + 2) * kstep; const char* b2 = last ? nB : cB + (size_t)(t + 2) * kstep;
;             const char* a3 = a2 + kstep; const char* b3 = b2 + kstep;
;             if (last && has_next) S.a_ready(nxt);
;             if constexpr (SP2) {
;             PG8_LDB(B0, 0, 0); PG8_LDB(B1, 0, 1); PG8_SCHED; PG8_LDA(At, 0, 0); PG8_STAGE(PG8_SA(1, 1), a1 + hstep, voffA);
;             PG8_WAIT_V(8); PG8_WAIT_L(0); PG8_BAR; PG8_MMA(0, 0, At, B0); PG8_MMA(0, 1, At, B1); PG8_BAR; PG8_SCHED;
;             PG8_LDA(At, 0, 1); PG8_STAGE(PG8_SB(0, 0), b2, voffB); PG8_STAGE(PG8_SB(0, 1), b2 + hstep, voffB); PG8_STAGE(PG8_SA(0, 0), a2, voffA);
;             PG8_WAIT_V(8); PG8_WAIT_L(0); PG8_BAR; PG8_MMA(1, 0, At, B0); PG8_MMA(1, 1, At, B1); PG8_BAR; PG8_SCHED;
.LBB0_1827:
	ds_read_b128 v[170:173], v151
	ds_read_b128 v[174:177], v153
	ds_read_b128 v[178:181], v155
	ds_read_b128 v[182:185], v156
	ds_read_b128 v[186:189], v157
	ds_read_b128 v[190:193], v158
	ds_read_b128 v[194:197], v159
	ds_read_b128 v[198:201], v160
	s_add_u32 s0, s44, 0xfffc0080
	s_addc_u32 s1, s45, -1
	s_cmp_eq_u32 s81, 12
	s_cselect_b32 s47, s39, s1
	s_cselect_b32 s46, s75, s0
	s_cselect_b32 s1, s37, s80
	s_cselect_b32 s0, s78, s79
	s_mov_b32 m0, s67
	ds_read_b128 v[202:205], v149
	ds_read_b128 v[206:209], v149 offset:1024
	ds_read_b128 v[210:213], v149 offset:2048
	ds_read_b128 v[214:217], v149 offset:3072
	ds_read_b128 v[218:221], v149 offset:4096
	ds_read_b128 v[222:225], v149 offset:5120
	ds_read_b128 v[226:229], v149 offset:6144
	ds_read_b128 v[230:233], v149 offset:7168
	global_load_lds_dwordx4 v138, s[44:45]
	s_mov_b32 m0, s68
	s_nop 0
	global_load_lds_dwordx4 v136, s[44:45]
	s_waitcnt vmcnt(8)
	s_waitcnt lgkmcnt(0)
	s_setprio 1
	s_barrier
	v_mfma_f32_16x16x32_bf16 v[124:127], v[170:173], v[202:205], v[124:127]
	v_mfma_f32_16x16x32_bf16 v[120:123], v[178:181], v[202:205], v[120:123]
	v_mfma_f32_16x16x32_bf16 v[108:111], v[170:173], v[210:213], v[108:111]
	v_mfma_f32_16x16x32_bf16 v[104:107], v[178:181], v[210:213], v[104:107]
	v_mfma_f32_16x16x32_bf16 v[92:95], v[170:173], v[218:221], v[92:95]
	v_mfma_f32_16x16x32_bf16 v[88:91], v[178:181], v[218:221], v[88:91]
	v_mfma_f32_16x16x32_bf16 v[76:79], v[170:173], v[226:229], v[76:79]
	v_mfma_f32_16x16x32_bf16 v[72:75], v[178:181], v[226:229], v[72:75]
	v_mfma_f32_16x16x32_bf16 v[124:127], v[174:177], v[206:209], v[124:127]
	v_mfma_f32_16x16x32_bf16 v[120:123], v[182:185], v[206:209], v[120:123]
	v_mfma_f32_16x16x32_bf16 v[108:111], v[174:177], v[214:217], v[108:111]
	v_mfma_f32_16x16x32_bf16 v[104:107], v[182:185], v[214:217], v[104:107]
	v_mfma_f32_16x16x32_bf16 v[92:95], v[174:177], v[222:225], v[92:95]
	v_mfma_f32_16x16x32_bf16 v[88:91], v[182:185], v[222:225], v[88:91]
	v_mfma_f32_16x16x32_bf16 v[76:79], v[174:177], v[230:233], v[76:79]
	v_mfma_f32_16x16x32_bf16 v[72:75], v[182:185], v[230:233], v[72:75]
	s_setprio 0
	s_setprio 1
	v_mfma_f32_16x16x32_bf16 v[116:119], v[186:189], v[202:205], v[116:119]
	v_mfma_f32_16x16x32_bf16 v[112:115], v[194:197], v[202:205], v[112:115]
	v_mfma_f32_16x16x32_bf16 v[100:103], v[186:189], v[210:213], v[100:103]
	v_mfma_f32_16x16x32_bf16 v[96:99], v[194:197], v[210:213], v[96:99]
	v_mfma_f32_16x16x32_bf16 v[84:87], v[186:189], v[218:221], v[84:87]
	v_mfma_f32_16x16x32_bf16 v[80:83], v[194:197], v[218:221], v[80:83]
	v_mfma_f32_16x16x32_bf16 v[68:71], v[186:189], v[226:229], v[68:71]
	v_mfma_f32_16x16x32_bf16 v[64:67], v[194:197], v[226:229], v[64:67]
	v_mfma_f32_16x16x32_bf16 v[116:119], v[190:193], v[206:209], v[116:119]
	v_mfma_f32_16x16x32_bf16 v[112:115], v[198:201], v[206:209], v[112:115]
	v_mfma_f32_16x16x32_bf16 v[100:103], v[190:193], v[214:217], v[100:103]
	v_mfma_f32_16x16x32_bf16 v[96:99], v[198:201], v[214:217], v[96:99]
	v_mfma_f32_16x16x32_bf16 v[84:87], v[190:193], v[222:225], v[84:87]
	v_mfma_f32_16x16x32_bf16 v[80:83], v[198:201], v[222:225], v[80:83]
	v_mfma_f32_16x16x32_bf16 v[68:71], v[190:193], v[230:233], v[68:71]
	v_mfma_f32_16x16x32_bf16 v[64:67], v[198:201], v[230:233], v[64:67]
	s_barrier
	s_setprio 0
	s_mov_b32 m0, s5
	s_add_u32 s98, s0, s16
	s_addc_u32 s99, s1, s17
	s_add_u32 s82, s0, 0x40000
	ds_read_b128 v[202:205], v149 offset:16384
	ds_read_b128 v[206:209], v149 offset:17408
	ds_read_b128 v[210:213], v149 offset:18432
	ds_read_b128 v[214:217], v149 offset:19456
	ds_read_b128 v[218:221], v149 offset:20480
	ds_read_b128 v[222:225], v149 offset:21504
	ds_read_b128 v[226:229], v149 offset:22528
	ds_read_b128 v[230:233], v149 offset:23552
	global_load_lds_dwordx4 v130, s[0:1]
	s_mov_b32 m0, s51
	s_addc_u32 s83, s1, 0
	global_load_lds_dwordx4 v134, s[0:1]
	s_mov_b32 m0, s52
	s_nop 0
	global_load_lds_dwordx4 v130, s[82:83]
	s_mov_b32 m0, s53
	s_nop 0
	global_load_lds_dwordx4 v134, s[82:83]
	s_add_u32 s100, s46, s16
	s_addc_u32 s101, s47, s17
	s_mov_b32 m0, s50
	s_nop 0
	global_load_lds_dwordx4 v128, s[46:47]
	s_mov_b32 m0, s54
	s_nop 0
	global_load_lds_dwordx4 v132, s[46:47]
	s_waitcnt vmcnt(8)
	s_waitcnt lgkmcnt(0)
	s_setprio 1
	s_barrier
	v_mfma_f32_16x16x32_bf16 v[60:63], v[170:173], v[202:205], v[60:63]
	v_mfma_f32_16x16x32_bf16 v[56:59], v[178:181], v[202:205], v[56:59]
	v_mfma_f32_16x16x32_bf16 v[44:47], v[170:173], v[210:213], v[44:47]
	v_mfma_f32_16x16x32_bf16 v[40:43], v[178:181], v[210:213], v[40:43]
	v_mfma_f32_16x16x32_bf16 v[28:31], v[170:173], v[218:221], v[28:31]
	v_mfma_f32_16x16x32_bf16 v[24:27], v[178:181], v[218:221], v[24:27]
	v_mfma_f32_16x16x32_bf16 v[12:15], v[170:173], v[226:229], v[12:15]
	v_mfma_f32_16x16x32_bf16 v[8:11], v[178:181], v[226:229], v[8:11]
	v_mfma_f32_16x16x32_bf16 v[60:63], v[174:177], v[206:209], v[60:63]
	v_mfma_f32_16x16x32_bf16 v[56:59], v[182:185], v[206:209], v[56:59]
	v_mfma_f32_16x16x32_bf16 v[44:47], v[174:177], v[214:217], v[44:47]
	v_mfma_f32_16x16x32_bf16 v[40:43], v[182:185], v[214:217], v[40:43]
	v_mfma_f32_16x16x32_bf16 v[28:31], v[174:177], v[222:225], v[28:31]
	v_mfma_f32_16x16x32_bf16 v[24:27], v[182:185], v[222:225], v[24:27]
	v_mfma_f32_16x16x32_bf16 v[12:15], v[174:177], v[230:233], v[12:15]
	v_mfma_f32_16x16x32_bf16 v[8:11], v[182:185], v[230:233], v[8:11]
	s_setprio 0
	s_setprio 1
	v_mfma_f32_16x16x32_bf16 v[52:55], v[186:189], v[202:205], v[52:55]
	v_mfma_f32_16x16x32_bf16 v[48:51], v[194:197], v[202:205], v[48:51]
	v_mfma_f32_16x16x32_bf16 v[36:39], v[186:189], v[210:213], v[36:39]
	v_mfma_f32_16x16x32_bf16 v[32:35], v[194:197], v[210:213], v[32:35]
	v_mfma_f32_16x16x32_bf16 v[20:23], v[186:189], v[218:221], v[20:23]
	v_mfma_f32_16x16x32_bf16 v[16:19], v[194:197], v[218:221], v[16:19]
	v_mfma_f32_16x16x32_bf16 v[4:7], v[186:189], v[226:229], v[4:7]
	v_mfma_f32_16x16x32_bf16 v[0:3], v[194:197], v[226:229], v[0:3]
	v_mfma_f32_16x16x32_bf16 v[52:55], v[190:193], v[206:209], v[52:55]
	v_mfma_f32_16x16x32_bf16 v[48:51], v[198:201], v[206:209], v[48:51]
	v_mfma_f32_16x16x32_bf16 v[36:39], v[190:193], v[214:217], v[36:39]
	v_mfma_f32_16x16x32_bf16 v[32:35], v[198:201], v[214:217], v[32:35]
	v_mfma_f32_16x16x32_bf16 v[20:23], v[190:193], v[222:225], v[20:23]
	v_mfma_f32_16x16x32_bf16 v[16:19], v[198:201], v[222:225], v[16:19]
	v_mfma_f32_16x16x32_bf16 v[4:7], v[190:193], v[230:233], v[4:7]
	v_mfma_f32_16x16x32_bf16 v[0:3], v[198:201], v[230:233], v[0:3]
	s_barrier
; #define PG8_STAGE(bufoff, gbase, voff) do { _Pragma("unroll") for (int _i = 0; _i < 2; ++_i) \
;         __builtin_amdgcn_global_load_lds((const unsigned*)((const char*)(gbase) + (voff)[_i]), (PG8_LAS unsigned*)(lds + (bufoff) + ldsw + _i * 8192), 16, 0, 0); } while (0)
; #define PG8_LDA(dst, b, h) do { _Pragma("unroll") for (int m = 0; m < 4; ++m) _Pragma("unroll") for (int k = 0; k < 2; ++k) dst[m][k] = *(const PG8_LAS bf16x8*)(lds + PG8_SA(b, h) + aoff + m * 2048 + k * 1024); } while (0)
; #define PG8_LDB(dst, b, h) do { _Pragma("unroll") for (int n = 0; n < 2; ++n) _Pragma("unroll") for (int k = 0; k < 2; ++k) dst[n][k] = *(const PG8_LAS bf16x8*)(lds + PG8_SB(b, h) + boff + n * 2048 + k * 1024); } while (0)
; #define PG8_MMA(ai, bj, At, Bt) do { __builtin_amdgcn_s_setprio(1); _Pragma("unroll") for (int m = 0; m < 4; ++m) _Pragma("unroll") for (int n = 0; n < 2; ++n) _Pragma("unroll") for (int k = 0; k < 2; ++k) \
;         acc[ai][bj][m][n] = __builtin_amdgcn_mfma_f32_16x16x32_bf16(Bt[n][k], At[m][k], acc[ai][bj][m][n], 0, 0, 0); __builtin_amdgcn_s_setprio(0); } while (0)
; #define PG8_WAIT_V(n) asm volatile("s_waitcnt vmcnt(" #n ")" ::: "memory")
; #define PG8_WAIT_L(n) asm volatile("s_waitcnt lgkmcnt(" #n ")" ::: "memory")
; #define PG8_BAR __builtin_amdgcn_s_barrier()
; #define PG8_SCHED __builtin_amdgcn_sched_barrier(0)
; template <class Epi, class Sched, bool ALIGN_EPI = false, bool SP2 = false>
; __device__ __forceinline__ void gemm_phase(PG8_LAS unsigned char* lds, const Gemm g, const Sched& S, const Epi& E, const int tid_arg) {
;     ...
;             PG8_LDB(B0, 1, 0); PG8_LDB(B1, 1, 1); PG8_SCHED; PG8_LDA(At, 1, 0); PG8_STAGE(PG8_SA(0, 1), a2 + hstep, voffA);
;             PG8_WAIT_V(8); PG8_WAIT_L(0); PG8_BAR; PG8_MMA(0, 0, At, B0); PG8_MMA(0, 1, At, B1); PG8_BAR; PG8_SCHED;
;             PG8_LDA(At, 1, 1); PG8_STAGE(PG8_SB(1, 0), b3, voffB); PG8_STAGE(PG8_SB(1, 1), b3 + hstep, voffB); PG8_STAGE(PG8_SA(1, 0), a3, voffA);
;             PG8_WAIT_V(8); PG8_WAIT_L(0); PG8_BAR; PG8_MMA(1, 0, At, B0); PG8_MMA(1, 1, At, B1); PG8_BAR; PG8_SCHED;
	s_setprio 0
	ds_read_b128 v[170:173], v161
	ds_read_b128 v[174:177], v162
	ds_read_b128 v[178:181], v163
	ds_read_b128 v[182:185], v164
	ds_read_b128 v[186:189], v165
	ds_read_b128 v[190:193], v166
	ds_read_b128 v[194:197], v167
	ds_read_b128 v[198:201], v168
	s_add_u32 s46, s46, 0x40000
	s_addc_u32 s47, s47, 0
	s_mov_b32 m0, s55
	ds_read_b128 v[202:205], v149 offset:32768
	ds_read_b128 v[206:209], v149 offset:33792
	ds_read_b128 v[210:213], v149 offset:34816
	ds_read_b128 v[214:217], v149 offset:35840
	ds_read_b128 v[218:221], v149 offset:36864
	ds_read_b128 v[222:225], v149 offset:37888
	ds_read_b128 v[226:229], v149 offset:38912
	ds_read_b128 v[230:233], v149 offset:39936
	global_load_lds_dwordx4 v128, s[46:47]
	s_mov_b32 m0, s56
	s_nop 0
	global_load_lds_dwordx4 v132, s[46:47]
	s_waitcnt vmcnt(8)
	s_waitcnt lgkmcnt(0)
	s_setprio 1
	s_barrier
	v_mfma_f32_16x16x32_bf16 v[124:127], v[170:173], v[202:205], v[124:127]
	v_mfma_f32_16x16x32_bf16 v[120:123], v[178:181], v[202:205], v[120:123]
	v_mfma_f32_16x16x32_bf16 v[108:111], v[170:173], v[210:213], v[108:111]
	v_mfma_f32_16x16x32_bf16 v[104:107], v[178:181], v[210:213], v[104:107]
	v_mfma_f32_16x16x32_bf16 v[92:95], v[170:173], v[218:221], v[92:95]
	v_mfma_f32_16x16x32_bf16 v[88:91], v[178:181], v[218:221], v[88:91]
	v_mfma_f32_16x16x32_bf16 v[76:79], v[170:173], v[226:229], v[76:79]
	v_mfma_f32_16x16x32_bf16 v[72:75], v[178:181], v[226:229], v[72:75]
	v_mfma_f32_16x16x32_bf16 v[124:127], v[174:177], v[206:209], v[124:127]
	v_mfma_f32_16x16x32_bf16 v[120:123], v[182:185], v[206:209], v[120:123]
	v_mfma_f32_16x16x32_bf16 v[108:111], v[174:177], v[214:217], v[108:111]
	v_mfma_f32_16x16x32_bf16 v[104:107], v[182:185], v[214:217], v[104:107]
	v_mfma_f32_16x16x32_bf16 v[92:95], v[174:177], v[222:225], v[92:95]
	v_mfma_f32_16x16x32_bf16 v[88:91], v[182:185], v[222:225], v[88:91]
	v_mfma_f32_16x16x32_bf16 v[76:79], v[174:177], v[230:233], v[76:79]
	v_mfma_f32_16x16x32_bf16 v[72:75], v[182:185], v[230:233], v[72:75]
	s_setprio 0
	s_setprio 1
	v_mfma_f32_16x16x32_bf16 v[116:119], v[186:189], v[202:205], v[116:119]
	v_mfma_f32_16x16x32_bf16 v[112:115], v[194:197], v[202:205], v[112:115]
	v_mfma_f32_16x16x32_bf16 v[100:103], v[186:189], v[210:213], v[100:103]
	v_mfma_f32_16x16x32_bf16 v[96:99], v[194:197], v[210:213], v[96:99]
	v_mfma_f32_16x16x32_bf16 v[84:87], v[186:189], v[218:221], v[84:87]
	v_mfma_f32_16x16x32_bf16 v[80:83], v[194:197], v[218:221], v[80:83]
	v_mfma_f32_16x16x32_bf16 v[68:71], v[186:189], v[226:229], v[68:71]
	v_mfma_f32_16x16x32_bf16 v[64:67], v[194:197], v[226:229], v[64:67]
	v_mfma_f32_16x16x32_bf16 v[116:119], v[190:193], v[206:209], v[116:119]
	v_mfma_f32_16x16x32_bf16 v[112:115], v[198:201], v[206:209], v[112:115]
	v_mfma_f32_16x16x32_bf16 v[100:103], v[190:193], v[214:217], v[100:103]
	v_mfma_f32_16x16x32_bf16 v[96:99], v[198:201], v[214:217], v[96:99]
	v_mfma_f32_16x16x32_bf16 v[84:87], v[190:193], v[222:225], v[84:87]
	v_mfma_f32_16x16x32_bf16 v[80:83], v[198:201], v[222:225], v[80:83]
	v_mfma_f32_16x16x32_bf16 v[68:71], v[190:193], v[230:233], v[68:71]
	v_mfma_f32_16x16x32_bf16 v[64:67], v[198:201], v[230:233], v[64:67]
	s_barrier
	s_setprio 0
	s_mov_b32 m0, s59
	s_add_u32 s0, s0, 0x40080
	ds_read_b128 v[202:205], v149 offset:49152
	ds_read_b128 v[206:209], v149 offset:50176
	ds_read_b128 v[210:213], v149 offset:51200
	ds_read_b128 v[214:217], v149 offset:52224
	ds_read_b128 v[218:221], v149 offset:53248
	ds_read_b128 v[222:225], v149 offset:54272
	ds_read_b128 v[226:229], v149 offset:55296
	ds_read_b128 v[230:233], v149 offset:56320
	global_load_lds_dwordx4 v130, s[98:99]
	s_mov_b32 m0, s60
	s_addc_u32 s1, s1, 0
	global_load_lds_dwordx4 v134, s[98:99]
	s_mov_b32 m0, s63
	s_nop 0
	global_load_lds_dwordx4 v130, s[0:1]
	s_mov_b32 m0, s64
	s_nop 0
	global_load_lds_dwordx4 v134, s[0:1]
	s_mov_b32 m0, s61
	s_nop 0
	global_load_lds_dwordx4 v128, s[100:101]
	s_mov_b32 m0, s62
	s_nop 0
	global_load_lds_dwordx4 v132, s[100:101]
	s_waitcnt vmcnt(8)
	s_waitcnt lgkmcnt(0)
	s_setprio 1
	s_barrier
	v_mfma_f32_16x16x32_bf16 v[60:63], v[170:173], v[202:205], v[60:63]
	v_mfma_f32_16x16x32_bf16 v[56:59], v[178:181], v[202:205], v[56:59]
	v_mfma_f32_16x16x32_bf16 v[44:47], v[170:173], v[210:213], v[44:47]
	v_mfma_f32_16x16x32_bf16 v[40:43], v[178:181], v[210:213], v[40:43]
	v_mfma_f32_16x16x32_bf16 v[28:31], v[170:173], v[218:221], v[28:31]
	v_mfma_f32_16x16x32_bf16 v[24:27], v[178:181], v[218:221], v[24:27]
	v_mfma_f32_16x16x32_bf16 v[12:15], v[170:173], v[226:229], v[12:15]
	v_mfma_f32_16x16x32_bf16 v[8:11], v[178:181], v[226:229], v[8:11]
	v_mfma_f32_16x16x32_bf16 v[60:63], v[174:177], v[206:209], v[60:63]
	v_mfma_f32_16x16x32_bf16 v[56:59], v[182:185], v[206:209], v[56:59]
	v_mfma_f32_16x16x32_bf16 v[44:47], v[174:177], v[214:217], v[44:47]
	v_mfma_f32_16x16x32_bf16 v[40:43], v[182:185], v[214:217], v[40:43]
	v_mfma_f32_16x16x32_bf16 v[28:31], v[174:177], v[222:225], v[28:31]
	v_mfma_f32_16x16x32_bf16 v[24:27], v[182:185], v[222:225], v[24:27]
	v_mfma_f32_16x16x32_bf16 v[12:15], v[174:177], v[230:233], v[12:15]
	v_mfma_f32_16x16x32_bf16 v[8:11], v[182:185], v[230:233], v[8:11]
	s_setprio 0
	s_setprio 1
	v_mfma_f32_16x16x32_bf16 v[52:55], v[186:189], v[202:205], v[52:55]
	v_mfma_f32_16x16x32_bf16 v[48:51], v[194:197], v[202:205], v[48:51]
	v_mfma_f32_16x16x32_bf16 v[36:39], v[186:189], v[210:213], v[36:39]
	v_mfma_f32_16x16x32_bf16 v[32:35], v[194:197], v[210:213], v[32:35]
	v_mfma_f32_16x16x32_bf16 v[20:23], v[186:189], v[218:221], v[20:23]
	v_mfma_f32_16x16x32_bf16 v[16:19], v[194:197], v[218:221], v[16:19]
	v_mfma_f32_16x16x32_bf16 v[4:7], v[186:189], v[226:229], v[4:7]
	v_mfma_f32_16x16x32_bf16 v[0:3], v[194:197], v[226:229], v[0:3]
	v_mfma_f32_16x16x32_bf16 v[52:55], v[190:193], v[206:209], v[52:55]
	v_mfma_f32_16x16x32_bf16 v[48:51], v[198:201], v[206:209], v[48:51]
	v_mfma_f32_16x16x32_bf16 v[36:39], v[190:193], v[214:217], v[36:39]
	v_mfma_f32_16x16x32_bf16 v[32:35], v[198:201], v[214:217], v[32:35]
	v_mfma_f32_16x16x32_bf16 v[20:23], v[190:193], v[222:225], v[20:23]
	v_mfma_f32_16x16x32_bf16 v[16:19], v[198:201], v[222:225], v[16:19]
	v_mfma_f32_16x16x32_bf16 v[4:7], v[190:193], v[230:233], v[4:7]
	v_mfma_f32_16x16x32_bf16 v[0:3], v[198:201], v[230:233], v[0:3]
	s_barrier
	s_setprio 0
	s_add_i32 s81, s81, 2
	s_add_u32 s79, s79, 0x100
	s_addc_u32 s80, s80, 0
	s_add_u32 s44, s44, 0x100
	s_addc_u32 s45, s45, 0
	s_cmp_gt_u32 s81, 13
	s_cbranch_scc0 .LBB0_1827
	s_and_b64 vcc, exec, s[18:19]
	s_cbranch_vccz .LBB0_1830
	s_barrier

; #define PG8_STAGE(bufoff, gbase, voff) do { _Pragma("unroll") for (int _i = 0; _i < 2; ++_i) \
;         __builtin_amdgcn_global_load_lds((const unsigned*)((const char*)(gbase) + (voff)[_i]), (PG8_LAS unsigned*)(lds + (bufoff) + ldsw + _i * 8192), 16, 0, 0); } while (0)
; #define PG8_LDA(dst, b, h) do { _Pragma("unroll") for (int m = 0; m < 4; ++m) _Pragma("unroll") for (int k = 0; k < 2; ++k) dst[m][k] = *(const PG8_LAS bf16x8*)(lds + PG8_SA(b, h) + aoff + m * 2048 + k * 1024); } while (0)
; #define PG8_LDB(dst, b, h) do { _Pragma("unroll") for (int n = 0; n < 2; ++n) _Pragma("unroll") for (int k = 0; k < 2; ++k) dst[n][k] = *(const PG8_LAS bf16x8*)(lds + PG8_SB(b, h) + boff + n * 2048 + k * 1024); } while (0)
; #define PG8_MMA(ai, bj, At, Bt) do { __builtin_amdgcn_s_setprio(1); _Pragma("unroll") for (int m = 0; m < 4; ++m) _Pragma("unroll") for (int n = 0; n < 2; ++n) _Pragma("unroll") for (int k = 0; k < 2; ++k) \
;         acc[ai][bj][m][n] = __builtin_amdgcn_mfma_f32_16x16x32_bf16(Bt[n][k], At[m][k], acc[ai][bj][m][n], 0, 0, 0); __builtin_amdgcn_s_setprio(0); } while (0)
; #define PG8_WAIT_V(n) asm volatile("s_waitcnt vmcnt(" #n ")" ::: "memory")
; #define PG8_BAR __builtin_amdgcn_s_barrier()
; template <class Epi, class Sched, bool ALIGN_EPI = false, bool SP2 = false>
; __device__ __forceinline__ void gemm_phase(PG8_LAS unsigned char* lds, const Gemm g, const Sched& S, const Epi& E, const int tid_arg) {
;     ...
;         for (int t = 0; t < nt; t += 2) {
;             const bool last = (t == nt - 2);
;             const char* a1 = cA + (size_t)(t + 1) * kstep;
;             const char* a2 = last ? nA : cA + (size_t)(t + 2) * kstep; const char* b2 = last ? nB : cB + (size_t)(t + 2) * kstep;
;             const char* a3 = a2 + kstep; const char* b3 = b2 + kstep;
;             if (last && has_next) S.a_ready(nxt);
;             if constexpr (SP2) {
;             PG8_LDB(B0, 0, 0); PG8_LDB(B1, 0, 1); PG8_SCHED; PG8_LDA(At, 0, 0); PG8_STAGE(PG8_SA(1, 1), a1 + hstep, voffA);
;             PG8_WAIT_V(8); PG8_WAIT_L(0); PG8_BAR; PG8_MMA(0, 0, At, B0); PG8_MMA(0, 1, At, B1); PG8_BAR; PG8_SCHED;
;             PG8_LDA(At, 0, 1); PG8_STAGE(PG8_SB(0, 0), b2, voffB); PG8_STAGE(PG8_SB(0, 1), b2 + hstep, voffB); PG8_STAGE(PG8_SA(0, 0), a2, voffA);
;             PG8_WAIT_V(8); PG8_WAIT_L(0); PG8_BAR; PG8_MMA(1, 0, At, B0); PG8_MMA(1, 1, At, B1); PG8_BAR; PG8_SCHED;
.LBB0_1911:
	ds_read_b128 v[144:147], v157
	ds_read_b128 v[148:151], v158
	ds_read_b128 v[174:177], v159
	ds_read_b128 v[178:181], v160
	ds_read_b128 v[182:185], v161
	ds_read_b128 v[186:189], v162
	ds_read_b128 v[190:193], v163
	ds_read_b128 v[194:197], v164
	s_add_i32 s36, s34, 2
	s_add_u32 s37, s6, 0x80
	s_addc_u32 s35, s7, 0
	s_cmp_eq_u32 s57, s34
	s_cselect_b32 s34, s28, s37
	s_cselect_b32 s35, s29, s35
	s_cselect_b32 s67, s31, s64
	s_cselect_b32 s66, s30, s63
	s_mov_b32 m0, s58
	ds_read_b128 v[198:201], v156
	ds_read_b128 v[202:205], v156 offset:1024
	ds_read_b128 v[206:209], v156 offset:2048
	ds_read_b128 v[210:213], v156 offset:3072
	ds_read_b128 v[214:217], v156 offset:4096
	ds_read_b128 v[218:221], v156 offset:5120
	ds_read_b128 v[222:225], v156 offset:6144
	ds_read_b128 v[226:229], v156 offset:7168
	global_load_lds_dwordx4 v138, s[6:7]
	s_mov_b32 m0, s59
	s_nop 0
	global_load_lds_dwordx4 v136, s[6:7]
	s_waitcnt vmcnt(8)
	s_waitcnt lgkmcnt(0)
	s_setprio 1
	s_barrier
	v_mfma_f32_16x16x32_bf16 v[124:127], v[144:147], v[198:201], v[124:127]
	v_mfma_f32_16x16x32_bf16 v[120:123], v[174:177], v[198:201], v[120:123]
	v_mfma_f32_16x16x32_bf16 v[108:111], v[144:147], v[206:209], v[108:111]
	v_mfma_f32_16x16x32_bf16 v[104:107], v[174:177], v[206:209], v[104:107]
	v_mfma_f32_16x16x32_bf16 v[92:95], v[144:147], v[214:217], v[92:95]
	v_mfma_f32_16x16x32_bf16 v[88:91], v[174:177], v[214:217], v[88:91]
	v_mfma_f32_16x16x32_bf16 v[76:79], v[144:147], v[222:225], v[76:79]
	v_mfma_f32_16x16x32_bf16 v[72:75], v[174:177], v[222:225], v[72:75]
	v_mfma_f32_16x16x32_bf16 v[124:127], v[148:151], v[202:205], v[124:127]
	v_mfma_f32_16x16x32_bf16 v[120:123], v[178:181], v[202:205], v[120:123]
	v_mfma_f32_16x16x32_bf16 v[108:111], v[148:151], v[210:213], v[108:111]
	v_mfma_f32_16x16x32_bf16 v[104:107], v[178:181], v[210:213], v[104:107]
	v_mfma_f32_16x16x32_bf16 v[92:95], v[148:151], v[218:221], v[92:95]
	v_mfma_f32_16x16x32_bf16 v[88:91], v[178:181], v[218:221], v[88:91]
	v_mfma_f32_16x16x32_bf16 v[76:79], v[148:151], v[226:229], v[76:79]
	v_mfma_f32_16x16x32_bf16 v[72:75], v[178:181], v[226:229], v[72:75]
	s_setprio 0
	s_setprio 1
	v_mfma_f32_16x16x32_bf16 v[116:119], v[182:185], v[198:201], v[116:119]
	v_mfma_f32_16x16x32_bf16 v[112:115], v[190:193], v[198:201], v[112:115]
	v_mfma_f32_16x16x32_bf16 v[100:103], v[182:185], v[206:209], v[100:103]
	v_mfma_f32_16x16x32_bf16 v[96:99], v[190:193], v[206:209], v[96:99]
	v_mfma_f32_16x16x32_bf16 v[84:87], v[182:185], v[214:217], v[84:87]
	v_mfma_f32_16x16x32_bf16 v[80:83], v[190:193], v[214:217], v[80:83]
	v_mfma_f32_16x16x32_bf16 v[68:71], v[182:185], v[222:225], v[68:71]
	v_mfma_f32_16x16x32_bf16 v[64:67], v[190:193], v[222:225], v[64:67]
	v_mfma_f32_16x16x32_bf16 v[116:119], v[186:189], v[202:205], v[116:119]
	v_mfma_f32_16x16x32_bf16 v[112:115], v[194:197], v[202:205], v[112:115]
	v_mfma_f32_16x16x32_bf16 v[100:103], v[186:189], v[210:213], v[100:103]
	v_mfma_f32_16x16x32_bf16 v[96:99], v[194:197], v[210:213], v[96:99]
	v_mfma_f32_16x16x32_bf16 v[84:87], v[186:189], v[218:221], v[84:87]
	v_mfma_f32_16x16x32_bf16 v[80:83], v[194:197], v[218:221], v[80:83]
	v_mfma_f32_16x16x32_bf16 v[68:71], v[186:189], v[226:229], v[68:71]
	v_mfma_f32_16x16x32_bf16 v[64:67], v[194:197], v[226:229], v[64:67]
	s_barrier
	s_setprio 0
	s_mov_b32 m0, s42
	s_add_u32 s98, s66, s20
	s_addc_u32 s99, s67, s21
	v_lshl_add_u64 v[152:153], s[66:67], 0, v[130:131]
	v_lshl_add_u64 v[230:231], s[66:67], 0, v[134:135]
	s_add_u32 s66, s66, s12
	ds_read_b128 v[198:201], v156 offset:16384
	ds_read_b128 v[202:205], v156 offset:17408
	ds_read_b128 v[206:209], v156 offset:18432
	ds_read_b128 v[210:213], v156 offset:19456
	ds_read_b128 v[214:217], v156 offset:20480
	ds_read_b128 v[218:221], v156 offset:21504
	ds_read_b128 v[222:225], v156 offset:22528
	ds_read_b128 v[226:229], v156 offset:23552
	global_load_lds_dwordx4 v[152:153], off
	s_mov_b32 m0, s43
	s_addc_u32 s67, s67, s13
	global_load_lds_dwordx4 v[230:231], off
	s_add_u32 s100, s66, s20
	s_addc_u32 s101, s67, s21
	s_mov_b32 m0, s44
	s_nop 0
	global_load_lds_dwordx4 v130, s[66:67]
	s_mov_b32 m0, s45
	v_lshl_add_u64 v[236:237], s[34:35], 0, v[128:129]
	global_load_lds_dwordx4 v134, s[66:67]
	s_mov_b32 m0, s41
	v_lshl_add_u64 v[238:239], s[34:35], 0, v[132:133]
	global_load_lds_dwordx4 v128, s[34:35]
	s_mov_b32 m0, s46
	s_nop 0
	global_load_lds_dwordx4 v132, s[34:35]
	s_waitcnt vmcnt(8)
	s_waitcnt lgkmcnt(0)
	s_setprio 1
	s_barrier
	v_mfma_f32_16x16x32_bf16 v[60:63], v[144:147], v[198:201], v[60:63]
	v_mfma_f32_16x16x32_bf16 v[56:59], v[174:177], v[198:201], v[56:59]
	v_mfma_f32_16x16x32_bf16 v[44:47], v[144:147], v[206:209], v[44:47]
	v_mfma_f32_16x16x32_bf16 v[40:43], v[174:177], v[206:209], v[40:43]
	v_mfma_f32_16x16x32_bf16 v[28:31], v[144:147], v[214:217], v[28:31]
	v_mfma_f32_16x16x32_bf16 v[24:27], v[174:177], v[214:217], v[24:27]
	v_mfma_f32_16x16x32_bf16 v[12:15], v[144:147], v[222:225], v[12:15]
	v_mfma_f32_16x16x32_bf16 v[8:11], v[174:177], v[222:225], v[8:11]
	v_mfma_f32_16x16x32_bf16 v[60:63], v[148:151], v[202:205], v[60:63]
	v_mfma_f32_16x16x32_bf16 v[56:59], v[178:181], v[202:205], v[56:59]
	v_mfma_f32_16x16x32_bf16 v[44:47], v[148:151], v[210:213], v[44:47]
	v_mfma_f32_16x16x32_bf16 v[40:43], v[178:181], v[210:213], v[40:43]
	v_mfma_f32_16x16x32_bf16 v[28:31], v[148:151], v[218:221], v[28:31]
	v_mfma_f32_16x16x32_bf16 v[24:27], v[178:181], v[218:221], v[24:27]
	v_mfma_f32_16x16x32_bf16 v[12:15], v[148:151], v[226:229], v[12:15]
	v_mfma_f32_16x16x32_bf16 v[8:11], v[178:181], v[226:229], v[8:11]
	s_setprio 0
	s_setprio 1
	v_mfma_f32_16x16x32_bf16 v[52:55], v[182:185], v[198:201], v[52:55]
	v_mfma_f32_16x16x32_bf16 v[48:51], v[190:193], v[198:201], v[48:51]
	v_mfma_f32_16x16x32_bf16 v[36:39], v[182:185], v[206:209], v[36:39]
	v_mfma_f32_16x16x32_bf16 v[32:35], v[190:193], v[206:209], v[32:35]
	v_mfma_f32_16x16x32_bf16 v[20:23], v[182:185], v[214:217], v[20:23]
	v_mfma_f32_16x16x32_bf16 v[16:19], v[190:193], v[214:217], v[16:19]
	v_mfma_f32_16x16x32_bf16 v[4:7], v[182:185], v[222:225], v[4:7]
	v_mfma_f32_16x16x32_bf16 v[0:3], v[190:193], v[222:225], v[0:3]
	v_mfma_f32_16x16x32_bf16 v[52:55], v[186:189], v[202:205], v[52:55]
	v_mfma_f32_16x16x32_bf16 v[48:51], v[194:197], v[202:205], v[48:51]
	v_mfma_f32_16x16x32_bf16 v[36:39], v[186:189], v[210:213], v[36:39]
	v_mfma_f32_16x16x32_bf16 v[32:35], v[194:197], v[210:213], v[32:35]
	v_mfma_f32_16x16x32_bf16 v[20:23], v[186:189], v[218:221], v[20:23]
	v_mfma_f32_16x16x32_bf16 v[16:19], v[194:197], v[218:221], v[16:19]
	v_mfma_f32_16x16x32_bf16 v[4:7], v[186:189], v[226:229], v[4:7]
	v_mfma_f32_16x16x32_bf16 v[0:3], v[194:197], v[226:229], v[0:3]
	s_barrier
; #define PG8_STAGE(bufoff, gbase, voff) do { _Pragma("unroll") for (int _i = 0; _i < 2; ++_i) \
;         __builtin_amdgcn_global_load_lds((const unsigned*)((const char*)(gbase) + (voff)[_i]), (PG8_LAS unsigned*)(lds + (bufoff) + ldsw + _i * 8192), 16, 0, 0); } while (0)
; #define PG8_LDA(dst, b, h) do { _Pragma("unroll") for (int m = 0; m < 4; ++m) _Pragma("unroll") for (int k = 0; k < 2; ++k) dst[m][k] = *(const PG8_LAS bf16x8*)(lds + PG8_SA(b, h) + aoff + m * 2048 + k * 1024); } while (0)
; #define PG8_LDB(dst, b, h) do { _Pragma("unroll") for (int n = 0; n < 2; ++n) _Pragma("unroll") for (int k = 0; k < 2; ++k) dst[n][k] = *(const PG8_LAS bf16x8*)(lds + PG8_SB(b, h) + boff + n * 2048 + k * 1024); } while (0)
; #define PG8_MMA(ai, bj, At, Bt) do { __builtin_amdgcn_s_setprio(1); _Pragma("unroll") for (int m = 0; m < 4; ++m) _Pragma("unroll") for (int n = 0; n < 2; ++n) _Pragma("unroll") for (int k = 0; k < 2; ++k) \
;         acc[ai][bj][m][n] = __builtin_amdgcn_mfma_f32_16x16x32_bf16(Bt[n][k], At[m][k], acc[ai][bj][m][n], 0, 0, 0); __builtin_amdgcn_s_setprio(0); } while (0)
; #define PG8_WAIT_V(n) asm volatile("s_waitcnt vmcnt(" #n ")" ::: "memory")
; #define PG8_WAIT_L(n) asm volatile("s_waitcnt lgkmcnt(" #n ")" ::: "memory")
; #define PG8_BAR __builtin_amdgcn_s_barrier()
; #define PG8_SCHED __builtin_amdgcn_sched_barrier(0)
; template <class Epi, class Sched, bool ALIGN_EPI = false, bool SP2 = false>
; __device__ __forceinline__ void gemm_phase(PG8_LAS unsigned char* lds, const Gemm g, const Sched& S, const Epi& E, const int tid_arg) {
;     ...
;             PG8_LDB(B0, 1, 0); PG8_LDB(B1, 1, 1); PG8_SCHED; PG8_LDA(At, 1, 0); PG8_STAGE(PG8_SA(0, 1), a2 + hstep, voffA);
;             PG8_WAIT_V(8); PG8_WAIT_L(0); PG8_BAR; PG8_MMA(0, 0, At, B0); PG8_MMA(0, 1, At, B1); PG8_BAR; PG8_SCHED;
;             PG8_LDA(At, 1, 1); PG8_STAGE(PG8_SB(1, 0), b3, voffB); PG8_STAGE(PG8_SB(1, 1), b3 + hstep, voffB); PG8_STAGE(PG8_SA(1, 0), a3, voffA);
;             PG8_WAIT_V(8); PG8_WAIT_L(0); PG8_BAR; PG8_MMA(1, 0, At, B0); PG8_MMA(1, 1, At, B1); PG8_BAR; PG8_SCHED;
	s_setprio 0
	ds_read_b128 v[144:147], v165
	ds_read_b128 v[148:151], v166
	ds_read_b128 v[174:177], v167
	ds_read_b128 v[178:181], v168
	ds_read_b128 v[182:185], v169
	ds_read_b128 v[186:189], v170
	ds_read_b128 v[190:193], v171
	ds_read_b128 v[194:197], v172
	s_add_u32 s34, s34, s12
	s_addc_u32 s35, s35, s13
	s_mov_b32 m0, s47
	ds_read_b128 v[198:201], v156 offset:32768
	ds_read_b128 v[202:205], v156 offset:33792
	ds_read_b128 v[206:209], v156 offset:34816
	ds_read_b128 v[210:213], v156 offset:35840
	ds_read_b128 v[214:217], v156 offset:36864
	ds_read_b128 v[218:221], v156 offset:37888
	ds_read_b128 v[222:225], v156 offset:38912
	ds_read_b128 v[226:229], v156 offset:39936
	global_load_lds_dwordx4 v128, s[34:35]
	s_mov_b32 m0, s48
	s_nop 0
	global_load_lds_dwordx4 v132, s[34:35]
	s_waitcnt vmcnt(8)
	s_waitcnt lgkmcnt(0)
	s_setprio 1
	s_barrier
	v_mfma_f32_16x16x32_bf16 v[124:127], v[144:147], v[198:201], v[124:127]
	v_mfma_f32_16x16x32_bf16 v[120:123], v[174:177], v[198:201], v[120:123]
	v_mfma_f32_16x16x32_bf16 v[108:111], v[144:147], v[206:209], v[108:111]
	v_mfma_f32_16x16x32_bf16 v[104:107], v[174:177], v[206:209], v[104:107]
	v_mfma_f32_16x16x32_bf16 v[92:95], v[144:147], v[214:217], v[92:95]
	v_mfma_f32_16x16x32_bf16 v[88:91], v[174:177], v[214:217], v[88:91]
	v_mfma_f32_16x16x32_bf16 v[76:79], v[144:147], v[222:225], v[76:79]
	v_mfma_f32_16x16x32_bf16 v[72:75], v[174:177], v[222:225], v[72:75]
	v_mfma_f32_16x16x32_bf16 v[124:127], v[148:151], v[202:205], v[124:127]
	v_mfma_f32_16x16x32_bf16 v[120:123], v[178:181], v[202:205], v[120:123]
	v_mfma_f32_16x16x32_bf16 v[108:111], v[148:151], v[210:213], v[108:111]
	v_mfma_f32_16x16x32_bf16 v[104:107], v[178:181], v[210:213], v[104:107]
	v_mfma_f32_16x16x32_bf16 v[92:95], v[148:151], v[218:221], v[92:95]
	v_mfma_f32_16x16x32_bf16 v[88:91], v[178:181], v[218:221], v[88:91]
	v_mfma_f32_16x16x32_bf16 v[76:79], v[148:151], v[226:229], v[76:79]
	v_mfma_f32_16x16x32_bf16 v[72:75], v[178:181], v[226:229], v[72:75]
	s_setprio 0
	s_setprio 1
	v_mfma_f32_16x16x32_bf16 v[116:119], v[182:185], v[198:201], v[116:119]
	v_mfma_f32_16x16x32_bf16 v[112:115], v[190:193], v[198:201], v[112:115]
	v_mfma_f32_16x16x32_bf16 v[100:103], v[182:185], v[206:209], v[100:103]
	v_mfma_f32_16x16x32_bf16 v[96:99], v[190:193], v[206:209], v[96:99]
	v_mfma_f32_16x16x32_bf16 v[84:87], v[182:185], v[214:217], v[84:87]
	v_mfma_f32_16x16x32_bf16 v[80:83], v[190:193], v[214:217], v[80:83]
	v_mfma_f32_16x16x32_bf16 v[68:71], v[182:185], v[222:225], v[68:71]
	v_mfma_f32_16x16x32_bf16 v[64:67], v[190:193], v[222:225], v[64:67]
	v_mfma_f32_16x16x32_bf16 v[116:119], v[186:189], v[202:205], v[116:119]
	v_mfma_f32_16x16x32_bf16 v[112:115], v[194:197], v[202:205], v[112:115]
	v_mfma_f32_16x16x32_bf16 v[100:103], v[186:189], v[210:213], v[100:103]
	v_mfma_f32_16x16x32_bf16 v[96:99], v[194:197], v[210:213], v[96:99]
	v_mfma_f32_16x16x32_bf16 v[84:87], v[186:189], v[218:221], v[84:87]
	v_mfma_f32_16x16x32_bf16 v[80:83], v[194:197], v[218:221], v[80:83]
	v_mfma_f32_16x16x32_bf16 v[68:71], v[186:189], v[226:229], v[68:71]
	v_mfma_f32_16x16x32_bf16 v[64:67], v[194:197], v[226:229], v[64:67]
	s_barrier
	s_setprio 0
	s_mov_b32 m0, s49
	ds_read_b128 v[198:201], v156 offset:49152
	ds_read_b128 v[202:205], v156 offset:50176
	ds_read_b128 v[206:209], v156 offset:51200
	ds_read_b128 v[210:213], v156 offset:52224
	ds_read_b128 v[214:217], v156 offset:53248
	ds_read_b128 v[218:221], v156 offset:54272
	ds_read_b128 v[222:225], v156 offset:55296
	ds_read_b128 v[226:229], v156 offset:56320
	global_load_lds_dwordx4 v130, s[98:99]
	s_mov_b32 m0, s50
	s_nop 0
	global_load_lds_dwordx4 v134, s[98:99]
	s_mov_b32 m0, s53
	s_nop 0
	global_load_lds_dwordx4 v130, s[100:101]
	s_mov_b32 m0, s54
	s_nop 0
	global_load_lds_dwordx4 v134, s[100:101]
	v_lshl_add_u64 v[152:153], v[236:237], 0, s[20:21]
	s_mov_b32 m0, s51
	s_nop 0
	global_load_lds_dwordx4 v[152:153], off
	v_lshl_add_u64 v[152:153], v[238:239], 0, s[20:21]
	s_mov_b32 m0, s52
	s_nop 0
	global_load_lds_dwordx4 v[152:153], off
	s_waitcnt vmcnt(8)
	s_waitcnt lgkmcnt(0)
	s_setprio 1
	s_barrier
	v_mfma_f32_16x16x32_bf16 v[60:63], v[144:147], v[198:201], v[60:63]
	v_mfma_f32_16x16x32_bf16 v[56:59], v[174:177], v[198:201], v[56:59]
	v_mfma_f32_16x16x32_bf16 v[44:47], v[144:147], v[206:209], v[44:47]
	v_mfma_f32_16x16x32_bf16 v[40:43], v[174:177], v[206:209], v[40:43]
	v_mfma_f32_16x16x32_bf16 v[28:31], v[144:147], v[214:217], v[28:31]
	v_mfma_f32_16x16x32_bf16 v[24:27], v[174:177], v[214:217], v[24:27]
	v_mfma_f32_16x16x32_bf16 v[12:15], v[144:147], v[222:225], v[12:15]
	v_mfma_f32_16x16x32_bf16 v[8:11], v[174:177], v[222:225], v[8:11]
	v_mfma_f32_16x16x32_bf16 v[60:63], v[148:151], v[202:205], v[60:63]
	v_mfma_f32_16x16x32_bf16 v[56:59], v[178:181], v[202:205], v[56:59]
	v_mfma_f32_16x16x32_bf16 v[44:47], v[148:151], v[210:213], v[44:47]
	v_mfma_f32_16x16x32_bf16 v[40:43], v[178:181], v[210:213], v[40:43]
	v_mfma_f32_16x16x32_bf16 v[28:31], v[148:151], v[218:221], v[28:31]
	v_mfma_f32_16x16x32_bf16 v[24:27], v[178:181], v[218:221], v[24:27]
	v_mfma_f32_16x16x32_bf16 v[12:15], v[148:151], v[226:229], v[12:15]
	v_mfma_f32_16x16x32_bf16 v[8:11], v[178:181], v[226:229], v[8:11]
	s_setprio 0
	s_setprio 1
	v_mfma_f32_16x16x32_bf16 v[52:55], v[182:185], v[198:201], v[52:55]
	v_mfma_f32_16x16x32_bf16 v[48:51], v[190:193], v[198:201], v[48:51]
	v_mfma_f32_16x16x32_bf16 v[36:39], v[182:185], v[206:209], v[36:39]
	v_mfma_f32_16x16x32_bf16 v[32:35], v[190:193], v[206:209], v[32:35]
	v_mfma_f32_16x16x32_bf16 v[20:23], v[182:185], v[214:217], v[20:23]
	v_mfma_f32_16x16x32_bf16 v[16:19], v[190:193], v[214:217], v[16:19]
	v_mfma_f32_16x16x32_bf16 v[4:7], v[182:185], v[222:225], v[4:7]
	v_mfma_f32_16x16x32_bf16 v[0:3], v[190:193], v[222:225], v[0:3]
	v_mfma_f32_16x16x32_bf16 v[52:55], v[186:189], v[202:205], v[52:55]
	v_mfma_f32_16x16x32_bf16 v[48:51], v[194:197], v[202:205], v[48:51]
	v_mfma_f32_16x16x32_bf16 v[36:39], v[186:189], v[210:213], v[36:39]
	v_mfma_f32_16x16x32_bf16 v[32:35], v[194:197], v[210:213], v[32:35]
	v_mfma_f32_16x16x32_bf16 v[20:23], v[186:189], v[218:221], v[20:23]
	v_mfma_f32_16x16x32_bf16 v[16:19], v[194:197], v[218:221], v[16:19]
	v_mfma_f32_16x16x32_bf16 v[4:7], v[186:189], v[226:229], v[4:7]
	v_mfma_f32_16x16x32_bf16 v[0:3], v[194:197], v[226:229], v[0:3]
	s_barrier
	s_setprio 0
	s_add_u32 s63, s63, 0x100
	s_addc_u32 s64, s64, 0
	s_add_u32 s6, s6, 0x100
	s_addc_u32 s7, s7, 0
	s_cmp_ge_i32 s36, s55
	s_mov_b32 s34, s36
	s_cbranch_scc0 .LBB0_1911
